# GEMM epilogue stores: address+data moved with ds_bpermute to lane 4*fr+fq so each lane quad writes 64 contiguous bytes of one row
# speedup vs baseline: 1.0135x; 1.0008x over previous
; #define LAS __attribute__((address_space(3)))
; __global__ void __launch_bounds__(NWAVES * 64, 2) hybrid_fwd(Args a) {
;     extern __shared__ __attribute__((aligned(16))) unsigned char lds_raw[];
;     cg::grid_group grid = cg::this_grid();
;     LAS unsigned char* lds = (LAS unsigned char*)lds_raw;
;     const int G = gridDim.x, bx = blockIdx.x, NGW = G * NWAVES;
;     const int wave_k = __builtin_amdgcn_readfirstlane((int)threadIdx.x >> 6);
;     ...
;     unsigned char* ws = a.ws;
;     ...
;     unsigned* barw = (unsigned*)(ws + WS_BAR);
;     if (bx == 0) for (int i = threadIdx.x; i < XCD_BAR_WORDS; i += NWAVES * 64) barw[i] = 0u;
_Z10hybrid_fwd4Args:
	v_mbcnt_lo_u32_b32 v255, -1, 0
	v_mbcnt_hi_u32_b32 v255, -1, v255
	v_and_b32_e32 v254, 3, v255
	v_lshrrev_b32_e32 v255, 2, v255
	v_lshl_add_u32 v255, v254, 4, v255
	v_lshlrev_b32_e32 v255, 2, v255
	s_mov_b32 s94, s2
	s_add_u32 s2, s0, 0x70
	s_addc_u32 s3, s1, 0
	s_load_dwordx4 s[16:19], s[0:1], 0x60
	s_load_dwordx8 s[20:27], s[0:1], 0x40
	v_writelane_b32 v252, s2, 0
	s_load_dwordx2 s[6:7], s[0:1], 0x70
	v_and_b32_e32 v18, 0x3ff, v0
	v_writelane_b32 v252, s3, 1
	s_load_dword s2, s[0:1], 0x78
	v_readfirstlane_b32 s4, v18
	s_waitcnt lgkmcnt(0)
	v_writelane_b32 v252, s2, 2
	s_add_u32 s2, s18, 0x1fd00000
	s_addc_u32 s3, s19, 0
	v_writelane_b32 v252, s2, 3
	s_cmp_lg_u32 s94, 0
	s_nop 0
	v_writelane_b32 v252, s3, 4
	s_mov_b32 s2, 0
	s_cbranch_scc1 .LBB0_8
	v_sub_u32_e32 v1, 0xd7f, v18
	v_lshrrev_b32_e32 v2, 9, v1
	v_add_u32_e32 v1, 2, v2
	v_add_u32_e32 v19, 0x200, v18
	s_mov_b32 s14, s4
	v_and_b32_e32 v3, 14, v1
	v_mov_b32_e32 v1, v2
	s_mov_b64 s[8:9], 0
	s_mov_b32 s3, 1
	v_mov_b32_e32 v5, 0
	s_mov_b32 s10, s2
	v_mov_b64_e32 v[6:7], v[18:19]
	s_branch .LBB0_3

; __device__ __forceinline__ unsigned cvt_pk_bf16(float lo, float hi) { unsigned r; asm volatile("v_cvt_pk_bf16_f32 %0, %1, %2" : "=v"(r) : "v"(lo), "v"(hi)); return r; }
; #define EPI_FENCE() asm volatile("" ::: "memory")
; __device__ __forceinline__ float gelu_tanh(float x) {
;     const float y = x * (0.7978845608028654f + 0.7978845608028654f * 0.044715f * x * x);
;     const float e = __builtin_amdgcn_exp2f(-2.0f * 1.4426950408889634f * y);
;     return x * __builtin_amdgcn_rcpf(1.0f + e);
; }
;     __device__ __forceinline__ void operator()(const f32x4 (&acc)[2][2][4][2], const Unit& u, int wr, int wc, int fr, int fq) const {
;     ...
;         } else {
;             EPI_FENCE();
; #pragma unroll
;             for (int i = 0; i < 8; ++i) {
;                 const int ai = i >> 2, m = i & 3; bf16_t* rowp = Z + (size_t)(row0 + ai * HALF + m * 16) * 5120 + col0;
; #pragma unroll
;                 for (int bj = 0; bj < 2; ++bj) {
;                     f32x4 v0 = acc[ai][bj][m][0] * rs[i], v1 = acc[ai][bj][m][1] * rs[i];
;                     if (kind == 2) {
; #pragma unroll
;                         for (int e = 0; e < 4; ++e) { v0[e] = gelu_tanh(v0[e]); v1[e] = gelu_tanh(v1[e]); }
;                     }
;                     u32x4 w; w.x = cvt_pk_bf16(v0[0], v0[1]); w.y = cvt_pk_bf16(v0[2], v0[3]); w.z = cvt_pk_bf16(v1[0], v1[1]); w.w = cvt_pk_bf16(v1[2], v1[3]);
;                     *(u32x4*)(rowp + bj * HALF) = w;
;                 }
;             }
.LBB0_125:
	v_mov_b64_e32 v[130:131], s[8:9]
	v_mad_i64_i32 v[130:131], s[2:3], v206, s59, v[130:131]
	v_mov_b32_e32 v140, v186
	v_mov_b32_e32 v141, v186
	v_lshl_add_u64 v[130:131], v[188:189], 1, v[130:131]
	v_cvt_pk_bf16_f32 v136, v136, v137
	v_cvt_pk_bf16_f32 v137, v132, v133
	v_cvt_pk_bf16_f32 v138, v138, v139
	v_cvt_pk_bf16_f32 v139, v134, v135
	v_mov_b32_e32 v134, v186
	v_mov_b32_e32 v135, v186
	ds_bpermute_b32 v142, v255, v130
	ds_bpermute_b32 v143, v255, v131
	ds_bpermute_b32 v144, v255, v136
	ds_bpermute_b32 v145, v255, v137
	ds_bpermute_b32 v146, v255, v138
	ds_bpermute_b32 v147, v255, v139
	s_waitcnt lgkmcnt(0)
	global_store_dwordx4 v[142:143], v[144:147], off
	v_pk_mul_f32 v[132:133], v[120:121], v[134:135]
	v_pk_mul_f32 v[134:135], v[116:117], v[134:135]
	v_pk_mul_f32 v[136:137], v[118:119], v[140:141]
	s_and_b64 vcc, exec, s[4:5]
	v_pk_mul_f32 v[138:139], v[114:115], v[140:141]
	s_cbranch_vccnz .LBB0_127
	v_mul_f32_e32 v141, 0x3d122279, v138
	v_fmaak_f32 v141, v138, v141, 0x3f4c422a
	v_mul_f32_e32 v141, v138, v141
	v_mul_f32_e32 v141, 0xc038aa3b, v141
	v_exp_f32_e32 v141, v141
	v_mul_f32_e32 v140, 0x3d122279, v136
	v_fmaak_f32 v140, v136, v140, 0x3f4c422a
	v_mul_f32_e32 v140, v136, v140
	v_add_f32_e32 v141, 1.0, v141
	v_rcp_f32_e32 v142, v141
	v_mul_f32_e32 v141, 0x3d122279, v137
	v_fmaak_f32 v141, v137, v141, 0x3f4c422a
	v_mul_f32_e32 v141, v137, v141
	v_mul_f32_e32 v140, 0xc038aa3b, v140
	v_mul_f32_e32 v141, 0xc038aa3b, v141
	v_exp_f32_e32 v140, v140
	v_exp_f32_e32 v141, v141
	v_mul_f32_e32 v145, 0x3d122279, v134
	v_fmaak_f32 v145, v134, v145, 0x3f4c422a
	v_mul_f32_e32 v145, v134, v145
	v_mul_f32_e32 v145, 0xc038aa3b, v145
	v_add_f32_e32 v140, 1.0, v140
	v_add_f32_e32 v141, 1.0, v141
	v_exp_f32_e32 v145, v145
	v_rcp_f32_e32 v140, v140
	v_rcp_f32_e32 v141, v141
	v_mul_f32_e32 v143, 0x3d122279, v139
	v_add_f32_e32 v145, 1.0, v145
	v_mul_f32_e32 v144, 0x3d122279, v132
	v_rcp_f32_e32 v146, v145
	v_mul_f32_e32 v145, 0x3d122279, v133
	v_pk_mul_f32 v[136:137], v[136:137], v[140:141]
	v_mul_f32_e32 v140, 0x3d122279, v135
	v_fmaak_f32 v143, v139, v143, 0x3f4c422a
	v_fmaak_f32 v144, v132, v144, 0x3f4c422a
	v_fmaak_f32 v145, v133, v145, 0x3f4c422a
	v_fmaak_f32 v140, v135, v140, 0x3f4c422a
	v_mul_f32_e32 v143, v139, v143
	v_mul_f32_e32 v144, v132, v144
	v_mul_f32_e32 v145, v133, v145
	v_mul_f32_e32 v140, v135, v140
	v_mul_f32_e32 v143, 0xc038aa3b, v143
	v_mul_f32_e32 v144, 0xc038aa3b, v144
	v_mul_f32_e32 v145, 0xc038aa3b, v145
	v_mul_f32_e32 v140, 0xc038aa3b, v140
	v_exp_f32_e32 v143, v143
	v_exp_f32_e32 v144, v144
	v_exp_f32_e32 v145, v145
	v_exp_f32_e32 v140, v140
	v_add_f32_e32 v143, 1.0, v143
	v_add_f32_e32 v144, 1.0, v144
	v_add_f32_e32 v145, 1.0, v145
	v_add_f32_e32 v140, 1.0, v140
	v_rcp_f32_e32 v143, v143
	v_rcp_f32_e32 v144, v144
	v_rcp_f32_e32 v145, v145
	v_rcp_f32_e32 v147, v140
	v_pk_mul_f32 v[138:139], v[138:139], v[142:143]
	v_pk_mul_f32 v[132:133], v[132:133], v[144:145]
	v_pk_mul_f32 v[134:135], v[134:135], v[146:147]
.LBB0_127:
	v_cvt_pk_bf16_f32 v136, v136, v137
	v_cvt_pk_bf16_f32 v137, v132, v133
	v_cvt_pk_bf16_f32 v138, v138, v139
	s_nop 0
	v_cvt_pk_bf16_f32 v139, v134, v135
	ds_bpermute_b32 v140, v255, v130
	ds_bpermute_b32 v141, v255, v131
	ds_bpermute_b32 v142, v255, v136
	ds_bpermute_b32 v143, v255, v137
	ds_bpermute_b32 v144, v255, v138
	ds_bpermute_b32 v145, v255, v139
	s_waitcnt lgkmcnt(0)
	global_store_dwordx4 v[140:141], v[142:145], off offset:256
	v_mov_b32_e32 v130, v187
	v_pk_mul_f32 v[132:133], v[112:113], v[130:131] op_sel_hi:[1,0]
	v_pk_mul_f32 v[136:137], v[110:111], v[130:131] op_sel_hi:[1,0]
	v_pk_mul_f32 v[134:135], v[108:109], v[130:131] op_sel_hi:[1,0]
	s_and_b64 vcc, exec, s[4:5]
	v_pk_mul_f32 v[138:139], v[106:107], v[130:131] op_sel_hi:[1,0]
	s_cbranch_vccnz .LBB0_129
	v_mul_f32_e32 v131, 0x3d122279, v138
	v_fmaak_f32 v131, v138, v131, 0x3f4c422a
	v_mul_f32_e32 v131, v138, v131
	v_mul_f32_e32 v131, 0xc038aa3b, v131
	v_exp_f32_e32 v131, v131
	v_mul_f32_e32 v130, 0x3d122279, v136
	v_fmaak_f32 v130, v136, v130, 0x3f4c422a
	v_mul_f32_e32 v130, v136, v130
	v_add_f32_e32 v131, 1.0, v131
	v_rcp_f32_e32 v140, v131
	v_mul_f32_e32 v131, 0x3d122279, v137
	v_fmaak_f32 v131, v137, v131, 0x3f4c422a
	v_mul_f32_e32 v131, v137, v131
	v_mul_f32_e32 v130, 0xc038aa3b, v130
	v_mul_f32_e32 v131, 0xc038aa3b, v131
	v_exp_f32_e32 v130, v130
	v_exp_f32_e32 v131, v131
	v_mul_f32_e32 v143, 0x3d122279, v134
	v_fmaak_f32 v143, v134, v143, 0x3f4c422a
	v_mul_f32_e32 v143, v134, v143
	v_mul_f32_e32 v143, 0xc038aa3b, v143
	v_add_f32_e32 v130, 1.0, v130
	v_add_f32_e32 v131, 1.0, v131
	v_exp_f32_e32 v143, v143
	v_rcp_f32_e32 v130, v130
	v_rcp_f32_e32 v131, v131
	v_mul_f32_e32 v141, 0x3d122279, v139
	v_add_f32_e32 v143, 1.0, v143
	v_mul_f32_e32 v142, 0x3d122279, v132
	v_rcp_f32_e32 v144, v143
	v_mul_f32_e32 v143, 0x3d122279, v133
	v_pk_mul_f32 v[136:137], v[136:137], v[130:131]
	v_mul_f32_e32 v130, 0x3d122279, v135
	v_fmaak_f32 v141, v139, v141, 0x3f4c422a
	v_fmaak_f32 v142, v132, v142, 0x3f4c422a
	v_fmaak_f32 v143, v133, v143, 0x3f4c422a
	v_fmaak_f32 v130, v135, v130, 0x3f4c422a
	v_mul_f32_e32 v141, v139, v141
	v_mul_f32_e32 v142, v132, v142
	v_mul_f32_e32 v143, v133, v143
	v_mul_f32_e32 v130, v135, v130
	v_mul_f32_e32 v141, 0xc038aa3b, v141
	v_mul_f32_e32 v142, 0xc038aa3b, v142
	v_mul_f32_e32 v143, 0xc038aa3b, v143
	v_mul_f32_e32 v130, 0xc038aa3b, v130
	v_exp_f32_e32 v141, v141
	v_exp_f32_e32 v142, v142
	v_exp_f32_e32 v143, v143
	v_exp_f32_e32 v130, v130
	v_add_f32_e32 v141, 1.0, v141
	v_add_f32_e32 v142, 1.0, v142
	v_add_f32_e32 v143, 1.0, v143
	v_add_f32_e32 v130, 1.0, v130
	v_rcp_f32_e32 v141, v141
	v_rcp_f32_e32 v142, v142
	v_rcp_f32_e32 v143, v143
	v_rcp_f32_e32 v145, v130
	v_pk_mul_f32 v[138:139], v[138:139], v[140:141]
	v_pk_mul_f32 v[132:133], v[132:133], v[142:143]
	v_pk_mul_f32 v[134:135], v[134:135], v[144:145]
; __device__ __forceinline__ unsigned cvt_pk_bf16(float lo, float hi) { unsigned r; asm volatile("v_cvt_pk_bf16_f32 %0, %1, %2" : "=v"(r) : "v"(lo), "v"(hi)); return r; }
; #define EPI_FENCE() asm volatile("" ::: "memory")
; __device__ __forceinline__ float gelu_tanh(float x) {
;     const float y = x * (0.7978845608028654f + 0.7978845608028654f * 0.044715f * x * x);
;     const float e = __builtin_amdgcn_exp2f(-2.0f * 1.4426950408889634f * y);
;     return x * __builtin_amdgcn_rcpf(1.0f + e);
; }
;     __device__ __forceinline__ void operator()(const f32x4 (&acc)[2][2][4][2], const Unit& u, int wr, int wc, int fr, int fq) const {
;     ...
;         } else {
;             EPI_FENCE();
; #pragma unroll
;             for (int i = 0; i < 8; ++i) {
;                 const int ai = i >> 2, m = i & 3; bf16_t* rowp = Z + (size_t)(row0 + ai * HALF + m * 16) * 5120 + col0;
; #pragma unroll
;                 for (int bj = 0; bj < 2; ++bj) {
;                     f32x4 v0 = acc[ai][bj][m][0] * rs[i], v1 = acc[ai][bj][m][1] * rs[i];
;                     if (kind == 2) {
; #pragma unroll
;                         for (int e = 0; e < 4; ++e) { v0[e] = gelu_tanh(v0[e]); v1[e] = gelu_tanh(v1[e]); }
;                     }
;                     u32x4 w; w.x = cvt_pk_bf16(v0[0], v0[1]); w.y = cvt_pk_bf16(v0[2], v0[3]); w.z = cvt_pk_bf16(v1[0], v1[1]); w.w = cvt_pk_bf16(v1[2], v1[3]);
;                     *(u32x4*)(rowp + bj * HALF) = w;
;                 }
;             }
.LBB0_129:
	v_or_b32_e32 v142, 16, v206
	v_mov_b64_e32 v[130:131], s[8:9]
	v_mad_i64_i32 v[130:131], s[2:3], v142, s59, v[130:131]
	v_mov_b32_e32 v140, v187
	v_mov_b32_e32 v141, v187
	v_lshl_add_u64 v[130:131], v[188:189], 1, v[130:131]
	v_cvt_pk_bf16_f32 v136, v136, v137
	v_cvt_pk_bf16_f32 v137, v132, v133
	v_cvt_pk_bf16_f32 v138, v138, v139
	v_cvt_pk_bf16_f32 v139, v134, v135
	v_mov_b32_e32 v134, v187
	v_mov_b32_e32 v135, v187
	ds_bpermute_b32 v142, v255, v130
	ds_bpermute_b32 v143, v255, v131
	ds_bpermute_b32 v144, v255, v136
	ds_bpermute_b32 v145, v255, v137
	ds_bpermute_b32 v146, v255, v138
	ds_bpermute_b32 v147, v255, v139
	s_waitcnt lgkmcnt(0)
	global_store_dwordx4 v[142:143], v[144:147], off
	v_pk_mul_f32 v[132:133], v[104:105], v[134:135]
	v_pk_mul_f32 v[134:135], v[100:101], v[134:135]
	v_pk_mul_f32 v[136:137], v[102:103], v[140:141]
	s_and_b64 vcc, exec, s[4:5]
	v_pk_mul_f32 v[138:139], v[98:99], v[140:141]
	s_cbranch_vccnz .LBB0_131
	v_mul_f32_e32 v141, 0x3d122279, v138
	v_fmaak_f32 v141, v138, v141, 0x3f4c422a
	v_mul_f32_e32 v141, v138, v141
	v_mul_f32_e32 v141, 0xc038aa3b, v141
	v_exp_f32_e32 v141, v141
	v_mul_f32_e32 v140, 0x3d122279, v136
	v_fmaak_f32 v140, v136, v140, 0x3f4c422a
	v_mul_f32_e32 v140, v136, v140
	v_add_f32_e32 v141, 1.0, v141
	v_rcp_f32_e32 v142, v141
	v_mul_f32_e32 v141, 0x3d122279, v137
	v_fmaak_f32 v141, v137, v141, 0x3f4c422a
	v_mul_f32_e32 v141, v137, v141
	v_mul_f32_e32 v140, 0xc038aa3b, v140
	v_mul_f32_e32 v141, 0xc038aa3b, v141
	v_exp_f32_e32 v140, v140
	v_exp_f32_e32 v141, v141
	v_mul_f32_e32 v145, 0x3d122279, v134
	v_fmaak_f32 v145, v134, v145, 0x3f4c422a
	v_mul_f32_e32 v145, v134, v145
	v_mul_f32_e32 v145, 0xc038aa3b, v145
	v_add_f32_e32 v140, 1.0, v140
	v_add_f32_e32 v141, 1.0, v141
	v_exp_f32_e32 v145, v145
	v_rcp_f32_e32 v140, v140
	v_rcp_f32_e32 v141, v141
	v_mul_f32_e32 v143, 0x3d122279, v139
	v_add_f32_e32 v145, 1.0, v145
	v_mul_f32_e32 v144, 0x3d122279, v132
	v_rcp_f32_e32 v146, v145
	v_mul_f32_e32 v145, 0x3d122279, v133
	v_pk_mul_f32 v[136:137], v[136:137], v[140:141]
	v_mul_f32_e32 v140, 0x3d122279, v135
	v_fmaak_f32 v143, v139, v143, 0x3f4c422a
	v_fmaak_f32 v144, v132, v144, 0x3f4c422a
	v_fmaak_f32 v145, v133, v145, 0x3f4c422a
	v_fmaak_f32 v140, v135, v140, 0x3f4c422a
	v_mul_f32_e32 v143, v139, v143
	v_mul_f32_e32 v144, v132, v144
	v_mul_f32_e32 v145, v133, v145
	v_mul_f32_e32 v140, v135, v140
	v_mul_f32_e32 v143, 0xc038aa3b, v143
	v_mul_f32_e32 v144, 0xc038aa3b, v144
	v_mul_f32_e32 v145, 0xc038aa3b, v145
	v_mul_f32_e32 v140, 0xc038aa3b, v140
	v_exp_f32_e32 v143, v143
	v_exp_f32_e32 v144, v144
	v_exp_f32_e32 v145, v145
	v_exp_f32_e32 v140, v140
	v_add_f32_e32 v143, 1.0, v143
	v_add_f32_e32 v144, 1.0, v144
	v_add_f32_e32 v145, 1.0, v145
	v_add_f32_e32 v140, 1.0, v140
	v_rcp_f32_e32 v143, v143
	v_rcp_f32_e32 v144, v144
	v_rcp_f32_e32 v145, v145
	v_rcp_f32_e32 v147, v140
	v_pk_mul_f32 v[138:139], v[138:139], v[142:143]
	v_pk_mul_f32 v[132:133], v[132:133], v[144:145]
	v_pk_mul_f32 v[134:135], v[134:135], v[146:147]
.LBB0_131:
	v_cvt_pk_bf16_f32 v136, v136, v137
	v_cvt_pk_bf16_f32 v137, v132, v133
	v_cvt_pk_bf16_f32 v138, v138, v139
	s_nop 0
	v_cvt_pk_bf16_f32 v139, v134, v135
	ds_bpermute_b32 v140, v255, v130
	ds_bpermute_b32 v141, v255, v131
	ds_bpermute_b32 v142, v255, v136
	ds_bpermute_b32 v143, v255, v137
	ds_bpermute_b32 v144, v255, v138
	ds_bpermute_b32 v145, v255, v139
	s_waitcnt lgkmcnt(0)
	global_store_dwordx4 v[140:141], v[142:145], off offset:256
	v_pk_mul_f32 v[132:133], v[96:97], v[184:185] op_sel_hi:[1,0]
	v_pk_mul_f32 v[134:135], v[92:93], v[184:185] op_sel_hi:[1,0]
	v_pk_mul_f32 v[136:137], v[94:95], v[184:185] op_sel_hi:[1,0]
	s_and_b64 vcc, exec, s[4:5]
	v_pk_mul_f32 v[138:139], v[90:91], v[184:185] op_sel_hi:[1,0]
	s_cbranch_vccnz .LBB0_133
	v_mul_f32_e32 v131, 0x3d122279, v138
	v_fmaak_f32 v131, v138, v131, 0x3f4c422a
	v_mul_f32_e32 v131, v138, v131
	v_mul_f32_e32 v131, 0xc038aa3b, v131
	v_exp_f32_e32 v131, v131
	v_mul_f32_e32 v130, 0x3d122279, v136
	v_fmaak_f32 v130, v136, v130, 0x3f4c422a
	v_mul_f32_e32 v130, v136, v130
	v_add_f32_e32 v131, 1.0, v131
	v_rcp_f32_e32 v140, v131
	v_mul_f32_e32 v131, 0x3d122279, v137
	v_fmaak_f32 v131, v137, v131, 0x3f4c422a
	v_mul_f32_e32 v131, v137, v131
	v_mul_f32_e32 v130, 0xc038aa3b, v130
	v_mul_f32_e32 v131, 0xc038aa3b, v131
	v_exp_f32_e32 v130, v130
	v_exp_f32_e32 v131, v131
	v_mul_f32_e32 v143, 0x3d122279, v134
	v_fmaak_f32 v143, v134, v143, 0x3f4c422a
	v_mul_f32_e32 v143, v134, v143
	v_mul_f32_e32 v143, 0xc038aa3b, v143
	v_add_f32_e32 v130, 1.0, v130
	v_add_f32_e32 v131, 1.0, v131
	v_exp_f32_e32 v143, v143
	v_rcp_f32_e32 v130, v130
	v_rcp_f32_e32 v131, v131
	v_mul_f32_e32 v141, 0x3d122279, v139
	v_add_f32_e32 v143, 1.0, v143
	v_mul_f32_e32 v142, 0x3d122279, v132
	v_rcp_f32_e32 v144, v143
	v_mul_f32_e32 v143, 0x3d122279, v133
	v_pk_mul_f32 v[136:137], v[136:137], v[130:131]
	v_mul_f32_e32 v130, 0x3d122279, v135
	v_fmaak_f32 v141, v139, v141, 0x3f4c422a
	v_fmaak_f32 v142, v132, v142, 0x3f4c422a
	v_fmaak_f32 v143, v133, v143, 0x3f4c422a
	v_fmaak_f32 v130, v135, v130, 0x3f4c422a
	v_mul_f32_e32 v141, v139, v141
	v_mul_f32_e32 v142, v132, v142
	v_mul_f32_e32 v143, v133, v143
	v_mul_f32_e32 v130, v135, v130
	v_mul_f32_e32 v141, 0xc038aa3b, v141
	v_mul_f32_e32 v142, 0xc038aa3b, v142
	v_mul_f32_e32 v143, 0xc038aa3b, v143
	v_mul_f32_e32 v130, 0xc038aa3b, v130
	v_exp_f32_e32 v141, v141
	v_exp_f32_e32 v142, v142
	v_exp_f32_e32 v143, v143
	v_exp_f32_e32 v130, v130
	v_add_f32_e32 v141, 1.0, v141
	v_add_f32_e32 v142, 1.0, v142
	v_add_f32_e32 v143, 1.0, v143
	v_add_f32_e32 v130, 1.0, v130
	v_rcp_f32_e32 v141, v141
	v_rcp_f32_e32 v142, v142
	v_rcp_f32_e32 v143, v143
	v_rcp_f32_e32 v145, v130
	v_pk_mul_f32 v[138:139], v[138:139], v[140:141]
	v_pk_mul_f32 v[132:133], v[132:133], v[142:143]
	v_pk_mul_f32 v[134:135], v[134:135], v[144:145]
; __device__ __forceinline__ unsigned cvt_pk_bf16(float lo, float hi) { unsigned r; asm volatile("v_cvt_pk_bf16_f32 %0, %1, %2" : "=v"(r) : "v"(lo), "v"(hi)); return r; }
; #define EPI_FENCE() asm volatile("" ::: "memory")
; __device__ __forceinline__ float gelu_tanh(float x) {
;     const float y = x * (0.7978845608028654f + 0.7978845608028654f * 0.044715f * x * x);
;     const float e = __builtin_amdgcn_exp2f(-2.0f * 1.4426950408889634f * y);
;     return x * __builtin_amdgcn_rcpf(1.0f + e);
; }
;     __device__ __forceinline__ void operator()(const f32x4 (&acc)[2][2][4][2], const Unit& u, int wr, int wc, int fr, int fq) const {
;     ...
;         } else {
;             EPI_FENCE();
; #pragma unroll
;             for (int i = 0; i < 8; ++i) {
;                 const int ai = i >> 2, m = i & 3; bf16_t* rowp = Z + (size_t)(row0 + ai * HALF + m * 16) * 5120 + col0;
; #pragma unroll
;                 for (int bj = 0; bj < 2; ++bj) {
;                     f32x4 v0 = acc[ai][bj][m][0] * rs[i], v1 = acc[ai][bj][m][1] * rs[i];
;                     if (kind == 2) {
; #pragma unroll
;                         for (int e = 0; e < 4; ++e) { v0[e] = gelu_tanh(v0[e]); v1[e] = gelu_tanh(v1[e]); }
;                     }
;                     u32x4 w; w.x = cvt_pk_bf16(v0[0], v0[1]); w.y = cvt_pk_bf16(v0[2], v0[3]); w.z = cvt_pk_bf16(v1[0], v1[1]); w.w = cvt_pk_bf16(v1[2], v1[3]);
;                     *(u32x4*)(rowp + bj * HALF) = w;
;                 }
;             }
.LBB0_133:
	v_or_b32_e32 v142, 32, v206
	v_mov_b64_e32 v[130:131], s[8:9]
	v_mad_i64_i32 v[130:131], s[2:3], v142, s59, v[130:131]
	v_mov_b32_e32 v140, v184
	v_mov_b32_e32 v141, v184
	v_lshl_add_u64 v[130:131], v[188:189], 1, v[130:131]
	v_cvt_pk_bf16_f32 v136, v136, v137
	v_cvt_pk_bf16_f32 v137, v132, v133
	v_cvt_pk_bf16_f32 v138, v138, v139
	v_cvt_pk_bf16_f32 v139, v134, v135
	v_mov_b32_e32 v134, v184
	v_mov_b32_e32 v135, v184
	ds_bpermute_b32 v142, v255, v130
	ds_bpermute_b32 v143, v255, v131
	ds_bpermute_b32 v144, v255, v136
	ds_bpermute_b32 v145, v255, v137
	ds_bpermute_b32 v146, v255, v138
	ds_bpermute_b32 v147, v255, v139
	s_waitcnt lgkmcnt(0)
	global_store_dwordx4 v[142:143], v[144:147], off
	v_pk_mul_f32 v[132:133], v[88:89], v[134:135]
	v_pk_mul_f32 v[134:135], v[84:85], v[134:135]
	v_pk_mul_f32 v[136:137], v[86:87], v[140:141]
	s_and_b64 vcc, exec, s[4:5]
	v_pk_mul_f32 v[138:139], v[82:83], v[140:141]
	s_cbranch_vccnz .LBB0_135
	v_mul_f32_e32 v141, 0x3d122279, v138
	v_fmaak_f32 v141, v138, v141, 0x3f4c422a
	v_mul_f32_e32 v141, v138, v141
	v_mul_f32_e32 v141, 0xc038aa3b, v141
	v_exp_f32_e32 v141, v141
	v_mul_f32_e32 v140, 0x3d122279, v136
	v_fmaak_f32 v140, v136, v140, 0x3f4c422a
	v_mul_f32_e32 v140, v136, v140
	v_add_f32_e32 v141, 1.0, v141
	v_rcp_f32_e32 v142, v141
	v_mul_f32_e32 v141, 0x3d122279, v137
	v_fmaak_f32 v141, v137, v141, 0x3f4c422a
	v_mul_f32_e32 v141, v137, v141
	v_mul_f32_e32 v140, 0xc038aa3b, v140
	v_mul_f32_e32 v141, 0xc038aa3b, v141
	v_exp_f32_e32 v140, v140
	v_exp_f32_e32 v141, v141
	v_mul_f32_e32 v145, 0x3d122279, v134
	v_fmaak_f32 v145, v134, v145, 0x3f4c422a
	v_mul_f32_e32 v145, v134, v145
	v_mul_f32_e32 v145, 0xc038aa3b, v145
	v_add_f32_e32 v140, 1.0, v140
	v_add_f32_e32 v141, 1.0, v141
	v_exp_f32_e32 v145, v145
	v_rcp_f32_e32 v140, v140
	v_rcp_f32_e32 v141, v141
	v_mul_f32_e32 v143, 0x3d122279, v139
	v_add_f32_e32 v145, 1.0, v145
	v_mul_f32_e32 v144, 0x3d122279, v132
	v_rcp_f32_e32 v146, v145
	v_mul_f32_e32 v145, 0x3d122279, v133
	v_pk_mul_f32 v[136:137], v[136:137], v[140:141]
	v_mul_f32_e32 v140, 0x3d122279, v135
	v_fmaak_f32 v143, v139, v143, 0x3f4c422a
	v_fmaak_f32 v144, v132, v144, 0x3f4c422a
	v_fmaak_f32 v145, v133, v145, 0x3f4c422a
	v_fmaak_f32 v140, v135, v140, 0x3f4c422a
	v_mul_f32_e32 v143, v139, v143
	v_mul_f32_e32 v144, v132, v144
	v_mul_f32_e32 v145, v133, v145
	v_mul_f32_e32 v140, v135, v140
	v_mul_f32_e32 v143, 0xc038aa3b, v143
	v_mul_f32_e32 v144, 0xc038aa3b, v144
	v_mul_f32_e32 v145, 0xc038aa3b, v145
	v_mul_f32_e32 v140, 0xc038aa3b, v140
	v_exp_f32_e32 v143, v143
	v_exp_f32_e32 v144, v144
	v_exp_f32_e32 v145, v145
	v_exp_f32_e32 v140, v140
	v_add_f32_e32 v143, 1.0, v143
	v_add_f32_e32 v144, 1.0, v144
	v_add_f32_e32 v145, 1.0, v145
	v_add_f32_e32 v140, 1.0, v140
	v_rcp_f32_e32 v143, v143
	v_rcp_f32_e32 v144, v144
	v_rcp_f32_e32 v145, v145
	v_rcp_f32_e32 v147, v140
	v_pk_mul_f32 v[138:139], v[138:139], v[142:143]
	v_pk_mul_f32 v[132:133], v[132:133], v[144:145]
	v_pk_mul_f32 v[134:135], v[134:135], v[146:147]
.LBB0_135:
	v_cvt_pk_bf16_f32 v136, v136, v137
	v_cvt_pk_bf16_f32 v137, v132, v133
	v_cvt_pk_bf16_f32 v138, v138, v139
	s_nop 0
	v_cvt_pk_bf16_f32 v139, v134, v135
	ds_bpermute_b32 v140, v255, v130
	ds_bpermute_b32 v141, v255, v131
	ds_bpermute_b32 v142, v255, v136
	ds_bpermute_b32 v143, v255, v137
	ds_bpermute_b32 v144, v255, v138
	ds_bpermute_b32 v145, v255, v139
	s_waitcnt lgkmcnt(0)
	global_store_dwordx4 v[140:141], v[142:145], off offset:256
	v_mov_b32_e32 v130, v185
	v_pk_mul_f32 v[132:133], v[80:81], v[130:131] op_sel_hi:[1,0]
	v_pk_mul_f32 v[136:137], v[78:79], v[130:131] op_sel_hi:[1,0]
	v_pk_mul_f32 v[134:135], v[76:77], v[130:131] op_sel_hi:[1,0]
	s_and_b64 vcc, exec, s[4:5]
	v_pk_mul_f32 v[138:139], v[74:75], v[130:131] op_sel_hi:[1,0]
	s_cbranch_vccnz .LBB0_137
	v_mul_f32_e32 v131, 0x3d122279, v138
	v_fmaak_f32 v131, v138, v131, 0x3f4c422a
	v_mul_f32_e32 v131, v138, v131
	v_mul_f32_e32 v131, 0xc038aa3b, v131
	v_exp_f32_e32 v131, v131
	v_mul_f32_e32 v130, 0x3d122279, v136
	v_fmaak_f32 v130, v136, v130, 0x3f4c422a
	v_mul_f32_e32 v130, v136, v130
	v_add_f32_e32 v131, 1.0, v131
	v_rcp_f32_e32 v140, v131
	v_mul_f32_e32 v131, 0x3d122279, v137
	v_fmaak_f32 v131, v137, v131, 0x3f4c422a
	v_mul_f32_e32 v131, v137, v131
	v_mul_f32_e32 v130, 0xc038aa3b, v130
	v_mul_f32_e32 v131, 0xc038aa3b, v131
	v_exp_f32_e32 v130, v130
	v_exp_f32_e32 v131, v131
	v_mul_f32_e32 v143, 0x3d122279, v134
	v_fmaak_f32 v143, v134, v143, 0x3f4c422a
	v_mul_f32_e32 v143, v134, v143
	v_mul_f32_e32 v143, 0xc038aa3b, v143
	v_add_f32_e32 v130, 1.0, v130
	v_add_f32_e32 v131, 1.0, v131
	v_exp_f32_e32 v143, v143
	v_rcp_f32_e32 v130, v130
	v_rcp_f32_e32 v131, v131
	v_mul_f32_e32 v141, 0x3d122279, v139
	v_add_f32_e32 v143, 1.0, v143
	v_mul_f32_e32 v142, 0x3d122279, v132
	v_rcp_f32_e32 v144, v143
	v_mul_f32_e32 v143, 0x3d122279, v133
	v_pk_mul_f32 v[136:137], v[136:137], v[130:131]
	v_mul_f32_e32 v130, 0x3d122279, v135
	v_fmaak_f32 v141, v139, v141, 0x3f4c422a
	v_fmaak_f32 v142, v132, v142, 0x3f4c422a
	v_fmaak_f32 v143, v133, v143, 0x3f4c422a
	v_fmaak_f32 v130, v135, v130, 0x3f4c422a
	v_mul_f32_e32 v141, v139, v141
	v_mul_f32_e32 v142, v132, v142
	v_mul_f32_e32 v143, v133, v143
	v_mul_f32_e32 v130, v135, v130
	v_mul_f32_e32 v141, 0xc038aa3b, v141
	v_mul_f32_e32 v142, 0xc038aa3b, v142
	v_mul_f32_e32 v143, 0xc038aa3b, v143
	v_mul_f32_e32 v130, 0xc038aa3b, v130
	v_exp_f32_e32 v141, v141
	v_exp_f32_e32 v142, v142
	v_exp_f32_e32 v143, v143
	v_exp_f32_e32 v130, v130
	v_add_f32_e32 v141, 1.0, v141
	v_add_f32_e32 v142, 1.0, v142
	v_add_f32_e32 v143, 1.0, v143
	v_add_f32_e32 v130, 1.0, v130
	v_rcp_f32_e32 v141, v141
	v_rcp_f32_e32 v142, v142
	v_rcp_f32_e32 v143, v143
	v_rcp_f32_e32 v145, v130
	v_pk_mul_f32 v[138:139], v[138:139], v[140:141]
	v_pk_mul_f32 v[132:133], v[132:133], v[142:143]
	v_pk_mul_f32 v[134:135], v[134:135], v[144:145]
; __device__ __forceinline__ unsigned cvt_pk_bf16(float lo, float hi) { unsigned r; asm volatile("v_cvt_pk_bf16_f32 %0, %1, %2" : "=v"(r) : "v"(lo), "v"(hi)); return r; }
; #define EPI_FENCE() asm volatile("" ::: "memory")
; __device__ __forceinline__ float gelu_tanh(float x) {
;     const float y = x * (0.7978845608028654f + 0.7978845608028654f * 0.044715f * x * x);
;     const float e = __builtin_amdgcn_exp2f(-2.0f * 1.4426950408889634f * y);
;     return x * __builtin_amdgcn_rcpf(1.0f + e);
; }
;     __device__ __forceinline__ void operator()(const f32x4 (&acc)[2][2][4][2], const Unit& u, int wr, int wc, int fr, int fq) const {
;     ...
;         } else {
;             EPI_FENCE();
; #pragma unroll
;             for (int i = 0; i < 8; ++i) {
;                 const int ai = i >> 2, m = i & 3; bf16_t* rowp = Z + (size_t)(row0 + ai * HALF + m * 16) * 5120 + col0;
; #pragma unroll
;                 for (int bj = 0; bj < 2; ++bj) {
;                     f32x4 v0 = acc[ai][bj][m][0] * rs[i], v1 = acc[ai][bj][m][1] * rs[i];
;                     if (kind == 2) {
; #pragma unroll
;                         for (int e = 0; e < 4; ++e) { v0[e] = gelu_tanh(v0[e]); v1[e] = gelu_tanh(v1[e]); }
;                     }
;                     u32x4 w; w.x = cvt_pk_bf16(v0[0], v0[1]); w.y = cvt_pk_bf16(v0[2], v0[3]); w.z = cvt_pk_bf16(v1[0], v1[1]); w.w = cvt_pk_bf16(v1[2], v1[3]);
;                     *(u32x4*)(rowp + bj * HALF) = w;
;                 }
;             }
.LBB0_137:
	v_or_b32_e32 v142, 48, v206
	v_mov_b64_e32 v[130:131], s[8:9]
	v_mad_i64_i32 v[130:131], s[2:3], v142, s59, v[130:131]
	v_mov_b32_e32 v140, v185
	v_mov_b32_e32 v141, v185
	v_lshl_add_u64 v[130:131], v[188:189], 1, v[130:131]
	v_cvt_pk_bf16_f32 v136, v136, v137
	v_cvt_pk_bf16_f32 v137, v132, v133
	v_cvt_pk_bf16_f32 v138, v138, v139
	v_cvt_pk_bf16_f32 v139, v134, v135
	v_mov_b32_e32 v134, v185
	v_mov_b32_e32 v135, v185
	ds_bpermute_b32 v142, v255, v130
	ds_bpermute_b32 v143, v255, v131
	ds_bpermute_b32 v144, v255, v136
	ds_bpermute_b32 v145, v255, v137
	ds_bpermute_b32 v146, v255, v138
	ds_bpermute_b32 v147, v255, v139
	s_waitcnt lgkmcnt(0)
	global_store_dwordx4 v[142:143], v[144:147], off
	v_pk_mul_f32 v[132:133], v[72:73], v[134:135]
	v_pk_mul_f32 v[134:135], v[68:69], v[134:135]
	v_pk_mul_f32 v[136:137], v[70:71], v[140:141]
	s_and_b64 vcc, exec, s[4:5]
	v_pk_mul_f32 v[138:139], v[66:67], v[140:141]
	s_cbranch_vccnz .LBB0_139
	v_mul_f32_e32 v141, 0x3d122279, v138
	v_fmaak_f32 v141, v138, v141, 0x3f4c422a
	v_mul_f32_e32 v141, v138, v141
	v_mul_f32_e32 v141, 0xc038aa3b, v141
	v_exp_f32_e32 v141, v141
	v_mul_f32_e32 v140, 0x3d122279, v136
	v_fmaak_f32 v140, v136, v140, 0x3f4c422a
	v_mul_f32_e32 v140, v136, v140
	v_add_f32_e32 v141, 1.0, v141
	v_rcp_f32_e32 v142, v141
	v_mul_f32_e32 v141, 0x3d122279, v137
	v_fmaak_f32 v141, v137, v141, 0x3f4c422a
	v_mul_f32_e32 v141, v137, v141
	v_mul_f32_e32 v140, 0xc038aa3b, v140
	v_mul_f32_e32 v141, 0xc038aa3b, v141
	v_exp_f32_e32 v140, v140
	v_exp_f32_e32 v141, v141
	v_mul_f32_e32 v145, 0x3d122279, v134
	v_fmaak_f32 v145, v134, v145, 0x3f4c422a
	v_mul_f32_e32 v145, v134, v145
	v_mul_f32_e32 v145, 0xc038aa3b, v145
	v_add_f32_e32 v140, 1.0, v140
	v_add_f32_e32 v141, 1.0, v141
	v_exp_f32_e32 v145, v145
	v_rcp_f32_e32 v140, v140
	v_rcp_f32_e32 v141, v141
	v_mul_f32_e32 v143, 0x3d122279, v139
	v_add_f32_e32 v145, 1.0, v145
	v_mul_f32_e32 v144, 0x3d122279, v132
	v_rcp_f32_e32 v146, v145
	v_mul_f32_e32 v145, 0x3d122279, v133
	v_pk_mul_f32 v[136:137], v[136:137], v[140:141]
	v_mul_f32_e32 v140, 0x3d122279, v135
	v_fmaak_f32 v143, v139, v143, 0x3f4c422a
	v_fmaak_f32 v144, v132, v144, 0x3f4c422a
	v_fmaak_f32 v145, v133, v145, 0x3f4c422a
	v_fmaak_f32 v140, v135, v140, 0x3f4c422a
	v_mul_f32_e32 v143, v139, v143
	v_mul_f32_e32 v144, v132, v144
	v_mul_f32_e32 v145, v133, v145
	v_mul_f32_e32 v140, v135, v140
	v_mul_f32_e32 v143, 0xc038aa3b, v143
	v_mul_f32_e32 v144, 0xc038aa3b, v144
	v_mul_f32_e32 v145, 0xc038aa3b, v145
	v_mul_f32_e32 v140, 0xc038aa3b, v140
	v_exp_f32_e32 v143, v143
	v_exp_f32_e32 v144, v144
	v_exp_f32_e32 v145, v145
	v_exp_f32_e32 v140, v140
	v_add_f32_e32 v143, 1.0, v143
	v_add_f32_e32 v144, 1.0, v144
	v_add_f32_e32 v145, 1.0, v145
	v_add_f32_e32 v140, 1.0, v140
	v_rcp_f32_e32 v143, v143
	v_rcp_f32_e32 v144, v144
	v_rcp_f32_e32 v145, v145
	v_rcp_f32_e32 v147, v140
	v_pk_mul_f32 v[138:139], v[138:139], v[142:143]
	v_pk_mul_f32 v[132:133], v[132:133], v[144:145]
	v_pk_mul_f32 v[134:135], v[134:135], v[146:147]
.LBB0_139:
	v_cvt_pk_bf16_f32 v136, v136, v137
	v_cvt_pk_bf16_f32 v137, v132, v133
	v_cvt_pk_bf16_f32 v138, v138, v139
	s_nop 0
	v_cvt_pk_bf16_f32 v139, v134, v135
	ds_bpermute_b32 v140, v255, v130
	ds_bpermute_b32 v141, v255, v131
	ds_bpermute_b32 v142, v255, v136
	ds_bpermute_b32 v143, v255, v137
	ds_bpermute_b32 v144, v255, v138
	ds_bpermute_b32 v145, v255, v139
	s_waitcnt lgkmcnt(0)
	global_store_dwordx4 v[140:141], v[142:145], off offset:256
	v_pk_mul_f32 v[132:133], v[64:65], v[182:183] op_sel_hi:[1,0]
	v_pk_mul_f32 v[134:135], v[60:61], v[182:183] op_sel_hi:[1,0]
	v_pk_mul_f32 v[136:137], v[62:63], v[182:183] op_sel_hi:[1,0]
	s_and_b64 vcc, exec, s[4:5]
	v_pk_mul_f32 v[138:139], v[58:59], v[182:183] op_sel_hi:[1,0]
	s_cbranch_vccnz .LBB0_141
	v_mul_f32_e32 v131, 0x3d122279, v138
	v_fmaak_f32 v131, v138, v131, 0x3f4c422a
	v_mul_f32_e32 v131, v138, v131
	v_mul_f32_e32 v131, 0xc038aa3b, v131
	v_exp_f32_e32 v131, v131
	v_mul_f32_e32 v130, 0x3d122279, v136
	v_fmaak_f32 v130, v136, v130, 0x3f4c422a
	v_mul_f32_e32 v130, v136, v130
	v_add_f32_e32 v131, 1.0, v131
	v_rcp_f32_e32 v140, v131
	v_mul_f32_e32 v131, 0x3d122279, v137
	v_fmaak_f32 v131, v137, v131, 0x3f4c422a
	v_mul_f32_e32 v131, v137, v131
	v_mul_f32_e32 v130, 0xc038aa3b, v130
	v_mul_f32_e32 v131, 0xc038aa3b, v131
	v_exp_f32_e32 v130, v130
	v_exp_f32_e32 v131, v131
	v_mul_f32_e32 v143, 0x3d122279, v134
	v_fmaak_f32 v143, v134, v143, 0x3f4c422a
	v_mul_f32_e32 v143, v134, v143
	v_mul_f32_e32 v143, 0xc038aa3b, v143
	v_add_f32_e32 v130, 1.0, v130
	v_add_f32_e32 v131, 1.0, v131
	v_exp_f32_e32 v143, v143
	v_rcp_f32_e32 v130, v130
	v_rcp_f32_e32 v131, v131
	v_mul_f32_e32 v141, 0x3d122279, v139
	v_add_f32_e32 v143, 1.0, v143
	v_mul_f32_e32 v142, 0x3d122279, v132
	v_rcp_f32_e32 v144, v143
	v_mul_f32_e32 v143, 0x3d122279, v133
	v_pk_mul_f32 v[136:137], v[136:137], v[130:131]
	v_mul_f32_e32 v130, 0x3d122279, v135
	v_fmaak_f32 v141, v139, v141, 0x3f4c422a
	v_fmaak_f32 v142, v132, v142, 0x3f4c422a
	v_fmaak_f32 v143, v133, v143, 0x3f4c422a
	v_fmaak_f32 v130, v135, v130, 0x3f4c422a
	v_mul_f32_e32 v141, v139, v141
	v_mul_f32_e32 v142, v132, v142
	v_mul_f32_e32 v143, v133, v143
	v_mul_f32_e32 v130, v135, v130
	v_mul_f32_e32 v141, 0xc038aa3b, v141
	v_mul_f32_e32 v142, 0xc038aa3b, v142
	v_mul_f32_e32 v143, 0xc038aa3b, v143
	v_mul_f32_e32 v130, 0xc038aa3b, v130
	v_exp_f32_e32 v141, v141
	v_exp_f32_e32 v142, v142
	v_exp_f32_e32 v143, v143
	v_exp_f32_e32 v130, v130
	v_add_f32_e32 v141, 1.0, v141
	v_add_f32_e32 v142, 1.0, v142
	v_add_f32_e32 v143, 1.0, v143
	v_add_f32_e32 v130, 1.0, v130
	v_rcp_f32_e32 v141, v141
	v_rcp_f32_e32 v142, v142
	v_rcp_f32_e32 v143, v143
	v_rcp_f32_e32 v145, v130
	v_pk_mul_f32 v[138:139], v[138:139], v[140:141]
	v_pk_mul_f32 v[132:133], v[132:133], v[142:143]
	v_pk_mul_f32 v[134:135], v[134:135], v[144:145]
; __device__ __forceinline__ unsigned cvt_pk_bf16(float lo, float hi) { unsigned r; asm volatile("v_cvt_pk_bf16_f32 %0, %1, %2" : "=v"(r) : "v"(lo), "v"(hi)); return r; }
; #define EPI_FENCE() asm volatile("" ::: "memory")
; __device__ __forceinline__ float gelu_tanh(float x) {
;     const float y = x * (0.7978845608028654f + 0.7978845608028654f * 0.044715f * x * x);
;     const float e = __builtin_amdgcn_exp2f(-2.0f * 1.4426950408889634f * y);
;     return x * __builtin_amdgcn_rcpf(1.0f + e);
; }
;     __device__ __forceinline__ void operator()(const f32x4 (&acc)[2][2][4][2], const Unit& u, int wr, int wc, int fr, int fq) const {
;     ...
;         } else {
;             EPI_FENCE();
; #pragma unroll
;             for (int i = 0; i < 8; ++i) {
;                 const int ai = i >> 2, m = i & 3; bf16_t* rowp = Z + (size_t)(row0 + ai * HALF + m * 16) * 5120 + col0;
; #pragma unroll
;                 for (int bj = 0; bj < 2; ++bj) {
;                     f32x4 v0 = acc[ai][bj][m][0] * rs[i], v1 = acc[ai][bj][m][1] * rs[i];
;                     if (kind == 2) {
; #pragma unroll
;                         for (int e = 0; e < 4; ++e) { v0[e] = gelu_tanh(v0[e]); v1[e] = gelu_tanh(v1[e]); }
;                     }
;                     u32x4 w; w.x = cvt_pk_bf16(v0[0], v0[1]); w.y = cvt_pk_bf16(v0[2], v0[3]); w.z = cvt_pk_bf16(v1[0], v1[1]); w.w = cvt_pk_bf16(v1[2], v1[3]);
;                     *(u32x4*)(rowp + bj * HALF) = w;
;                 }
;             }
.LBB0_141:
	v_add_u32_e32 v140, 0x80, v206
	v_mov_b64_e32 v[130:131], s[8:9]
	v_mad_i64_i32 v[130:131], s[2:3], v140, s59, v[130:131]
	v_mov_b32_e32 v142, v182
	v_mov_b32_e32 v143, v182
	v_lshl_add_u64 v[130:131], v[188:189], 1, v[130:131]
	v_cvt_pk_bf16_f32 v136, v136, v137
	v_cvt_pk_bf16_f32 v137, v132, v133
	v_cvt_pk_bf16_f32 v138, v138, v139
	v_cvt_pk_bf16_f32 v139, v134, v135
	v_mov_b32_e32 v134, v182
	v_mov_b32_e32 v135, v182
	ds_bpermute_b32 v144, v255, v130
	ds_bpermute_b32 v145, v255, v131
	ds_bpermute_b32 v146, v255, v136
	ds_bpermute_b32 v147, v255, v137
	ds_bpermute_b32 v148, v255, v138
	ds_bpermute_b32 v149, v255, v139
	s_waitcnt lgkmcnt(0)
	global_store_dwordx4 v[144:145], v[146:149], off
	v_pk_mul_f32 v[132:133], v[56:57], v[134:135]
	v_pk_mul_f32 v[134:135], v[52:53], v[134:135]
	v_pk_mul_f32 v[136:137], v[54:55], v[142:143]
	s_and_b64 vcc, exec, s[4:5]
	v_pk_mul_f32 v[138:139], v[50:51], v[142:143]
	s_cbranch_vccnz .LBB0_143
	v_mul_f32_e32 v141, 0x3d122279, v136
	v_fmaak_f32 v141, v136, v141, 0x3f4c422a
	v_mul_f32_e32 v141, v136, v141
	v_mul_f32_e32 v141, 0xc038aa3b, v141
	v_exp_f32_e32 v141, v141
	s_nop 0
	v_add_f32_e32 v141, 1.0, v141
	v_rcp_f32_e32 v142, v141
	v_mul_f32_e32 v141, 0x3d122279, v138
	v_fmaak_f32 v141, v138, v141, 0x3f4c422a
	v_mul_f32_e32 v141, v138, v141
	v_mul_f32_e32 v141, 0xc038aa3b, v141
	v_exp_f32_e32 v141, v141
	s_nop 0
	v_add_f32_e32 v141, 1.0, v141
	v_rcp_f32_e32 v144, v141
	v_mul_f32_e32 v141, 0x3d122279, v137
	v_fmaak_f32 v141, v137, v141, 0x3f4c422a
	v_mul_f32_e32 v141, v137, v141
	v_mul_f32_e32 v141, 0xc038aa3b, v141
	v_exp_f32_e32 v141, v141
	s_nop 0
	v_add_f32_e32 v141, 1.0, v141
	v_rcp_f32_e32 v143, v141
	v_mul_f32_e32 v141, 0x3d122279, v139
	v_fmaak_f32 v141, v139, v141, 0x3f4c422a
	v_mul_f32_e32 v141, v139, v141
	v_mul_f32_e32 v141, 0xc038aa3b, v141
	v_exp_f32_e32 v141, v141
	v_pk_mul_f32 v[136:137], v[136:137], v[142:143]
	v_add_f32_e32 v141, 1.0, v141
	v_rcp_f32_e32 v145, v141
	v_mul_f32_e32 v141, 0x3d122279, v132
	v_fmaak_f32 v141, v132, v141, 0x3f4c422a
	v_mul_f32_e32 v141, v132, v141
	v_mul_f32_e32 v141, 0xc038aa3b, v141
	v_exp_f32_e32 v141, v141
	v_pk_mul_f32 v[138:139], v[138:139], v[144:145]
	v_add_f32_e32 v141, 1.0, v141
	v_rcp_f32_e32 v146, v141
	v_mul_f32_e32 v141, 0x3d122279, v134
	v_fmaak_f32 v141, v134, v141, 0x3f4c422a
	v_mul_f32_e32 v141, v134, v141
	v_mul_f32_e32 v141, 0xc038aa3b, v141
	v_exp_f32_e32 v141, v141
	s_nop 0
	v_add_f32_e32 v141, 1.0, v141
	v_rcp_f32_e32 v148, v141
	v_mul_f32_e32 v141, 0x3d122279, v133
	v_fmaak_f32 v141, v133, v141, 0x3f4c422a
	v_mul_f32_e32 v141, v133, v141
	v_mul_f32_e32 v141, 0xc038aa3b, v141
	v_exp_f32_e32 v141, v141
	s_nop 0
	v_add_f32_e32 v141, 1.0, v141
	v_rcp_f32_e32 v147, v141
	v_mul_f32_e32 v141, 0x3d122279, v135
	v_fmaak_f32 v141, v135, v141, 0x3f4c422a
	v_mul_f32_e32 v141, v135, v141
	v_mul_f32_e32 v141, 0xc038aa3b, v141
	v_exp_f32_e32 v141, v141
	v_pk_mul_f32 v[132:133], v[132:133], v[146:147]
	v_add_f32_e32 v141, 1.0, v141
	v_rcp_f32_e32 v149, v141
	s_nop 0
	v_pk_mul_f32 v[134:135], v[134:135], v[148:149]
.LBB0_143:
	v_cvt_pk_bf16_f32 v136, v136, v137
	v_cvt_pk_bf16_f32 v137, v132, v133
	v_cvt_pk_bf16_f32 v138, v138, v139
	s_nop 0
	v_cvt_pk_bf16_f32 v139, v134, v135
	ds_bpermute_b32 v142, v255, v130
	ds_bpermute_b32 v143, v255, v131
	ds_bpermute_b32 v144, v255, v136
	ds_bpermute_b32 v145, v255, v137
	ds_bpermute_b32 v146, v255, v138
	ds_bpermute_b32 v147, v255, v139
	s_waitcnt lgkmcnt(0)
	global_store_dwordx4 v[142:143], v[144:147], off offset:256
	v_mov_b32_e32 v130, v183
	v_pk_mul_f32 v[132:133], v[48:49], v[130:131] op_sel_hi:[1,0]
	v_pk_mul_f32 v[136:137], v[46:47], v[130:131] op_sel_hi:[1,0]
	v_pk_mul_f32 v[134:135], v[44:45], v[130:131] op_sel_hi:[1,0]
	s_and_b64 vcc, exec, s[4:5]
	v_pk_mul_f32 v[138:139], v[42:43], v[130:131] op_sel_hi:[1,0]
	s_cbranch_vccnz .LBB0_145
	v_mul_f32_e32 v141, 0x3d122279, v139
	v_fmaak_f32 v141, v139, v141, 0x3f4c422a
	v_mul_f32_e32 v141, v139, v141
	v_mul_f32_e32 v141, 0xc038aa3b, v141
	v_exp_f32_e32 v141, v141
	v_mul_f32_e32 v131, 0x3d122279, v138
	v_fmaak_f32 v131, v138, v131, 0x3f4c422a
	v_mul_f32_e32 v131, v138, v131
	v_mul_f32_e32 v131, 0xc038aa3b, v131
	v_add_f32_e32 v141, 1.0, v141
	v_exp_f32_e32 v131, v131
	v_rcp_f32_e32 v143, v141
	v_mul_f32_e32 v141, 0x3d122279, v132
	v_fmaak_f32 v141, v132, v141, 0x3f4c422a
	v_mul_f32_e32 v141, v132, v141
	v_mul_f32_e32 v141, 0xc038aa3b, v141
	v_add_f32_e32 v131, 1.0, v131
	v_exp_f32_e32 v141, v141
	v_mul_f32_e32 v130, 0x3d122279, v136
	v_rcp_f32_e32 v142, v131
	v_mul_f32_e32 v131, 0x3d122279, v137
	v_fmaak_f32 v130, v136, v130, 0x3f4c422a
	v_fmaak_f32 v131, v137, v131, 0x3f4c422a
	v_mul_f32_e32 v130, v136, v130
	v_mul_f32_e32 v131, v137, v131
	v_mul_f32_e32 v130, 0xc038aa3b, v130
	v_mul_f32_e32 v131, 0xc038aa3b, v131
	v_add_f32_e32 v141, 1.0, v141
	v_exp_f32_e32 v130, v130
	v_exp_f32_e32 v131, v131
	v_rcp_f32_e32 v144, v141
	v_mul_f32_e32 v141, 0x3d122279, v134
	v_fmaak_f32 v141, v134, v141, 0x3f4c422a
	v_mul_f32_e32 v141, v134, v141
	v_mul_f32_e32 v141, 0xc038aa3b, v141
	v_add_f32_e32 v130, 1.0, v130
	v_add_f32_e32 v131, 1.0, v131
	v_exp_f32_e32 v141, v141
	v_rcp_f32_e32 v130, v130
	v_rcp_f32_e32 v131, v131
	v_pk_mul_f32 v[138:139], v[138:139], v[142:143]
	v_add_f32_e32 v141, 1.0, v141
	v_rcp_f32_e32 v146, v141
	v_mul_f32_e32 v141, 0x3d122279, v133
	v_pk_mul_f32 v[136:137], v[136:137], v[130:131]
	v_mul_f32_e32 v130, 0x3d122279, v135
	v_fmaak_f32 v141, v133, v141, 0x3f4c422a
	v_fmaak_f32 v130, v135, v130, 0x3f4c422a
	v_mul_f32_e32 v141, v133, v141
	v_mul_f32_e32 v130, v135, v130
	v_mul_f32_e32 v141, 0xc038aa3b, v141
	v_mul_f32_e32 v130, 0xc038aa3b, v130
	v_exp_f32_e32 v141, v141
	v_exp_f32_e32 v130, v130
	v_add_f32_e32 v141, 1.0, v141
	v_add_f32_e32 v130, 1.0, v130
	v_rcp_f32_e32 v145, v141
	v_rcp_f32_e32 v147, v130
	v_pk_mul_f32 v[132:133], v[132:133], v[144:145]
	v_pk_mul_f32 v[134:135], v[134:135], v[146:147]
; __device__ __forceinline__ unsigned cvt_pk_bf16(float lo, float hi) { unsigned r; asm volatile("v_cvt_pk_bf16_f32 %0, %1, %2" : "=v"(r) : "v"(lo), "v"(hi)); return r; }
; #define EPI_FENCE() asm volatile("" ::: "memory")
; __device__ __forceinline__ float gelu_tanh(float x) {
;     const float y = x * (0.7978845608028654f + 0.7978845608028654f * 0.044715f * x * x);
;     const float e = __builtin_amdgcn_exp2f(-2.0f * 1.4426950408889634f * y);
;     return x * __builtin_amdgcn_rcpf(1.0f + e);
; }
;     __device__ __forceinline__ void operator()(const f32x4 (&acc)[2][2][4][2], const Unit& u, int wr, int wc, int fr, int fq) const {
;     ...
;         } else {
;             EPI_FENCE();
; #pragma unroll
;             for (int i = 0; i < 8; ++i) {
;                 const int ai = i >> 2, m = i & 3; bf16_t* rowp = Z + (size_t)(row0 + ai * HALF + m * 16) * 5120 + col0;
; #pragma unroll
;                 for (int bj = 0; bj < 2; ++bj) {
;                     f32x4 v0 = acc[ai][bj][m][0] * rs[i], v1 = acc[ai][bj][m][1] * rs[i];
;                     if (kind == 2) {
; #pragma unroll
;                         for (int e = 0; e < 4; ++e) { v0[e] = gelu_tanh(v0[e]); v1[e] = gelu_tanh(v1[e]); }
;                     }
;                     u32x4 w; w.x = cvt_pk_bf16(v0[0], v0[1]); w.y = cvt_pk_bf16(v0[2], v0[3]); w.z = cvt_pk_bf16(v1[0], v1[1]); w.w = cvt_pk_bf16(v1[2], v1[3]);
;                     *(u32x4*)(rowp + bj * HALF) = w;
;                 }
;             }
.LBB0_145:
	v_or_b32_e32 v141, 16, v140
	v_mov_b64_e32 v[130:131], s[8:9]
	v_mad_i64_i32 v[130:131], s[2:3], v141, s59, v[130:131]
	v_mov_b32_e32 v142, v183
	v_mov_b32_e32 v143, v183
	v_lshl_add_u64 v[130:131], v[188:189], 1, v[130:131]
	v_cvt_pk_bf16_f32 v136, v136, v137
	v_cvt_pk_bf16_f32 v137, v132, v133
	v_cvt_pk_bf16_f32 v138, v138, v139
	v_cvt_pk_bf16_f32 v139, v134, v135
	v_mov_b32_e32 v134, v183
	v_mov_b32_e32 v135, v183
	ds_bpermute_b32 v144, v255, v130
	ds_bpermute_b32 v145, v255, v131
	ds_bpermute_b32 v146, v255, v136
	ds_bpermute_b32 v147, v255, v137
	ds_bpermute_b32 v148, v255, v138
	ds_bpermute_b32 v149, v255, v139
	s_waitcnt lgkmcnt(0)
	global_store_dwordx4 v[144:145], v[146:149], off
	v_pk_mul_f32 v[132:133], v[40:41], v[134:135]
	v_pk_mul_f32 v[134:135], v[36:37], v[134:135]
	v_pk_mul_f32 v[136:137], v[38:39], v[142:143]
	s_and_b64 vcc, exec, s[4:5]
	v_pk_mul_f32 v[138:139], v[34:35], v[142:143]
	s_cbranch_vccnz .LBB0_147
	v_mul_f32_e32 v141, 0x3d122279, v136
	v_fmaak_f32 v141, v136, v141, 0x3f4c422a
	v_mul_f32_e32 v141, v136, v141
	v_mul_f32_e32 v141, 0xc038aa3b, v141
	v_exp_f32_e32 v141, v141
	s_nop 0
	v_add_f32_e32 v141, 1.0, v141
	v_rcp_f32_e32 v142, v141
	v_mul_f32_e32 v141, 0x3d122279, v138
	v_fmaak_f32 v141, v138, v141, 0x3f4c422a
	v_mul_f32_e32 v141, v138, v141
	v_mul_f32_e32 v141, 0xc038aa3b, v141
	v_exp_f32_e32 v141, v141
	s_nop 0
	v_add_f32_e32 v141, 1.0, v141
	v_rcp_f32_e32 v144, v141
	v_mul_f32_e32 v141, 0x3d122279, v137
	v_fmaak_f32 v141, v137, v141, 0x3f4c422a
	v_mul_f32_e32 v141, v137, v141
	v_mul_f32_e32 v141, 0xc038aa3b, v141
	v_exp_f32_e32 v141, v141
	s_nop 0
	v_add_f32_e32 v141, 1.0, v141
	v_rcp_f32_e32 v143, v141
	v_mul_f32_e32 v141, 0x3d122279, v139
	v_fmaak_f32 v141, v139, v141, 0x3f4c422a
	v_mul_f32_e32 v141, v139, v141
	v_mul_f32_e32 v141, 0xc038aa3b, v141
	v_exp_f32_e32 v141, v141
	v_pk_mul_f32 v[136:137], v[136:137], v[142:143]
	v_add_f32_e32 v141, 1.0, v141
	v_rcp_f32_e32 v145, v141
	v_mul_f32_e32 v141, 0x3d122279, v132
	v_fmaak_f32 v141, v132, v141, 0x3f4c422a
	v_mul_f32_e32 v141, v132, v141
	v_mul_f32_e32 v141, 0xc038aa3b, v141
	v_exp_f32_e32 v141, v141
	v_pk_mul_f32 v[138:139], v[138:139], v[144:145]
	v_add_f32_e32 v141, 1.0, v141
	v_rcp_f32_e32 v146, v141
	v_mul_f32_e32 v141, 0x3d122279, v134
	v_fmaak_f32 v141, v134, v141, 0x3f4c422a
	v_mul_f32_e32 v141, v134, v141
	v_mul_f32_e32 v141, 0xc038aa3b, v141
	v_exp_f32_e32 v141, v141
	s_nop 0
	v_add_f32_e32 v141, 1.0, v141
	v_rcp_f32_e32 v148, v141
	v_mul_f32_e32 v141, 0x3d122279, v133
	v_fmaak_f32 v141, v133, v141, 0x3f4c422a
	v_mul_f32_e32 v141, v133, v141
	v_mul_f32_e32 v141, 0xc038aa3b, v141
	v_exp_f32_e32 v141, v141
	s_nop 0
	v_add_f32_e32 v141, 1.0, v141
	v_rcp_f32_e32 v147, v141
	v_mul_f32_e32 v141, 0x3d122279, v135
	v_fmaak_f32 v141, v135, v141, 0x3f4c422a
	v_mul_f32_e32 v141, v135, v141
	v_mul_f32_e32 v141, 0xc038aa3b, v141
	v_exp_f32_e32 v141, v141
	v_pk_mul_f32 v[132:133], v[132:133], v[146:147]
	v_add_f32_e32 v141, 1.0, v141
	v_rcp_f32_e32 v149, v141
	s_nop 0
	v_pk_mul_f32 v[134:135], v[134:135], v[148:149]
.LBB0_147:
	v_cvt_pk_bf16_f32 v136, v136, v137
	v_cvt_pk_bf16_f32 v137, v132, v133
	v_cvt_pk_bf16_f32 v138, v138, v139
	s_nop 0
	v_cvt_pk_bf16_f32 v139, v134, v135
	ds_bpermute_b32 v142, v255, v130
	ds_bpermute_b32 v143, v255, v131
	ds_bpermute_b32 v144, v255, v136
	ds_bpermute_b32 v145, v255, v137
	ds_bpermute_b32 v146, v255, v138
	ds_bpermute_b32 v147, v255, v139
	s_waitcnt lgkmcnt(0)
	global_store_dwordx4 v[142:143], v[144:147], off offset:256
	v_pk_mul_f32 v[132:133], v[32:33], v[180:181] op_sel_hi:[1,0]
	v_pk_mul_f32 v[134:135], v[28:29], v[180:181] op_sel_hi:[1,0]
	v_pk_mul_f32 v[136:137], v[30:31], v[180:181] op_sel_hi:[1,0]
	s_and_b64 vcc, exec, s[4:5]
	v_pk_mul_f32 v[138:139], v[26:27], v[180:181] op_sel_hi:[1,0]
	s_cbranch_vccnz .LBB0_149
	v_mul_f32_e32 v141, 0x3d122279, v139
	v_fmaak_f32 v141, v139, v141, 0x3f4c422a
	v_mul_f32_e32 v141, v139, v141
	v_mul_f32_e32 v141, 0xc038aa3b, v141
	v_exp_f32_e32 v141, v141
	v_mul_f32_e32 v131, 0x3d122279, v138
	v_fmaak_f32 v131, v138, v131, 0x3f4c422a
	v_mul_f32_e32 v131, v138, v131
	v_mul_f32_e32 v131, 0xc038aa3b, v131
	v_add_f32_e32 v141, 1.0, v141
	v_exp_f32_e32 v131, v131
	v_rcp_f32_e32 v143, v141
	v_mul_f32_e32 v141, 0x3d122279, v132
	v_fmaak_f32 v141, v132, v141, 0x3f4c422a
	v_mul_f32_e32 v141, v132, v141
	v_mul_f32_e32 v141, 0xc038aa3b, v141
	v_add_f32_e32 v131, 1.0, v131
	v_exp_f32_e32 v141, v141
	v_mul_f32_e32 v130, 0x3d122279, v136
	v_rcp_f32_e32 v142, v131
	v_mul_f32_e32 v131, 0x3d122279, v137
	v_fmaak_f32 v130, v136, v130, 0x3f4c422a
	v_fmaak_f32 v131, v137, v131, 0x3f4c422a
	v_mul_f32_e32 v130, v136, v130
	v_mul_f32_e32 v131, v137, v131
	v_mul_f32_e32 v130, 0xc038aa3b, v130
	v_mul_f32_e32 v131, 0xc038aa3b, v131
	v_add_f32_e32 v141, 1.0, v141
	v_exp_f32_e32 v130, v130
	v_exp_f32_e32 v131, v131
	v_rcp_f32_e32 v144, v141
	v_mul_f32_e32 v141, 0x3d122279, v134
	v_fmaak_f32 v141, v134, v141, 0x3f4c422a
	v_mul_f32_e32 v141, v134, v141
	v_mul_f32_e32 v141, 0xc038aa3b, v141
	v_add_f32_e32 v130, 1.0, v130
	v_add_f32_e32 v131, 1.0, v131
	v_exp_f32_e32 v141, v141
	v_rcp_f32_e32 v130, v130
	v_rcp_f32_e32 v131, v131
	v_pk_mul_f32 v[138:139], v[138:139], v[142:143]
	v_add_f32_e32 v141, 1.0, v141
	v_rcp_f32_e32 v146, v141
	v_mul_f32_e32 v141, 0x3d122279, v133
	v_pk_mul_f32 v[136:137], v[136:137], v[130:131]
	v_mul_f32_e32 v130, 0x3d122279, v135
	v_fmaak_f32 v141, v133, v141, 0x3f4c422a
	v_fmaak_f32 v130, v135, v130, 0x3f4c422a
	v_mul_f32_e32 v141, v133, v141
	v_mul_f32_e32 v130, v135, v130
	v_mul_f32_e32 v141, 0xc038aa3b, v141
	v_mul_f32_e32 v130, 0xc038aa3b, v130
	v_exp_f32_e32 v141, v141
	v_exp_f32_e32 v130, v130
	v_add_f32_e32 v141, 1.0, v141
	v_add_f32_e32 v130, 1.0, v130
	v_rcp_f32_e32 v145, v141
	v_rcp_f32_e32 v147, v130
	v_pk_mul_f32 v[132:133], v[132:133], v[144:145]
	v_pk_mul_f32 v[134:135], v[134:135], v[146:147]
; __device__ __forceinline__ unsigned cvt_pk_bf16(float lo, float hi) { unsigned r; asm volatile("v_cvt_pk_bf16_f32 %0, %1, %2" : "=v"(r) : "v"(lo), "v"(hi)); return r; }
; #define EPI_FENCE() asm volatile("" ::: "memory")
; __device__ __forceinline__ float gelu_tanh(float x) {
;     const float y = x * (0.7978845608028654f + 0.7978845608028654f * 0.044715f * x * x);
;     const float e = __builtin_amdgcn_exp2f(-2.0f * 1.4426950408889634f * y);
;     return x * __builtin_amdgcn_rcpf(1.0f + e);
; }
;     __device__ __forceinline__ void operator()(const f32x4 (&acc)[2][2][4][2], const Unit& u, int wr, int wc, int fr, int fq) const {
;     ...
;         } else {
;             EPI_FENCE();
; #pragma unroll
;             for (int i = 0; i < 8; ++i) {
;                 const int ai = i >> 2, m = i & 3; bf16_t* rowp = Z + (size_t)(row0 + ai * HALF + m * 16) * 5120 + col0;
; #pragma unroll
;                 for (int bj = 0; bj < 2; ++bj) {
;                     f32x4 v0 = acc[ai][bj][m][0] * rs[i], v1 = acc[ai][bj][m][1] * rs[i];
;                     if (kind == 2) {
; #pragma unroll
;                         for (int e = 0; e < 4; ++e) { v0[e] = gelu_tanh(v0[e]); v1[e] = gelu_tanh(v1[e]); }
;                     }
;                     u32x4 w; w.x = cvt_pk_bf16(v0[0], v0[1]); w.y = cvt_pk_bf16(v0[2], v0[3]); w.z = cvt_pk_bf16(v1[0], v1[1]); w.w = cvt_pk_bf16(v1[2], v1[3]);
;                     *(u32x4*)(rowp + bj * HALF) = w;
;                 }
;             }
.LBB0_149:
	v_or_b32_e32 v141, 32, v140
	v_mov_b64_e32 v[130:131], s[8:9]
	v_mad_i64_i32 v[130:131], s[2:3], v141, s59, v[130:131]
	v_mov_b32_e32 v142, v180
	v_mov_b32_e32 v143, v180
	v_lshl_add_u64 v[130:131], v[188:189], 1, v[130:131]
	v_cvt_pk_bf16_f32 v136, v136, v137
	v_cvt_pk_bf16_f32 v137, v132, v133
	v_cvt_pk_bf16_f32 v138, v138, v139
	v_cvt_pk_bf16_f32 v139, v134, v135
	v_mov_b32_e32 v134, v180
	v_mov_b32_e32 v135, v180
	ds_bpermute_b32 v144, v255, v130
	ds_bpermute_b32 v145, v255, v131
	ds_bpermute_b32 v146, v255, v136
	ds_bpermute_b32 v147, v255, v137
	ds_bpermute_b32 v148, v255, v138
	ds_bpermute_b32 v149, v255, v139
	s_waitcnt lgkmcnt(0)
	global_store_dwordx4 v[144:145], v[146:149], off
	v_pk_mul_f32 v[132:133], v[24:25], v[134:135]
	v_pk_mul_f32 v[134:135], v[20:21], v[134:135]
	v_pk_mul_f32 v[136:137], v[22:23], v[142:143]
	s_and_b64 vcc, exec, s[4:5]
	v_pk_mul_f32 v[138:139], v[18:19], v[142:143]
	s_cbranch_vccnz .LBB0_151
	v_mul_f32_e32 v141, 0x3d122279, v136
	v_fmaak_f32 v141, v136, v141, 0x3f4c422a
	v_mul_f32_e32 v141, v136, v141
	v_mul_f32_e32 v141, 0xc038aa3b, v141
	v_exp_f32_e32 v141, v141
	s_nop 0
	v_add_f32_e32 v141, 1.0, v141
	v_rcp_f32_e32 v142, v141
	v_mul_f32_e32 v141, 0x3d122279, v138
	v_fmaak_f32 v141, v138, v141, 0x3f4c422a
	v_mul_f32_e32 v141, v138, v141
	v_mul_f32_e32 v141, 0xc038aa3b, v141
	v_exp_f32_e32 v141, v141
	s_nop 0
	v_add_f32_e32 v141, 1.0, v141
	v_rcp_f32_e32 v144, v141
	v_mul_f32_e32 v141, 0x3d122279, v137
	v_fmaak_f32 v141, v137, v141, 0x3f4c422a
	v_mul_f32_e32 v141, v137, v141
	v_mul_f32_e32 v141, 0xc038aa3b, v141
	v_exp_f32_e32 v141, v141
	s_nop 0
	v_add_f32_e32 v141, 1.0, v141
	v_rcp_f32_e32 v143, v141
	v_mul_f32_e32 v141, 0x3d122279, v139
	v_fmaak_f32 v141, v139, v141, 0x3f4c422a
	v_mul_f32_e32 v141, v139, v141
	v_mul_f32_e32 v141, 0xc038aa3b, v141
	v_exp_f32_e32 v141, v141
	v_pk_mul_f32 v[136:137], v[136:137], v[142:143]
	v_add_f32_e32 v141, 1.0, v141
	v_rcp_f32_e32 v145, v141
	v_mul_f32_e32 v141, 0x3d122279, v132
	v_fmaak_f32 v141, v132, v141, 0x3f4c422a
	v_mul_f32_e32 v141, v132, v141
	v_mul_f32_e32 v141, 0xc038aa3b, v141
	v_exp_f32_e32 v141, v141
	v_pk_mul_f32 v[138:139], v[138:139], v[144:145]
	v_add_f32_e32 v141, 1.0, v141
	v_rcp_f32_e32 v146, v141
	v_mul_f32_e32 v141, 0x3d122279, v134
	v_fmaak_f32 v141, v134, v141, 0x3f4c422a
	v_mul_f32_e32 v141, v134, v141
	v_mul_f32_e32 v141, 0xc038aa3b, v141
	v_exp_f32_e32 v141, v141
	s_nop 0
	v_add_f32_e32 v141, 1.0, v141
	v_rcp_f32_e32 v148, v141
	v_mul_f32_e32 v141, 0x3d122279, v133
	v_fmaak_f32 v141, v133, v141, 0x3f4c422a
	v_mul_f32_e32 v141, v133, v141
	v_mul_f32_e32 v141, 0xc038aa3b, v141
	v_exp_f32_e32 v141, v141
	s_nop 0
	v_add_f32_e32 v141, 1.0, v141
	v_rcp_f32_e32 v147, v141
	v_mul_f32_e32 v141, 0x3d122279, v135
	v_fmaak_f32 v141, v135, v141, 0x3f4c422a
	v_mul_f32_e32 v141, v135, v141
	v_mul_f32_e32 v141, 0xc038aa3b, v141
	v_exp_f32_e32 v141, v141
	v_pk_mul_f32 v[132:133], v[132:133], v[146:147]
	v_add_f32_e32 v141, 1.0, v141
	v_rcp_f32_e32 v149, v141
	s_nop 0
	v_pk_mul_f32 v[134:135], v[134:135], v[148:149]
.LBB0_151:
	v_cvt_pk_bf16_f32 v136, v136, v137
	v_cvt_pk_bf16_f32 v137, v132, v133
	v_cvt_pk_bf16_f32 v138, v138, v139
	s_nop 0
	v_cvt_pk_bf16_f32 v139, v134, v135
	ds_bpermute_b32 v142, v255, v130
	ds_bpermute_b32 v143, v255, v131
	ds_bpermute_b32 v144, v255, v136
	ds_bpermute_b32 v145, v255, v137
	ds_bpermute_b32 v146, v255, v138
	ds_bpermute_b32 v147, v255, v139
	s_waitcnt lgkmcnt(0)
	global_store_dwordx4 v[142:143], v[144:147], off offset:256
	v_mov_b32_e32 v130, v181
	v_pk_mul_f32 v[132:133], v[16:17], v[130:131] op_sel_hi:[1,0]
	v_pk_mul_f32 v[136:137], v[14:15], v[130:131] op_sel_hi:[1,0]
	v_pk_mul_f32 v[134:135], v[12:13], v[130:131] op_sel_hi:[1,0]
	s_and_b64 vcc, exec, s[4:5]
	v_pk_mul_f32 v[138:139], v[10:11], v[130:131] op_sel_hi:[1,0]
	s_cbranch_vccnz .LBB0_153
	v_mul_f32_e32 v141, 0x3d122279, v139
	v_fmaak_f32 v141, v139, v141, 0x3f4c422a
	v_mul_f32_e32 v141, v139, v141
	v_mul_f32_e32 v141, 0xc038aa3b, v141
	v_exp_f32_e32 v141, v141
	v_mul_f32_e32 v131, 0x3d122279, v138
	v_fmaak_f32 v131, v138, v131, 0x3f4c422a
	v_mul_f32_e32 v131, v138, v131
	v_mul_f32_e32 v131, 0xc038aa3b, v131
	v_add_f32_e32 v141, 1.0, v141
	v_exp_f32_e32 v131, v131
	v_rcp_f32_e32 v143, v141
	v_mul_f32_e32 v141, 0x3d122279, v132
	v_fmaak_f32 v141, v132, v141, 0x3f4c422a
	v_mul_f32_e32 v141, v132, v141
	v_mul_f32_e32 v141, 0xc038aa3b, v141
	v_add_f32_e32 v131, 1.0, v131
	v_exp_f32_e32 v141, v141
	v_mul_f32_e32 v130, 0x3d122279, v136
	v_rcp_f32_e32 v142, v131
	v_mul_f32_e32 v131, 0x3d122279, v137
	v_fmaak_f32 v130, v136, v130, 0x3f4c422a
	v_fmaak_f32 v131, v137, v131, 0x3f4c422a
	v_mul_f32_e32 v130, v136, v130
	v_mul_f32_e32 v131, v137, v131
	v_mul_f32_e32 v130, 0xc038aa3b, v130
	v_mul_f32_e32 v131, 0xc038aa3b, v131
	v_add_f32_e32 v141, 1.0, v141
	v_exp_f32_e32 v130, v130
	v_exp_f32_e32 v131, v131
	v_rcp_f32_e32 v144, v141
	v_mul_f32_e32 v141, 0x3d122279, v134
	v_fmaak_f32 v141, v134, v141, 0x3f4c422a
	v_mul_f32_e32 v141, v134, v141
	v_mul_f32_e32 v141, 0xc038aa3b, v141
	v_add_f32_e32 v130, 1.0, v130
	v_add_f32_e32 v131, 1.0, v131
	v_exp_f32_e32 v141, v141
	v_rcp_f32_e32 v130, v130
	v_rcp_f32_e32 v131, v131
	v_pk_mul_f32 v[138:139], v[138:139], v[142:143]
	v_add_f32_e32 v141, 1.0, v141
	v_rcp_f32_e32 v146, v141
	v_mul_f32_e32 v141, 0x3d122279, v133
	v_pk_mul_f32 v[136:137], v[136:137], v[130:131]
	v_mul_f32_e32 v130, 0x3d122279, v135
	v_fmaak_f32 v141, v133, v141, 0x3f4c422a
	v_fmaak_f32 v130, v135, v130, 0x3f4c422a
	v_mul_f32_e32 v141, v133, v141
	v_mul_f32_e32 v130, v135, v130
	v_mul_f32_e32 v141, 0xc038aa3b, v141
	v_mul_f32_e32 v130, 0xc038aa3b, v130
	v_exp_f32_e32 v141, v141
	v_exp_f32_e32 v130, v130
	v_add_f32_e32 v141, 1.0, v141
	v_add_f32_e32 v130, 1.0, v130
	v_rcp_f32_e32 v145, v141
	v_rcp_f32_e32 v147, v130
	v_pk_mul_f32 v[132:133], v[132:133], v[144:145]
	v_pk_mul_f32 v[134:135], v[134:135], v[146:147]
; __device__ __forceinline__ unsigned cvt_pk_bf16(float lo, float hi) { unsigned r; asm volatile("v_cvt_pk_bf16_f32 %0, %1, %2" : "=v"(r) : "v"(lo), "v"(hi)); return r; }
; #define EPI_FENCE() asm volatile("" ::: "memory")
;     __device__ __forceinline__ void operator()(const f32x4 (&acc)[2][2][4][2], const Unit& u, int wr, int wc, int fr, int fq) const {
;     ...
;         float rs[8]; load_rs(rs, rst, u.pm, wr * 64 + fr);
;         if (kind == 0) {
; #pragma unroll
;             for (int ai = 0; ai < 2; ++ai) {
;                 f32x4 cs[4][2];
; #pragma unroll
;                 for (int m = 0; m < 4; ++m) { const int row = row0 + ai * HALF + m * 16; const f32x4* rp = (const f32x4*)(rope + ((size_t)(row & 4095) * 64 + j0) * 2); cs[m][0] = rp[0]; cs[m][1] = rp[1]; }
;     ...
;         } else {
;             EPI_FENCE();
; #pragma unroll
;             for (int i = 0; i < 8; ++i) {
;                 const int ai = i >> 2, m = i & 3; bf16_t* rowp = Z + (size_t)(row0 + ai * HALF + m * 16) * 5120 + col0;
; #pragma unroll
;                 for (int bj = 0; bj < 2; ++bj) {
;                     f32x4 v0 = acc[ai][bj][m][0] * rs[i], v1 = acc[ai][bj][m][1] * rs[i];
;                     if (kind == 2) {
; #pragma unroll
;                         for (int e = 0; e < 4; ++e) { v0[e] = gelu_tanh(v0[e]); v1[e] = gelu_tanh(v1[e]); }
;                     }
;                     u32x4 w; w.x = cvt_pk_bf16(v0[0], v0[1]); w.y = cvt_pk_bf16(v0[2], v0[3]); w.z = cvt_pk_bf16(v1[0], v1[1]); w.w = cvt_pk_bf16(v1[2], v1[3]);
;                     *(u32x4*)(rowp + bj * HALF) = w;
;                 }
;             }
.LBB0_153:
	v_or_b32_e32 v140, 48, v140
	v_mov_b64_e32 v[130:131], s[8:9]
	v_mad_i64_i32 v[130:131], s[2:3], v140, s59, v[130:131]
	v_mov_b32_e32 v142, v181
	v_mov_b32_e32 v143, v181
	v_lshl_add_u64 v[130:131], v[188:189], 1, v[130:131]
	v_cvt_pk_bf16_f32 v136, v136, v137
	v_cvt_pk_bf16_f32 v137, v132, v133
	v_cvt_pk_bf16_f32 v138, v138, v139
	v_cvt_pk_bf16_f32 v139, v134, v135
	v_mov_b32_e32 v134, v181
	v_mov_b32_e32 v135, v181
	ds_bpermute_b32 v144, v255, v130
	ds_bpermute_b32 v145, v255, v131
	ds_bpermute_b32 v146, v255, v136
	ds_bpermute_b32 v147, v255, v137
	ds_bpermute_b32 v148, v255, v138
	ds_bpermute_b32 v149, v255, v139
	s_waitcnt lgkmcnt(0)
	global_store_dwordx4 v[144:145], v[146:149], off
	v_pk_mul_f32 v[132:133], v[8:9], v[134:135]
	v_pk_mul_f32 v[134:135], v[4:5], v[134:135]
	v_pk_mul_f32 v[136:137], v[6:7], v[142:143]
	s_and_b64 vcc, exec, s[4:5]
	v_pk_mul_f32 v[138:139], v[2:3], v[142:143]
	s_cbranch_vccnz .LBB0_155
	v_mul_f32_e32 v141, 0x3d122279, v138
	v_fmaak_f32 v141, v138, v141, 0x3f4c422a
	v_mul_f32_e32 v141, v138, v141
	v_mul_f32_e32 v141, 0xc038aa3b, v141
	v_exp_f32_e32 v141, v141
	v_mul_f32_e32 v140, 0x3d122279, v136
	v_fmaak_f32 v140, v136, v140, 0x3f4c422a
	v_mul_f32_e32 v140, v136, v140
	v_add_f32_e32 v141, 1.0, v141
	v_rcp_f32_e32 v142, v141
	v_mul_f32_e32 v141, 0x3d122279, v137
	v_fmaak_f32 v141, v137, v141, 0x3f4c422a
	v_mul_f32_e32 v141, v137, v141
	v_mul_f32_e32 v140, 0xc038aa3b, v140
	v_mul_f32_e32 v141, 0xc038aa3b, v141
	v_exp_f32_e32 v140, v140
	v_exp_f32_e32 v141, v141
	v_mul_f32_e32 v145, 0x3d122279, v134
	v_fmaak_f32 v145, v134, v145, 0x3f4c422a
	v_mul_f32_e32 v145, v134, v145
	v_mul_f32_e32 v145, 0xc038aa3b, v145
	v_add_f32_e32 v140, 1.0, v140
	v_add_f32_e32 v141, 1.0, v141
	v_exp_f32_e32 v145, v145
	v_rcp_f32_e32 v140, v140
	v_rcp_f32_e32 v141, v141
	v_mul_f32_e32 v143, 0x3d122279, v139
	v_add_f32_e32 v145, 1.0, v145
	v_mul_f32_e32 v144, 0x3d122279, v132
	v_rcp_f32_e32 v146, v145
	v_mul_f32_e32 v145, 0x3d122279, v133
	v_pk_mul_f32 v[136:137], v[136:137], v[140:141]
	v_mul_f32_e32 v140, 0x3d122279, v135
	v_fmaak_f32 v143, v139, v143, 0x3f4c422a
	v_fmaak_f32 v144, v132, v144, 0x3f4c422a
	v_fmaak_f32 v145, v133, v145, 0x3f4c422a
	v_fmaak_f32 v140, v135, v140, 0x3f4c422a
	v_mul_f32_e32 v143, v139, v143
	v_mul_f32_e32 v144, v132, v144
	v_mul_f32_e32 v145, v133, v145
	v_mul_f32_e32 v140, v135, v140
	v_mul_f32_e32 v143, 0xc038aa3b, v143
	v_mul_f32_e32 v144, 0xc038aa3b, v144
	v_mul_f32_e32 v145, 0xc038aa3b, v145
	v_mul_f32_e32 v140, 0xc038aa3b, v140
	v_exp_f32_e32 v143, v143
	v_exp_f32_e32 v144, v144
	v_exp_f32_e32 v145, v145
	v_exp_f32_e32 v140, v140
	v_add_f32_e32 v143, 1.0, v143
	v_add_f32_e32 v144, 1.0, v144
	v_add_f32_e32 v145, 1.0, v145
	v_add_f32_e32 v140, 1.0, v140
	v_rcp_f32_e32 v143, v143
	v_rcp_f32_e32 v144, v144
	v_rcp_f32_e32 v145, v145
	v_rcp_f32_e32 v147, v140
	v_pk_mul_f32 v[138:139], v[138:139], v[142:143]
	v_pk_mul_f32 v[132:133], v[132:133], v[144:145]
	v_pk_mul_f32 v[134:135], v[134:135], v[146:147]
.LBB0_155:
	s_mov_b64 s[4:5], 0
	v_cvt_pk_bf16_f32 v136, v136, v137
	v_cvt_pk_bf16_f32 v137, v132, v133
	v_cvt_pk_bf16_f32 v138, v138, v139
	v_cvt_pk_bf16_f32 v139, v134, v135
	ds_bpermute_b32 v140, v255, v130
	ds_bpermute_b32 v141, v255, v131
	ds_bpermute_b32 v142, v255, v136
	ds_bpermute_b32 v143, v255, v137
	ds_bpermute_b32 v144, v255, v138
	ds_bpermute_b32 v145, v255, v139
	s_waitcnt lgkmcnt(0)
	global_store_dwordx4 v[140:141], v[142:145], off offset:256
.LBB0_156:
	s_and_b64 vcc, exec, s[4:5]
	v_readlane_b32 s50, v252, 33
	v_readlane_b32 s51, v252, 34
	s_cbranch_vccz .LBB0_158
	v_lshlrev_b32_e32 v208, 6, v206
	v_and_b32_e32 v130, 0x3f3c0, v208
	v_mov_b32_e32 v131, v0
	v_lshl_add_u64 v[132:133], v[130:131], 0, v[174:175]
	v_lshl_add_u64 v[132:133], v[132:133], 3, s[10:11]
	global_load_dwordx4 v[210:213], v[132:133], off offset:16
	global_load_dwordx4 v[214:217], v[132:133], off
	v_or_b32_e32 v132, 0x400, v130
	v_mov_b32_e32 v133, v0
	v_lshl_add_u64 v[132:133], v[132:133], 0, v[174:175]
	v_lshl_add_u64 v[132:133], v[132:133], 3, s[10:11]
	global_load_dwordx4 v[146:149], v[132:133], off offset:16
	global_load_dwordx4 v[150:153], v[132:133], off
	v_or_b32_e32 v132, 0x800, v130
	v_mov_b32_e32 v133, v0
	v_lshl_add_u64 v[132:133], v[132:133], 0, v[174:175]
	v_lshl_add_u64 v[132:133], v[132:133], 3, s[10:11]
	global_load_dwordx4 v[138:141], v[132:133], off offset:16
	global_load_dwordx4 v[142:145], v[132:133], off
	v_or_b32_e32 v130, 0xc00, v130
	v_lshl_add_u64 v[130:131], v[130:131], 0, v[174:175]
	v_lshl_add_u64 v[134:135], v[130:131], 3, s[10:11]
	global_load_dwordx4 v[130:133], v[134:135], off offset:16
	s_nop 0
	global_load_dwordx4 v[134:137], v[134:135], off
	s_cmp_gt_i32 s41, 7
	s_cselect_b64 vcc, -1, 0
	v_cndmask_b32_e32 v207, 1.0, v199, vcc
	s_waitcnt lgkmcnt(0)
	v_mul_f32_e32 v186, v207, v186
	v_mov_b64_e32 v[190:191], s[8:9]
	v_mad_i64_i32 v[218:219], s[2:3], v206, s59, v[190:191]
	v_lshlrev_b64 v[188:189], 1, v[188:189]
	v_lshl_add_u64 v[218:219], v[218:219], 0, v[188:189]
	s_waitcnt vmcnt(0)
; __device__ __forceinline__ unsigned cvt_pk_bf16(float lo, float hi) { unsigned r; asm volatile("v_cvt_pk_bf16_f32 %0, %1, %2" : "=v"(r) : "v"(lo), "v"(hi)); return r; }
; #define EPI_FENCE() asm volatile("" ::: "memory")
;     __device__ __forceinline__ void operator()(const f32x4 (&acc)[2][2][4][2], const Unit& u, int wr, int wc, int fr, int fq) const {
;     ...
;                 for (int m = 0; m < 4; ++m) { const int row = row0 + ai * HALF + m * 16; const f32x4* rp = (const f32x4*)(rope + ((size_t)(row & 4095) * 64 + j0) * 2); cs[m][0] = rp[0]; cs[m][1] = rp[1]; }
;                 EPI_FENCE();
; #pragma unroll
;                 for (int m = 0; m < 4; ++m) {
;                     bf16_t* rowp = Z + (size_t)(row0 + ai * HALF + m * 16) * 5120 + col0;
;                     const float sc = rs[4 * ai + m] * qs; const f32x4 c0 = cs[m][0] * sc, c1 = cs[m][1] * sc;
; #pragma unroll
;                     for (int bj = 0; bj < 2; ++bj) {
;                         const f32x4 v0 = acc[ai][bj][m][0], v1 = acc[ai][bj][m][1];
;                         u32x4 w;
;                         w.x = cvt_pk_bf16(v0[0] * c0[0] - v0[1] * c0[1], v0[1] * c0[0] + v0[0] * c0[1]);
;                         w.y = cvt_pk_bf16(v0[2] * c0[2] - v0[3] * c0[3], v0[3] * c0[2] + v0[2] * c0[3]);
;                         w.z = cvt_pk_bf16(v1[0] * c1[0] - v1[1] * c1[1], v1[1] * c1[0] + v1[0] * c1[1]);
;                         w.w = cvt_pk_bf16(v1[2] * c1[2] - v1[3] * c1[3], v1[3] * c1[2] + v1[2] * c1[3]);
;                         *(u32x4*)(rowp + bj * HALF) = w;
;                     }
;                 }
	v_pk_mul_f32 v[210:211], v[186:187], v[210:211] op_sel_hi:[0,1]
	v_pk_mul_f32 v[214:215], v[186:187], v[214:215] op_sel_hi:[0,1]
	v_pk_mul_f32 v[216:217], v[186:187], v[216:217] op_sel_hi:[0,1]
	v_pk_mul_f32 v[220:221], v[128:129], v[216:217]
	v_pk_mul_f32 v[222:223], v[126:127], v[214:215]
	v_pk_mul_f32 v[126:127], v[126:127], v[214:215] op_sel:[1,0] op_sel_hi:[0,1]
	v_pk_mul_f32 v[128:129], v[128:129], v[216:217] op_sel:[1,0] op_sel_hi:[0,1]
	v_add_f32_e32 v126, v126, v127
	v_sub_f32_e32 v127, v220, v221
	v_add_f32_e32 v128, v128, v129
	v_pk_mul_f32 v[212:213], v[186:187], v[212:213] op_sel_hi:[0,1]
	v_sub_f32_e32 v186, v222, v223
	v_cvt_pk_bf16_f32 v126, v186, v126
	v_cvt_pk_bf16_f32 v127, v127, v128
	v_pk_mul_f32 v[128:129], v[122:123], v[210:211]
	v_pk_mul_f32 v[122:123], v[122:123], v[210:211] op_sel:[1,0] op_sel_hi:[0,1]
	v_sub_f32_e32 v128, v128, v129
	v_add_f32_e32 v122, v122, v123
	v_pk_mul_f32 v[220:221], v[124:125], v[212:213]
	v_cvt_pk_bf16_f32 v128, v128, v122
	v_pk_mul_f32 v[122:123], v[124:125], v[212:213] op_sel:[1,0] op_sel_hi:[0,1]
	v_sub_f32_e32 v129, v220, v221
	v_add_f32_e32 v122, v122, v123
	v_cvt_pk_bf16_f32 v129, v129, v122
	v_pk_mul_f32 v[122:123], v[120:121], v[216:217]
	v_pk_mul_f32 v[124:125], v[118:119], v[214:215]
	v_pk_mul_f32 v[118:119], v[118:119], v[214:215] op_sel:[1,0] op_sel_hi:[0,1]
	v_pk_mul_f32 v[120:121], v[120:121], v[216:217] op_sel:[1,0] op_sel_hi:[0,1]
	v_add_f32_e32 v118, v118, v119
	v_sub_f32_e32 v119, v122, v123
	v_add_f32_e32 v120, v120, v121
	ds_bpermute_b32 v220, v255, v218
	ds_bpermute_b32 v221, v255, v219
	ds_bpermute_b32 v222, v255, v126
	ds_bpermute_b32 v223, v255, v127
	ds_bpermute_b32 v224, v255, v128
	ds_bpermute_b32 v225, v255, v129
	s_waitcnt lgkmcnt(0)
	global_store_dwordx4 v[220:221], v[222:225], off
	v_sub_f32_e32 v124, v124, v125
	v_cvt_pk_bf16_f32 v118, v124, v118
	v_cvt_pk_bf16_f32 v119, v119, v120
	v_pk_mul_f32 v[120:121], v[114:115], v[210:211]
	v_pk_mul_f32 v[114:115], v[114:115], v[210:211] op_sel:[1,0] op_sel_hi:[0,1]
	v_pk_mul_f32 v[122:123], v[116:117], v[212:213]
	v_sub_f32_e32 v120, v120, v121
	v_add_f32_e32 v114, v114, v115
	v_cvt_pk_bf16_f32 v120, v120, v114
	v_sub_f32_e32 v121, v122, v123
	v_pk_mul_f32 v[114:115], v[116:117], v[212:213] op_sel:[1,0] op_sel_hi:[0,1]
	v_add_f32_e32 v114, v114, v115
	v_cvt_pk_bf16_f32 v121, v121, v114
	v_mul_f32_e32 v116, v207, v187
	ds_bpermute_b32 v122, v255, v218
	ds_bpermute_b32 v123, v255, v219
	ds_bpermute_b32 v124, v255, v118
	ds_bpermute_b32 v125, v255, v119
	ds_bpermute_b32 v126, v255, v120
	ds_bpermute_b32 v127, v255, v121
	s_waitcnt lgkmcnt(0)
	global_store_dwordx4 v[122:123], v[124:127], off offset:256
	v_pk_mul_f32 v[122:123], v[116:117], v[146:147] op_sel_hi:[0,1]
	v_or_b32_e32 v114, 16, v206
	v_pk_mul_f32 v[118:119], v[116:117], v[150:151] op_sel_hi:[0,1]
	v_pk_mul_f32 v[120:121], v[116:117], v[152:153] op_sel_hi:[0,1]
	v_pk_mul_f32 v[124:125], v[112:113], v[120:121]
	v_pk_mul_f32 v[126:127], v[110:111], v[118:119]
	v_pk_mul_f32 v[110:111], v[110:111], v[118:119] op_sel:[1,0] op_sel_hi:[0,1]
	v_pk_mul_f32 v[112:113], v[112:113], v[120:121] op_sel:[1,0] op_sel_hi:[0,1]
	v_add_f32_e32 v110, v110, v111
	v_sub_f32_e32 v111, v124, v125
	v_add_f32_e32 v112, v112, v113
	v_sub_f32_e32 v126, v126, v127
	v_cvt_pk_bf16_f32 v110, v126, v110
	v_cvt_pk_bf16_f32 v111, v111, v112
	v_pk_mul_f32 v[112:113], v[106:107], v[122:123]
	v_pk_mul_f32 v[106:107], v[106:107], v[122:123] op_sel:[1,0] op_sel_hi:[0,1]
	v_pk_mul_f32 v[116:117], v[116:117], v[148:149] op_sel_hi:[0,1]
	v_sub_f32_e32 v112, v112, v113
	v_add_f32_e32 v106, v106, v107
	v_pk_mul_f32 v[124:125], v[108:109], v[116:117]
	v_cvt_pk_bf16_f32 v112, v112, v106
	v_pk_mul_f32 v[106:107], v[108:109], v[116:117] op_sel:[1,0] op_sel_hi:[0,1]
	v_sub_f32_e32 v113, v124, v125
	v_add_f32_e32 v106, v106, v107
	v_mad_i64_i32 v[114:115], s[2:3], v114, s59, v[190:191]
	v_cvt_pk_bf16_f32 v113, v113, v106
	v_pk_mul_f32 v[106:107], v[104:105], v[120:121]
	v_pk_mul_f32 v[108:109], v[102:103], v[118:119]
	v_pk_mul_f32 v[102:103], v[102:103], v[118:119] op_sel:[1,0] op_sel_hi:[0,1]
	v_pk_mul_f32 v[104:105], v[104:105], v[120:121] op_sel:[1,0] op_sel_hi:[0,1]
	v_lshl_add_u64 v[114:115], v[114:115], 0, v[188:189]
	v_add_f32_e32 v102, v102, v103
	v_sub_f32_e32 v103, v106, v107
	v_add_f32_e32 v104, v104, v105
	ds_bpermute_b32 v124, v255, v114
	ds_bpermute_b32 v125, v255, v115
	ds_bpermute_b32 v126, v255, v110
	ds_bpermute_b32 v127, v255, v111
	ds_bpermute_b32 v128, v255, v112
	ds_bpermute_b32 v129, v255, v113
	s_waitcnt lgkmcnt(0)
	global_store_dwordx4 v[124:125], v[126:129], off
	v_sub_f32_e32 v108, v108, v109
	v_cvt_pk_bf16_f32 v102, v108, v102
	v_cvt_pk_bf16_f32 v103, v103, v104
	v_pk_mul_f32 v[104:105], v[98:99], v[122:123]
	v_pk_mul_f32 v[98:99], v[98:99], v[122:123] op_sel:[1,0] op_sel_hi:[0,1]
	v_pk_mul_f32 v[106:107], v[100:101], v[116:117]
	v_sub_f32_e32 v104, v104, v105
	v_add_f32_e32 v98, v98, v99
	v_cvt_pk_bf16_f32 v104, v104, v98
	v_sub_f32_e32 v105, v106, v107
	v_pk_mul_f32 v[98:99], v[100:101], v[116:117] op_sel:[1,0] op_sel_hi:[0,1]
	v_add_f32_e32 v98, v98, v99
	v_cvt_pk_bf16_f32 v105, v105, v98
	v_mul_f32_e32 v100, v207, v184
	ds_bpermute_b32 v106, v255, v114
	ds_bpermute_b32 v107, v255, v115
	ds_bpermute_b32 v108, v255, v102
	ds_bpermute_b32 v109, v255, v103
	ds_bpermute_b32 v110, v255, v104
	ds_bpermute_b32 v111, v255, v105
	s_waitcnt lgkmcnt(0)
; __device__ __forceinline__ unsigned cvt_pk_bf16(float lo, float hi) { unsigned r; asm volatile("v_cvt_pk_bf16_f32 %0, %1, %2" : "=v"(r) : "v"(lo), "v"(hi)); return r; }
; #define EPI_FENCE() asm volatile("" ::: "memory")
;     __device__ __forceinline__ void operator()(const f32x4 (&acc)[2][2][4][2], const Unit& u, int wr, int wc, int fr, int fq) const {
;     ...
;                 for (int m = 0; m < 4; ++m) { const int row = row0 + ai * HALF + m * 16; const f32x4* rp = (const f32x4*)(rope + ((size_t)(row & 4095) * 64 + j0) * 2); cs[m][0] = rp[0]; cs[m][1] = rp[1]; }
;                 EPI_FENCE();
; #pragma unroll
;                 for (int m = 0; m < 4; ++m) {
;                     bf16_t* rowp = Z + (size_t)(row0 + ai * HALF + m * 16) * 5120 + col0;
;                     const float sc = rs[4 * ai + m] * qs; const f32x4 c0 = cs[m][0] * sc, c1 = cs[m][1] * sc;
; #pragma unroll
;                     for (int bj = 0; bj < 2; ++bj) {
;                         const f32x4 v0 = acc[ai][bj][m][0], v1 = acc[ai][bj][m][1];
;                         u32x4 w;
;                         w.x = cvt_pk_bf16(v0[0] * c0[0] - v0[1] * c0[1], v0[1] * c0[0] + v0[0] * c0[1]);
;                         w.y = cvt_pk_bf16(v0[2] * c0[2] - v0[3] * c0[3], v0[3] * c0[2] + v0[2] * c0[3]);
;                         w.z = cvt_pk_bf16(v1[0] * c1[0] - v1[1] * c1[1], v1[1] * c1[0] + v1[0] * c1[1]);
;                         w.w = cvt_pk_bf16(v1[2] * c1[2] - v1[3] * c1[3], v1[3] * c1[2] + v1[2] * c1[3]);
;                         *(u32x4*)(rowp + bj * HALF) = w;
;                     }
;                 }
	global_store_dwordx4 v[106:107], v[108:111], off offset:256
	v_pk_mul_f32 v[106:107], v[100:101], v[138:139] op_sel_hi:[0,1]
	v_or_b32_e32 v98, 32, v206
	v_pk_mul_f32 v[102:103], v[100:101], v[142:143] op_sel_hi:[0,1]
	v_pk_mul_f32 v[104:105], v[100:101], v[144:145] op_sel_hi:[0,1]
	v_pk_mul_f32 v[108:109], v[96:97], v[104:105]
	v_pk_mul_f32 v[110:111], v[94:95], v[102:103]
	v_pk_mul_f32 v[94:95], v[94:95], v[102:103] op_sel:[1,0] op_sel_hi:[0,1]
	v_pk_mul_f32 v[96:97], v[96:97], v[104:105] op_sel:[1,0] op_sel_hi:[0,1]
	v_add_f32_e32 v94, v94, v95
	v_sub_f32_e32 v95, v108, v109
	v_add_f32_e32 v96, v96, v97
	v_sub_f32_e32 v110, v110, v111
	v_cvt_pk_bf16_f32 v94, v110, v94
	v_cvt_pk_bf16_f32 v95, v95, v96
	v_pk_mul_f32 v[96:97], v[90:91], v[106:107]
	v_pk_mul_f32 v[90:91], v[90:91], v[106:107] op_sel:[1,0] op_sel_hi:[0,1]
	v_pk_mul_f32 v[100:101], v[100:101], v[140:141] op_sel_hi:[0,1]
	v_sub_f32_e32 v96, v96, v97
	v_add_f32_e32 v90, v90, v91
	v_pk_mul_f32 v[108:109], v[92:93], v[100:101]
	v_cvt_pk_bf16_f32 v96, v96, v90
	v_pk_mul_f32 v[90:91], v[92:93], v[100:101] op_sel:[1,0] op_sel_hi:[0,1]
	v_sub_f32_e32 v97, v108, v109
	v_add_f32_e32 v90, v90, v91
	v_mad_i64_i32 v[98:99], s[2:3], v98, s59, v[190:191]
	v_cvt_pk_bf16_f32 v97, v97, v90
	v_pk_mul_f32 v[90:91], v[88:89], v[104:105]
	v_pk_mul_f32 v[92:93], v[86:87], v[102:103]
	v_pk_mul_f32 v[86:87], v[86:87], v[102:103] op_sel:[1,0] op_sel_hi:[0,1]
	v_pk_mul_f32 v[88:89], v[88:89], v[104:105] op_sel:[1,0] op_sel_hi:[0,1]
	v_lshl_add_u64 v[98:99], v[98:99], 0, v[188:189]
	v_add_f32_e32 v86, v86, v87
	v_sub_f32_e32 v87, v90, v91
	v_add_f32_e32 v88, v88, v89
	ds_bpermute_b32 v108, v255, v98
	ds_bpermute_b32 v109, v255, v99
	ds_bpermute_b32 v110, v255, v94
	ds_bpermute_b32 v111, v255, v95
	ds_bpermute_b32 v112, v255, v96
	ds_bpermute_b32 v113, v255, v97
	s_waitcnt lgkmcnt(0)
	global_store_dwordx4 v[108:109], v[110:113], off
	v_sub_f32_e32 v92, v92, v93
	v_cvt_pk_bf16_f32 v86, v92, v86
	v_cvt_pk_bf16_f32 v87, v87, v88
	v_pk_mul_f32 v[88:89], v[82:83], v[106:107]
	v_pk_mul_f32 v[82:83], v[82:83], v[106:107] op_sel:[1,0] op_sel_hi:[0,1]
	v_pk_mul_f32 v[90:91], v[84:85], v[100:101]
	v_sub_f32_e32 v88, v88, v89
	v_add_f32_e32 v82, v82, v83
	v_cvt_pk_bf16_f32 v88, v88, v82
	v_sub_f32_e32 v89, v90, v91
	v_pk_mul_f32 v[82:83], v[84:85], v[100:101] op_sel:[1,0] op_sel_hi:[0,1]
	v_add_f32_e32 v82, v82, v83
	v_cvt_pk_bf16_f32 v89, v89, v82
	v_mul_f32_e32 v84, v207, v185
	ds_bpermute_b32 v90, v255, v98
	ds_bpermute_b32 v91, v255, v99
	ds_bpermute_b32 v92, v255, v86
	ds_bpermute_b32 v93, v255, v87
	ds_bpermute_b32 v94, v255, v88
	ds_bpermute_b32 v95, v255, v89
	s_waitcnt lgkmcnt(0)
	global_store_dwordx4 v[90:91], v[92:95], off offset:256
	v_pk_mul_f32 v[90:91], v[84:85], v[130:131] op_sel_hi:[0,1]
	v_or_b32_e32 v82, 48, v206
	v_pk_mul_f32 v[86:87], v[84:85], v[134:135] op_sel_hi:[0,1]
	v_pk_mul_f32 v[88:89], v[84:85], v[136:137] op_sel_hi:[0,1]
	v_pk_mul_f32 v[92:93], v[80:81], v[88:89]
	v_pk_mul_f32 v[94:95], v[78:79], v[86:87]
	v_pk_mul_f32 v[78:79], v[78:79], v[86:87] op_sel:[1,0] op_sel_hi:[0,1]
	v_pk_mul_f32 v[80:81], v[80:81], v[88:89] op_sel:[1,0] op_sel_hi:[0,1]
	v_add_f32_e32 v78, v78, v79
	v_sub_f32_e32 v79, v92, v93
	v_add_f32_e32 v80, v80, v81
	v_sub_f32_e32 v94, v94, v95
	v_cvt_pk_bf16_f32 v78, v94, v78
	v_cvt_pk_bf16_f32 v79, v79, v80
	v_pk_mul_f32 v[80:81], v[74:75], v[90:91]
	v_pk_mul_f32 v[74:75], v[74:75], v[90:91] op_sel:[1,0] op_sel_hi:[0,1]
	v_pk_mul_f32 v[84:85], v[84:85], v[132:133] op_sel_hi:[0,1]
	v_sub_f32_e32 v80, v80, v81
	v_add_f32_e32 v74, v74, v75
	v_pk_mul_f32 v[92:93], v[76:77], v[84:85]
	v_cvt_pk_bf16_f32 v80, v80, v74
	v_pk_mul_f32 v[74:75], v[76:77], v[84:85] op_sel:[1,0] op_sel_hi:[0,1]
	v_sub_f32_e32 v81, v92, v93
	v_add_f32_e32 v74, v74, v75
	v_mad_i64_i32 v[82:83], s[2:3], v82, s59, v[190:191]
	v_cvt_pk_bf16_f32 v81, v81, v74
	v_pk_mul_f32 v[74:75], v[72:73], v[88:89]
	v_pk_mul_f32 v[76:77], v[70:71], v[86:87]
	v_pk_mul_f32 v[70:71], v[70:71], v[86:87] op_sel:[1,0] op_sel_hi:[0,1]
	v_pk_mul_f32 v[72:73], v[72:73], v[88:89] op_sel:[1,0] op_sel_hi:[0,1]
	v_lshl_add_u64 v[82:83], v[82:83], 0, v[188:189]
	v_add_f32_e32 v70, v70, v71
	v_sub_f32_e32 v71, v74, v75
	v_add_f32_e32 v72, v72, v73
	ds_bpermute_b32 v92, v255, v82
	ds_bpermute_b32 v93, v255, v83
	ds_bpermute_b32 v94, v255, v78
	ds_bpermute_b32 v95, v255, v79
	ds_bpermute_b32 v96, v255, v80
	ds_bpermute_b32 v97, v255, v81
	s_waitcnt lgkmcnt(0)
	global_store_dwordx4 v[92:93], v[94:97], off
	v_sub_f32_e32 v76, v76, v77
	v_cvt_pk_bf16_f32 v70, v76, v70
	v_cvt_pk_bf16_f32 v71, v71, v72
	v_pk_mul_f32 v[72:73], v[66:67], v[90:91]
	v_pk_mul_f32 v[66:67], v[66:67], v[90:91] op_sel:[1,0] op_sel_hi:[0,1]
	v_sub_f32_e32 v72, v72, v73
	v_add_f32_e32 v66, v66, v67
	v_pk_mul_f32 v[74:75], v[68:69], v[84:85]
	v_cvt_pk_bf16_f32 v72, v72, v66
	v_pk_mul_f32 v[66:67], v[68:69], v[84:85] op_sel:[1,0] op_sel_hi:[0,1]
	v_sub_f32_e32 v73, v74, v75
	v_add_f32_e32 v66, v66, v67
	v_cvt_pk_bf16_f32 v73, v73, v66
	v_add_u32_e32 v66, 0x2000, v208
	v_and_b32_e32 v66, 0x3f3c0, v66
	v_mov_b32_e32 v67, v0
	ds_bpermute_b32 v74, v255, v82
	ds_bpermute_b32 v75, v255, v83
	ds_bpermute_b32 v76, v255, v70
	ds_bpermute_b32 v77, v255, v71
	ds_bpermute_b32 v78, v255, v72
	ds_bpermute_b32 v79, v255, v73
	s_waitcnt lgkmcnt(0)
; __device__ __forceinline__ unsigned cvt_pk_bf16(float lo, float hi) { unsigned r; asm volatile("v_cvt_pk_bf16_f32 %0, %1, %2" : "=v"(r) : "v"(lo), "v"(hi)); return r; }
; #define EPI_FENCE() asm volatile("" ::: "memory")
;     __device__ __forceinline__ void operator()(const f32x4 (&acc)[2][2][4][2], const Unit& u, int wr, int wc, int fr, int fq) const {
;     ...
;                 for (int m = 0; m < 4; ++m) { const int row = row0 + ai * HALF + m * 16; const f32x4* rp = (const f32x4*)(rope + ((size_t)(row & 4095) * 64 + j0) * 2); cs[m][0] = rp[0]; cs[m][1] = rp[1]; }
;                 EPI_FENCE();
; #pragma unroll
;                 for (int m = 0; m < 4; ++m) {
;                     bf16_t* rowp = Z + (size_t)(row0 + ai * HALF + m * 16) * 5120 + col0;
;                     const float sc = rs[4 * ai + m] * qs; const f32x4 c0 = cs[m][0] * sc, c1 = cs[m][1] * sc;
; #pragma unroll
;                     for (int bj = 0; bj < 2; ++bj) {
;                         const f32x4 v0 = acc[ai][bj][m][0], v1 = acc[ai][bj][m][1];
;                         u32x4 w;
;                         w.x = cvt_pk_bf16(v0[0] * c0[0] - v0[1] * c0[1], v0[1] * c0[0] + v0[0] * c0[1]);
;                         w.y = cvt_pk_bf16(v0[2] * c0[2] - v0[3] * c0[3], v0[3] * c0[2] + v0[2] * c0[3]);
;                         w.z = cvt_pk_bf16(v1[0] * c1[0] - v1[1] * c1[1], v1[1] * c1[0] + v1[0] * c1[1]);
;                         w.w = cvt_pk_bf16(v1[2] * c1[2] - v1[3] * c1[3], v1[3] * c1[2] + v1[2] * c1[3]);
;                         *(u32x4*)(rowp + bj * HALF) = w;
;                     }
;                 }
	global_store_dwordx4 v[74:75], v[76:79], off offset:256
	v_lshl_add_u64 v[68:69], v[66:67], 0, v[174:175]
	v_lshl_add_u64 v[68:69], v[68:69], 3, s[10:11]
	global_load_dwordx4 v[70:73], v[68:69], off offset:16
	global_load_dwordx4 v[74:77], v[68:69], off
	v_or_b32_e32 v68, 0x400, v66
	v_mov_b32_e32 v69, v0
	v_lshl_add_u64 v[68:69], v[68:69], 0, v[174:175]
	v_lshl_add_u64 v[68:69], v[68:69], 3, s[10:11]
	global_load_dwordx4 v[78:81], v[68:69], off offset:16
	global_load_dwordx4 v[82:85], v[68:69], off
	v_or_b32_e32 v68, 0x800, v66
	v_mov_b32_e32 v69, v0
	v_lshl_add_u64 v[68:69], v[68:69], 0, v[174:175]
	v_lshl_add_u64 v[68:69], v[68:69], 3, s[10:11]
	global_load_dwordx4 v[86:89], v[68:69], off offset:16
	global_load_dwordx4 v[90:93], v[68:69], off
	v_or_b32_e32 v66, 0xc00, v66
	v_lshl_add_u64 v[66:67], v[66:67], 0, v[174:175]
	v_lshl_add_u64 v[94:95], v[66:67], 3, s[10:11]
	global_load_dwordx4 v[66:69], v[94:95], off offset:16
	s_nop 0
	global_load_dwordx4 v[94:97], v[94:95], off
	v_mul_f32_e32 v100, v207, v182
	v_add_u32_e32 v98, 0x80, v206
	v_mad_i64_i32 v[98:99], s[2:3], v98, s59, v[190:191]
	v_lshl_add_u64 v[98:99], v[98:99], 0, v[188:189]
	s_waitcnt vmcnt(7)
	v_pk_mul_f32 v[70:71], v[100:101], v[70:71] op_sel_hi:[0,1]
	s_waitcnt vmcnt(6)
	v_pk_mul_f32 v[74:75], v[100:101], v[74:75] op_sel_hi:[0,1]
	v_pk_mul_f32 v[76:77], v[100:101], v[76:77] op_sel_hi:[0,1]
	v_pk_mul_f32 v[72:73], v[100:101], v[72:73] op_sel_hi:[0,1]
	v_pk_mul_f32 v[100:101], v[64:65], v[76:77]
	v_pk_mul_f32 v[102:103], v[62:63], v[74:75]
	v_pk_mul_f32 v[62:63], v[62:63], v[74:75] op_sel:[1,0] op_sel_hi:[0,1]
	v_pk_mul_f32 v[64:65], v[64:65], v[76:77] op_sel:[1,0] op_sel_hi:[0,1]
	v_add_f32_e32 v62, v62, v63
	v_sub_f32_e32 v63, v100, v101
	v_add_f32_e32 v64, v64, v65
	v_sub_f32_e32 v102, v102, v103
	v_cvt_pk_bf16_f32 v62, v102, v62
	v_cvt_pk_bf16_f32 v63, v63, v64
	v_pk_mul_f32 v[64:65], v[58:59], v[70:71]
	v_pk_mul_f32 v[58:59], v[58:59], v[70:71] op_sel:[1,0] op_sel_hi:[0,1]
	v_sub_f32_e32 v64, v64, v65
	v_add_f32_e32 v58, v58, v59
	v_pk_mul_f32 v[100:101], v[60:61], v[72:73]
	v_cvt_pk_bf16_f32 v64, v64, v58
	v_pk_mul_f32 v[58:59], v[60:61], v[72:73] op_sel:[1,0] op_sel_hi:[0,1]
	v_sub_f32_e32 v65, v100, v101
	v_add_f32_e32 v58, v58, v59
	v_cvt_pk_bf16_f32 v65, v65, v58
	v_pk_mul_f32 v[58:59], v[56:57], v[76:77]
	v_pk_mul_f32 v[60:61], v[54:55], v[74:75]
	v_pk_mul_f32 v[54:55], v[54:55], v[74:75] op_sel:[1,0] op_sel_hi:[0,1]
	v_pk_mul_f32 v[56:57], v[56:57], v[76:77] op_sel:[1,0] op_sel_hi:[0,1]
	v_add_f32_e32 v54, v54, v55
	v_sub_f32_e32 v55, v58, v59
	v_add_f32_e32 v56, v56, v57
	ds_bpermute_b32 v100, v255, v98
	ds_bpermute_b32 v101, v255, v99
	ds_bpermute_b32 v102, v255, v62
	ds_bpermute_b32 v103, v255, v63
	ds_bpermute_b32 v104, v255, v64
	ds_bpermute_b32 v105, v255, v65
	s_waitcnt lgkmcnt(0)
	global_store_dwordx4 v[100:101], v[102:105], off
	v_sub_f32_e32 v60, v60, v61
	v_cvt_pk_bf16_f32 v54, v60, v54
	v_cvt_pk_bf16_f32 v55, v55, v56
	v_pk_mul_f32 v[56:57], v[50:51], v[70:71]
	v_pk_mul_f32 v[50:51], v[50:51], v[70:71] op_sel:[1,0] op_sel_hi:[0,1]
	v_pk_mul_f32 v[58:59], v[52:53], v[72:73]
	v_sub_f32_e32 v56, v56, v57
	v_add_f32_e32 v50, v50, v51
	v_cvt_pk_bf16_f32 v56, v56, v50
	v_sub_f32_e32 v57, v58, v59
	v_pk_mul_f32 v[50:51], v[52:53], v[72:73] op_sel:[1,0] op_sel_hi:[0,1]
	v_add_f32_e32 v50, v50, v51
	v_cvt_pk_bf16_f32 v57, v57, v50
	v_mul_f32_e32 v52, v207, v183
	ds_bpermute_b32 v58, v255, v98
	ds_bpermute_b32 v59, v255, v99
	ds_bpermute_b32 v60, v255, v54
	ds_bpermute_b32 v61, v255, v55
	ds_bpermute_b32 v62, v255, v56
	ds_bpermute_b32 v63, v255, v57
	s_waitcnt lgkmcnt(0)
	global_store_dwordx4 v[58:59], v[60:63], off offset:256
	s_waitcnt vmcnt(7)
	v_pk_mul_f32 v[58:59], v[52:53], v[78:79] op_sel_hi:[0,1]
	v_add_u32_e32 v50, 0x90, v206
	s_waitcnt vmcnt(6)
	v_pk_mul_f32 v[54:55], v[52:53], v[82:83] op_sel_hi:[0,1]
	v_pk_mul_f32 v[56:57], v[52:53], v[84:85] op_sel_hi:[0,1]
	v_pk_mul_f32 v[60:61], v[48:49], v[56:57]
	v_pk_mul_f32 v[62:63], v[46:47], v[54:55]
	v_pk_mul_f32 v[46:47], v[46:47], v[54:55] op_sel:[1,0] op_sel_hi:[0,1]
	v_pk_mul_f32 v[48:49], v[48:49], v[56:57] op_sel:[1,0] op_sel_hi:[0,1]
	v_add_f32_e32 v46, v46, v47
	v_sub_f32_e32 v47, v60, v61
	v_add_f32_e32 v48, v48, v49
	v_sub_f32_e32 v62, v62, v63
	v_cvt_pk_bf16_f32 v46, v62, v46
	v_cvt_pk_bf16_f32 v47, v47, v48
	v_pk_mul_f32 v[48:49], v[42:43], v[58:59]
	v_pk_mul_f32 v[42:43], v[42:43], v[58:59] op_sel:[1,0] op_sel_hi:[0,1]
	v_pk_mul_f32 v[52:53], v[52:53], v[80:81] op_sel_hi:[0,1]
	v_sub_f32_e32 v48, v48, v49
	v_add_f32_e32 v42, v42, v43
	v_pk_mul_f32 v[60:61], v[44:45], v[52:53]
	v_cvt_pk_bf16_f32 v48, v48, v42
	v_pk_mul_f32 v[42:43], v[44:45], v[52:53] op_sel:[1,0] op_sel_hi:[0,1]
	v_sub_f32_e32 v49, v60, v61
	v_add_f32_e32 v42, v42, v43
	v_mad_i64_i32 v[50:51], s[2:3], v50, s59, v[190:191]
	v_cvt_pk_bf16_f32 v49, v49, v42
	v_pk_mul_f32 v[42:43], v[40:41], v[56:57]
	v_pk_mul_f32 v[44:45], v[38:39], v[54:55]
	v_pk_mul_f32 v[38:39], v[38:39], v[54:55] op_sel:[1,0] op_sel_hi:[0,1]
	v_pk_mul_f32 v[40:41], v[40:41], v[56:57] op_sel:[1,0] op_sel_hi:[0,1]
	v_lshl_add_u64 v[50:51], v[50:51], 0, v[188:189]
	v_add_f32_e32 v38, v38, v39
	v_sub_f32_e32 v39, v42, v43
	v_add_f32_e32 v40, v40, v41
	ds_bpermute_b32 v60, v255, v50
	ds_bpermute_b32 v61, v255, v51
	ds_bpermute_b32 v62, v255, v46
	ds_bpermute_b32 v63, v255, v47
	ds_bpermute_b32 v64, v255, v48
	ds_bpermute_b32 v65, v255, v49
	s_waitcnt lgkmcnt(0)
; __device__ __forceinline__ unsigned cvt_pk_bf16(float lo, float hi) { unsigned r; asm volatile("v_cvt_pk_bf16_f32 %0, %1, %2" : "=v"(r) : "v"(lo), "v"(hi)); return r; }
; #define EPI_FENCE() asm volatile("" ::: "memory")
;     __device__ __forceinline__ void operator()(const f32x4 (&acc)[2][2][4][2], const Unit& u, int wr, int wc, int fr, int fq) const {
;     ...
;                 for (int m = 0; m < 4; ++m) { const int row = row0 + ai * HALF + m * 16; const f32x4* rp = (const f32x4*)(rope + ((size_t)(row & 4095) * 64 + j0) * 2); cs[m][0] = rp[0]; cs[m][1] = rp[1]; }
;                 EPI_FENCE();
; #pragma unroll
;                 for (int m = 0; m < 4; ++m) {
;                     bf16_t* rowp = Z + (size_t)(row0 + ai * HALF + m * 16) * 5120 + col0;
;                     const float sc = rs[4 * ai + m] * qs; const f32x4 c0 = cs[m][0] * sc, c1 = cs[m][1] * sc;
; #pragma unroll
;                     for (int bj = 0; bj < 2; ++bj) {
;                         const f32x4 v0 = acc[ai][bj][m][0], v1 = acc[ai][bj][m][1];
;                         u32x4 w;
;                         w.x = cvt_pk_bf16(v0[0] * c0[0] - v0[1] * c0[1], v0[1] * c0[0] + v0[0] * c0[1]);
;                         w.y = cvt_pk_bf16(v0[2] * c0[2] - v0[3] * c0[3], v0[3] * c0[2] + v0[2] * c0[3]);
;                         w.z = cvt_pk_bf16(v1[0] * c1[0] - v1[1] * c1[1], v1[1] * c1[0] + v1[0] * c1[1]);
;                         w.w = cvt_pk_bf16(v1[2] * c1[2] - v1[3] * c1[3], v1[3] * c1[2] + v1[2] * c1[3]);
;                         *(u32x4*)(rowp + bj * HALF) = w;
;                     }
;                 }
	global_store_dwordx4 v[60:61], v[62:65], off
	v_sub_f32_e32 v44, v44, v45
	v_cvt_pk_bf16_f32 v38, v44, v38
	v_cvt_pk_bf16_f32 v39, v39, v40
	v_pk_mul_f32 v[40:41], v[34:35], v[58:59]
	v_pk_mul_f32 v[34:35], v[34:35], v[58:59] op_sel:[1,0] op_sel_hi:[0,1]
	v_pk_mul_f32 v[42:43], v[36:37], v[52:53]
	v_sub_f32_e32 v40, v40, v41
	v_add_f32_e32 v34, v34, v35
	v_cvt_pk_bf16_f32 v40, v40, v34
	v_sub_f32_e32 v41, v42, v43
	v_pk_mul_f32 v[34:35], v[36:37], v[52:53] op_sel:[1,0] op_sel_hi:[0,1]
	v_add_f32_e32 v34, v34, v35
	v_cvt_pk_bf16_f32 v41, v41, v34
	v_mul_f32_e32 v36, v207, v180
	ds_bpermute_b32 v42, v255, v50
	ds_bpermute_b32 v43, v255, v51
	ds_bpermute_b32 v44, v255, v38
	ds_bpermute_b32 v45, v255, v39
	ds_bpermute_b32 v46, v255, v40
	ds_bpermute_b32 v47, v255, v41
	s_waitcnt lgkmcnt(0)
	global_store_dwordx4 v[42:43], v[44:47], off offset:256
	s_waitcnt vmcnt(7)
	v_pk_mul_f32 v[42:43], v[36:37], v[86:87] op_sel_hi:[0,1]
	v_add_u32_e32 v34, 0xa0, v206
	s_waitcnt vmcnt(6)
	v_pk_mul_f32 v[38:39], v[36:37], v[90:91] op_sel_hi:[0,1]
	v_pk_mul_f32 v[40:41], v[36:37], v[92:93] op_sel_hi:[0,1]
	v_pk_mul_f32 v[44:45], v[32:33], v[40:41]
	v_pk_mul_f32 v[46:47], v[30:31], v[38:39]
	v_pk_mul_f32 v[30:31], v[30:31], v[38:39] op_sel:[1,0] op_sel_hi:[0,1]
	v_pk_mul_f32 v[32:33], v[32:33], v[40:41] op_sel:[1,0] op_sel_hi:[0,1]
	v_add_f32_e32 v30, v30, v31
	v_sub_f32_e32 v31, v44, v45
	v_add_f32_e32 v32, v32, v33
	v_sub_f32_e32 v46, v46, v47
	v_cvt_pk_bf16_f32 v30, v46, v30
	v_cvt_pk_bf16_f32 v31, v31, v32
	v_pk_mul_f32 v[32:33], v[26:27], v[42:43]
	v_pk_mul_f32 v[26:27], v[26:27], v[42:43] op_sel:[1,0] op_sel_hi:[0,1]
	v_pk_mul_f32 v[36:37], v[36:37], v[88:89] op_sel_hi:[0,1]
	v_sub_f32_e32 v32, v32, v33
	v_add_f32_e32 v26, v26, v27
	v_pk_mul_f32 v[44:45], v[28:29], v[36:37]
	v_cvt_pk_bf16_f32 v32, v32, v26
	v_pk_mul_f32 v[26:27], v[28:29], v[36:37] op_sel:[1,0] op_sel_hi:[0,1]
	v_sub_f32_e32 v33, v44, v45
	v_add_f32_e32 v26, v26, v27
	v_mad_i64_i32 v[34:35], s[2:3], v34, s59, v[190:191]
	v_cvt_pk_bf16_f32 v33, v33, v26
	v_pk_mul_f32 v[26:27], v[24:25], v[40:41]
	v_pk_mul_f32 v[28:29], v[22:23], v[38:39]
	v_pk_mul_f32 v[22:23], v[22:23], v[38:39] op_sel:[1,0] op_sel_hi:[0,1]
	v_pk_mul_f32 v[24:25], v[24:25], v[40:41] op_sel:[1,0] op_sel_hi:[0,1]
	v_lshl_add_u64 v[34:35], v[34:35], 0, v[188:189]
	v_add_f32_e32 v22, v22, v23
	v_sub_f32_e32 v23, v26, v27
	v_add_f32_e32 v24, v24, v25
	ds_bpermute_b32 v44, v255, v34
	ds_bpermute_b32 v45, v255, v35
	ds_bpermute_b32 v46, v255, v30
	ds_bpermute_b32 v47, v255, v31
	ds_bpermute_b32 v48, v255, v32
	ds_bpermute_b32 v49, v255, v33
	s_waitcnt lgkmcnt(0)
	global_store_dwordx4 v[44:45], v[46:49], off
	v_sub_f32_e32 v28, v28, v29
	v_cvt_pk_bf16_f32 v22, v28, v22
	v_cvt_pk_bf16_f32 v23, v23, v24
	v_pk_mul_f32 v[24:25], v[18:19], v[42:43]
	v_pk_mul_f32 v[18:19], v[18:19], v[42:43] op_sel:[1,0] op_sel_hi:[0,1]
	v_pk_mul_f32 v[26:27], v[20:21], v[36:37]
	v_sub_f32_e32 v24, v24, v25
	v_add_f32_e32 v18, v18, v19
	v_cvt_pk_bf16_f32 v24, v24, v18
	v_sub_f32_e32 v25, v26, v27
	v_pk_mul_f32 v[18:19], v[20:21], v[36:37] op_sel:[1,0] op_sel_hi:[0,1]
	v_add_f32_e32 v18, v18, v19
	v_cvt_pk_bf16_f32 v25, v25, v18
	v_mul_f32_e32 v20, v207, v181
	ds_bpermute_b32 v26, v255, v34
	ds_bpermute_b32 v27, v255, v35
	ds_bpermute_b32 v28, v255, v22
	ds_bpermute_b32 v29, v255, v23
	ds_bpermute_b32 v30, v255, v24
	ds_bpermute_b32 v31, v255, v25
	s_waitcnt lgkmcnt(0)
	global_store_dwordx4 v[26:27], v[28:31], off offset:256
	s_waitcnt vmcnt(7)
	v_pk_mul_f32 v[26:27], v[20:21], v[66:67] op_sel_hi:[0,1]
	v_add_u32_e32 v18, 0xb0, v206
	s_waitcnt vmcnt(6)
	v_pk_mul_f32 v[22:23], v[20:21], v[94:95] op_sel_hi:[0,1]
	v_pk_mul_f32 v[24:25], v[20:21], v[96:97] op_sel_hi:[0,1]
	v_pk_mul_f32 v[28:29], v[16:17], v[24:25]
	v_pk_mul_f32 v[30:31], v[14:15], v[22:23]
	v_pk_mul_f32 v[14:15], v[14:15], v[22:23] op_sel:[1,0] op_sel_hi:[0,1]
	v_pk_mul_f32 v[16:17], v[16:17], v[24:25] op_sel:[1,0] op_sel_hi:[0,1]
	v_add_f32_e32 v14, v14, v15
	v_sub_f32_e32 v15, v28, v29
	v_add_f32_e32 v16, v16, v17
	v_sub_f32_e32 v30, v30, v31
	v_cvt_pk_bf16_f32 v14, v30, v14
	v_cvt_pk_bf16_f32 v15, v15, v16
	v_pk_mul_f32 v[16:17], v[10:11], v[26:27]
	v_pk_mul_f32 v[10:11], v[10:11], v[26:27] op_sel:[1,0] op_sel_hi:[0,1]
	v_pk_mul_f32 v[20:21], v[20:21], v[68:69] op_sel_hi:[0,1]
	v_sub_f32_e32 v16, v16, v17
	v_add_f32_e32 v10, v10, v11
	v_pk_mul_f32 v[28:29], v[12:13], v[20:21]
	v_cvt_pk_bf16_f32 v16, v16, v10
	v_pk_mul_f32 v[10:11], v[12:13], v[20:21] op_sel:[1,0] op_sel_hi:[0,1]
	v_sub_f32_e32 v17, v28, v29
	v_add_f32_e32 v10, v10, v11
	v_mad_i64_i32 v[18:19], s[2:3], v18, s59, v[190:191]
	v_cvt_pk_bf16_f32 v17, v17, v10
	v_pk_mul_f32 v[10:11], v[8:9], v[24:25]
	v_pk_mul_f32 v[12:13], v[6:7], v[22:23]
	v_pk_mul_f32 v[6:7], v[6:7], v[22:23] op_sel:[1,0] op_sel_hi:[0,1]
	v_pk_mul_f32 v[8:9], v[8:9], v[24:25] op_sel:[1,0] op_sel_hi:[0,1]
	v_lshl_add_u64 v[18:19], v[18:19], 0, v[188:189]
	v_add_f32_e32 v6, v6, v7
	v_sub_f32_e32 v7, v10, v11
	v_add_f32_e32 v8, v8, v9
	ds_bpermute_b32 v28, v255, v18
	ds_bpermute_b32 v29, v255, v19
	ds_bpermute_b32 v30, v255, v14
	ds_bpermute_b32 v31, v255, v15
	ds_bpermute_b32 v32, v255, v16
	ds_bpermute_b32 v33, v255, v17
	s_waitcnt lgkmcnt(0)
	global_store_dwordx4 v[28:29], v[30:33], off
	v_sub_f32_e32 v12, v12, v13
	v_cvt_pk_bf16_f32 v6, v12, v6
	v_cvt_pk_bf16_f32 v7, v7, v8
	v_pk_mul_f32 v[8:9], v[2:3], v[26:27]
	v_pk_mul_f32 v[2:3], v[2:3], v[26:27] op_sel:[1,0] op_sel_hi:[0,1]
	v_pk_mul_f32 v[10:11], v[4:5], v[20:21]
	v_sub_f32_e32 v8, v8, v9
	v_add_f32_e32 v2, v2, v3
	v_cvt_pk_bf16_f32 v8, v8, v2
	v_sub_f32_e32 v9, v10, v11
	v_pk_mul_f32 v[2:3], v[4:5], v[20:21] op_sel:[1,0] op_sel_hi:[0,1]
	v_add_f32_e32 v2, v2, v3
	v_cvt_pk_bf16_f32 v9, v9, v2
	ds_bpermute_b32 v10, v255, v18
	ds_bpermute_b32 v11, v255, v19
	ds_bpermute_b32 v12, v255, v6
	ds_bpermute_b32 v13, v255, v7
	ds_bpermute_b32 v14, v255, v8
	ds_bpermute_b32 v15, v255, v9
	s_waitcnt lgkmcnt(0)
	global_store_dwordx4 v[10:11], v[12:15], off offset:256

; __device__ __forceinline__ float sum_16_32(float v) { v += __shfl_xor(v, 16); v += __shfl_xor(v, 32); return v; }
; __device__ __forceinline__ unsigned cvt_pk_bf16(float lo, float hi) { unsigned r; asm volatile("v_cvt_pk_bf16_f32 %0, %1, %2" : "=v"(r) : "v"(lo), "v"(hi)); return r; }
;     __device__ __forceinline__ void operator()(const f32x4 (&acc)[2][2][4][2], const Unit& u, int wr, int wc, int fr, int fq) const {
;     ...
;         for (int ai = 0; ai < 2; ++ai) { float sm[4];
; #pragma unroll
;             for (int m = 0; m < 4; ++m) { const unsigned o = ob0 + (unsigned)((ai * HALF + m * 16) * LDC * 4); float s = 0.f;
; #pragma unroll
;                 for (int bj = 0; bj < 2; ++bj) {
;                     const f32x4 o0 = acc[ai][bj][m][0], o1 = acc[ai][bj][m][1];
;                     s += (o0[0] * o0[0] + o0[1] * o0[1]) + (o0[2] * o0[2] + o0[3] * o0[3]) + (o1[0] * o1[0] + o1[1] * o1[1]) + (o1[2] * o1[2] + o1[3] * o1[3]);
;                     if (wf32) { *(f32x4*)(ob + o + bj * HALF * 4) = o0; *(f32x4*)(ob + o + bj * HALF * 4 + 16) = o1; }
;                     else { u32x4 w; w.x = cvt_pk_bf16(o0[0], o0[1]); w.y = cvt_pk_bf16(o0[2], o0[3]); w.z = cvt_pk_bf16(o1[0], o1[1]); w.w = cvt_pk_bf16(o1[2], o1[3]);
;                            *(u32x4*)(xbb + (o >> 1) + bj * HALF * 2) = w; } }
;                 s = sum_16_32(s);
;                 sm[m] = s; }
;             ss[(size_t)(4 * u.pn + wc) * 16384 + u.pm * BM + wr * 64 + ai * HALF + 16 * fq + fr] = fq == 0 ? sm[0] : (fq == 1 ? sm[1] : (fq == 2 ? sm[2] : sm[3])); }
.LBB0_378:
	v_cvt_pk_bf16_f32 v166, v118, v119
	v_mov_b32_e32 v152, v118
	v_mov_b32_e32 v118, v119
	v_mov_b32_e32 v119, v123
	v_mov_b32_e32 v153, v122
	v_pk_mul_f32 v[118:119], v[118:119], v[118:119]
	v_cvt_pk_bf16_f32 v167, v120, v121
	v_cvt_pk_bf16_f32 v168, v114, v115
	v_cvt_pk_bf16_f32 v169, v116, v117
	s_lshl_b32 s0, s48, 8
	v_pk_fma_f32 v[118:119], v[152:153], v[152:153], v[118:119]
	v_mov_b32_e32 v152, v120
	v_mov_b32_e32 v120, v121
	v_mov_b32_e32 v121, v125
	v_mov_b32_e32 v153, v124
	v_pk_mul_f32 v[120:121], v[120:121], v[120:121]
	s_lshl_b32 s1, s33, 10
	v_pk_fma_f32 v[120:121], v[152:153], v[152:153], v[120:121]
	v_add_lshl_u32 v145, s0, v146, 13
	v_pk_add_f32 v[118:119], v[118:119], v[120:121]
	v_mov_b32_e32 v120, v114
	v_mov_b32_e32 v114, v115
	v_mov_b32_e32 v115, v127
	v_mov_b32_e32 v121, v126
	v_pk_mul_f32 v[114:115], v[114:115], v[114:115]
	v_add3_u32 v151, v148, s1, v145
	v_pk_fma_f32 v[114:115], v[120:121], v[120:121], v[114:115]
	v_lshrrev_b32_e32 v145, 1, v151
	v_pk_add_f32 v[114:115], v[118:119], v[114:115]
	v_mov_b32_e32 v118, v116
	v_mov_b32_e32 v116, v117
	v_mov_b32_e32 v117, v129
	v_mov_b32_e32 v119, v128
	v_pk_mul_f32 v[116:117], v[116:117], v[116:117]
	ds_bpermute_b32 v174, v255, v145
	ds_bpermute_b32 v176, v255, v166
	ds_bpermute_b32 v177, v255, v167
	ds_bpermute_b32 v178, v255, v168
	ds_bpermute_b32 v179, v255, v169
	s_waitcnt lgkmcnt(0)
	global_store_dwordx4 v174, v[176:179], s[12:13]
	v_pk_fma_f32 v[116:117], v[118:119], v[118:119], v[116:117]
	v_readlane_b32 s50, v252, 33
	v_pk_add_f32 v[114:115], v[116:117], v[114:115]
	v_cmp_lt_i32_e32 vcc, 0, v1
	v_add_f32_e32 v118, v114, v115
	ds_bpermute_b32 v119, v172, v118
	v_cvt_pk_bf16_f32 v114, v122, v123
	v_cvt_pk_bf16_f32 v115, v124, v125
	v_cvt_pk_bf16_f32 v116, v126, v127
	v_cvt_pk_bf16_f32 v117, v128, v129
	ds_bpermute_b32 v166, v255, v145
	ds_bpermute_b32 v168, v255, v114
	ds_bpermute_b32 v169, v255, v115
	ds_bpermute_b32 v170, v255, v116
	ds_bpermute_b32 v171, v255, v117
	s_waitcnt lgkmcnt(0)
	global_store_dwordx4 v166, v[168:171], s[12:13] offset:256
	s_mov_b64 s[2:3], 0
	v_readlane_b32 s51, v252, 34
	v_add_u32_e32 v116, 0x20000, v151
	v_mul_f32_e32 v117, v99, v99
	s_waitcnt lgkmcnt(0)
	v_add_f32_e32 v114, v118, v119
	v_lshrrev_b32_e32 v116, 1, v116
	v_fmac_f32_e32 v117, v98, v98
	v_mul_f32_e32 v118, v101, v101
	v_cvt_pk_bf16_f32 v98, v98, v99
	v_cvt_pk_bf16_f32 v99, v100, v101
	v_fmac_f32_e32 v118, v100, v100
	v_cvt_pk_bf16_f32 v100, v106, v107
	v_cvt_pk_bf16_f32 v101, v108, v109
	ds_bpermute_b32 v166, v255, v116
	ds_bpermute_b32 v168, v255, v98
	ds_bpermute_b32 v169, v255, v99
	ds_bpermute_b32 v170, v255, v100
	ds_bpermute_b32 v171, v255, v101
	s_waitcnt lgkmcnt(0)
	global_store_dwordx4 v166, v[168:171], s[12:13]
	v_add_f32_e32 v117, v117, v118
	v_mul_f32_e32 v118, v107, v107
	v_mul_f32_e32 v98, v103, v103
	v_mul_f32_e32 v99, v105, v105
	v_fmac_f32_e32 v98, v102, v102
	v_fmac_f32_e32 v99, v104, v104
	v_add_f32_e32 v98, v98, v99
	v_mul_f32_e32 v99, v111, v111
	v_fmac_f32_e32 v118, v106, v106
	v_fmac_f32_e32 v99, v110, v110
	v_add_f32_e32 v117, v117, v118
	v_mul_f32_e32 v118, v109, v109
	v_add_f32_e32 v98, v98, v99
	v_mul_f32_e32 v99, v113, v113
	v_fmac_f32_e32 v118, v108, v108
	v_fmac_f32_e32 v99, v112, v112
	v_add_f32_e32 v117, v118, v117
	v_add_f32_e32 v98, v99, v98
	v_add_f32_e32 v106, v117, v98
	v_cvt_pk_bf16_f32 v98, v102, v103
	ds_bpermute_b32 v102, v172, v106
	v_cvt_pk_bf16_f32 v99, v104, v105
	v_cvt_pk_bf16_f32 v100, v110, v111
	v_cvt_pk_bf16_f32 v101, v112, v113
	ds_bpermute_b32 v166, v255, v116
	ds_bpermute_b32 v168, v255, v98
	ds_bpermute_b32 v169, v255, v99
	ds_bpermute_b32 v170, v255, v100
	ds_bpermute_b32 v171, v255, v101
	s_waitcnt lgkmcnt(0)
; __device__ __forceinline__ float sum_16_32(float v) { v += __shfl_xor(v, 16); v += __shfl_xor(v, 32); return v; }
; __device__ __forceinline__ unsigned cvt_pk_bf16(float lo, float hi) { unsigned r; asm volatile("v_cvt_pk_bf16_f32 %0, %1, %2" : "=v"(r) : "v"(lo), "v"(hi)); return r; }
;     __device__ __forceinline__ void operator()(const f32x4 (&acc)[2][2][4][2], const Unit& u, int wr, int wc, int fr, int fq) const {
;     ...
;         for (int ai = 0; ai < 2; ++ai) { float sm[4];
; #pragma unroll
;             for (int m = 0; m < 4; ++m) { const unsigned o = ob0 + (unsigned)((ai * HALF + m * 16) * LDC * 4); float s = 0.f;
; #pragma unroll
;                 for (int bj = 0; bj < 2; ++bj) {
;                     const f32x4 o0 = acc[ai][bj][m][0], o1 = acc[ai][bj][m][1];
;                     s += (o0[0] * o0[0] + o0[1] * o0[1]) + (o0[2] * o0[2] + o0[3] * o0[3]) + (o1[0] * o1[0] + o1[1] * o1[1]) + (o1[2] * o1[2] + o1[3] * o1[3]);
;                     if (wf32) { *(f32x4*)(ob + o + bj * HALF * 4) = o0; *(f32x4*)(ob + o + bj * HALF * 4 + 16) = o1; }
;                     else { u32x4 w; w.x = cvt_pk_bf16(o0[0], o0[1]); w.y = cvt_pk_bf16(o0[2], o0[3]); w.z = cvt_pk_bf16(o1[0], o1[1]); w.w = cvt_pk_bf16(o1[2], o1[3]);
;                            *(u32x4*)(xbb + (o >> 1) + bj * HALF * 2) = w; } }
;                 s = sum_16_32(s);
;                 sm[m] = s; }
;             ss[(size_t)(4 * u.pn + wc) * 16384 + u.pm * BM + wr * 64 + ai * HALF + 16 * fq + fr] = fq == 0 ? sm[0] : (fq == 1 ? sm[1] : (fq == 2 ? sm[2] : sm[3])); }
	global_store_dwordx4 v166, v[168:171], s[12:13] offset:256
	ds_bpermute_b32 v115, v173, v114
	s_nop 0
	v_add_u32_e32 v100, 0x40000, v151
	v_mul_f32_e32 v101, v83, v83
	s_waitcnt lgkmcnt(0)
	v_add_f32_e32 v98, v106, v102
	v_lshrrev_b32_e32 v100, 1, v100
	v_fmac_f32_e32 v101, v82, v82
	v_mul_f32_e32 v102, v85, v85
	v_cvt_pk_bf16_f32 v82, v82, v83
	v_cvt_pk_bf16_f32 v83, v84, v85
	v_fmac_f32_e32 v102, v84, v84
	v_cvt_pk_bf16_f32 v84, v90, v91
	v_cvt_pk_bf16_f32 v85, v92, v93
	ds_bpermute_b32 v166, v255, v100
	ds_bpermute_b32 v168, v255, v82
	ds_bpermute_b32 v169, v255, v83
	ds_bpermute_b32 v170, v255, v84
	ds_bpermute_b32 v171, v255, v85
	s_waitcnt lgkmcnt(0)
	global_store_dwordx4 v166, v[168:171], s[12:13]
	v_add_f32_e32 v101, v101, v102
	v_mul_f32_e32 v102, v91, v91
	v_mul_f32_e32 v82, v87, v87
	v_mul_f32_e32 v83, v89, v89
	v_fmac_f32_e32 v82, v86, v86
	v_fmac_f32_e32 v83, v88, v88
	v_add_f32_e32 v82, v82, v83
	v_mul_f32_e32 v83, v95, v95
	v_fmac_f32_e32 v102, v90, v90
	v_fmac_f32_e32 v83, v94, v94
	v_add_f32_e32 v101, v101, v102
	v_mul_f32_e32 v102, v93, v93
	v_add_f32_e32 v82, v82, v83
	v_mul_f32_e32 v83, v97, v97
	v_fmac_f32_e32 v102, v92, v92
	v_fmac_f32_e32 v83, v96, v96
	v_add_f32_e32 v101, v102, v101
	v_add_f32_e32 v82, v83, v82
	v_add_f32_e32 v90, v101, v82
	v_cvt_pk_bf16_f32 v82, v86, v87
	ds_bpermute_b32 v86, v172, v90
	v_cvt_pk_bf16_f32 v83, v88, v89
	v_cvt_pk_bf16_f32 v84, v94, v95
	v_cvt_pk_bf16_f32 v85, v96, v97
	ds_bpermute_b32 v166, v255, v100
	ds_bpermute_b32 v168, v255, v82
	ds_bpermute_b32 v169, v255, v83
	ds_bpermute_b32 v170, v255, v84
	ds_bpermute_b32 v171, v255, v85
	s_waitcnt lgkmcnt(0)
	global_store_dwordx4 v166, v[168:171], s[12:13] offset:256
	ds_bpermute_b32 v99, v173, v98
	s_waitcnt lgkmcnt(0)
	v_add_f32_e32 v82, v90, v86
	v_mul_f32_e32 v85, v75, v75
	v_mul_f32_e32 v86, v77, v77
	v_fmac_f32_e32 v85, v74, v74
	v_fmac_f32_e32 v86, v76, v76
	v_cvt_pk_bf16_f32 v74, v74, v75
	v_cvt_pk_bf16_f32 v75, v76, v77
	v_mul_f32_e32 v76, v71, v71
	v_mul_f32_e32 v77, v73, v73
	v_fmac_f32_e32 v76, v70, v70
	v_fmac_f32_e32 v77, v72, v72
	v_add_f32_e32 v85, v85, v86
	v_mul_f32_e32 v86, v67, v67
	v_add_f32_e32 v76, v76, v77
	v_mul_f32_e32 v77, v79, v79
	v_fmac_f32_e32 v86, v66, v66
	v_fmac_f32_e32 v77, v78, v78
	v_add_f32_e32 v85, v85, v86
	v_mul_f32_e32 v86, v69, v69
	v_add_f32_e32 v76, v76, v77
	v_mul_f32_e32 v77, v81, v81
	v_fmac_f32_e32 v86, v68, v68
	v_fmac_f32_e32 v77, v80, v80
	v_add_f32_e32 v85, v86, v85
	v_add_f32_e32 v76, v77, v76
	v_add_f32_e32 v85, v85, v76
	ds_bpermute_b32 v86, v172, v85
	v_cvt_pk_bf16_f32 v76, v66, v67
	ds_bpermute_b32 v83, v173, v82
	v_add_u32_e32 v84, 0x60000, v151
	v_lshrrev_b32_e32 v84, 1, v84
	s_waitcnt lgkmcnt(0)
	v_add_f32_e32 v66, v85, v86
	ds_bpermute_b32 v67, v173, v66
	v_cvt_pk_bf16_f32 v77, v68, v69
	ds_bpermute_b32 v166, v255, v84
	ds_bpermute_b32 v168, v255, v74
	ds_bpermute_b32 v169, v255, v75
	ds_bpermute_b32 v170, v255, v76
	ds_bpermute_b32 v171, v255, v77
	s_waitcnt lgkmcnt(0)
	global_store_dwordx4 v166, v[168:171], s[12:13]
	v_cvt_pk_bf16_f32 v68, v70, v71
	v_cvt_pk_bf16_f32 v69, v72, v73
	v_cvt_pk_bf16_f32 v70, v78, v79
	v_cvt_pk_bf16_f32 v71, v80, v81
	ds_bpermute_b32 v166, v255, v84
	ds_bpermute_b32 v168, v255, v68
	ds_bpermute_b32 v169, v255, v69
	ds_bpermute_b32 v170, v255, v70
	ds_bpermute_b32 v171, v255, v71
	s_waitcnt lgkmcnt(0)
	global_store_dwordx4 v166, v[168:171], s[12:13] offset:256
	s_and_saveexec_b64 s[10:11], vcc
	s_xor_b64 s[10:11], exec, s[10:11]
	s_cbranch_execz .LBB0_388
	v_cmp_eq_u32_e32 vcc, 1, v1
	s_mov_b64 s[2:3], -1
	s_and_saveexec_b64 s[26:27], vcc
	v_add_f32_e32 v68, v98, v99
	s_xor_b64 s[2:3], exec, -1
	s_or_b64 exec, exec, s[26:27]
	s_and_b64 s[2:3], s[2:3], exec
	s_or_saveexec_b64 s[10:11], s[10:11]
	v_cmp_ne_u32_e32 vcc, 0, v1
	s_xor_b64 exec, exec, s[10:11]
	s_cbranch_execnz .LBB0_389

; __device__ __forceinline__ float sum_16_32(float v) { v += __shfl_xor(v, 16); v += __shfl_xor(v, 32); return v; }
; __device__ __forceinline__ unsigned cvt_pk_bf16(float lo, float hi) { unsigned r; asm volatile("v_cvt_pk_bf16_f32 %0, %1, %2" : "=v"(r) : "v"(lo), "v"(hi)); return r; }
;     __device__ __forceinline__ void operator()(const f32x4 (&acc)[2][2][4][2], const Unit& u, int wr, int wc, int fr, int fq) const {
;     ...
;         for (int ai = 0; ai < 2; ++ai) { float sm[4];
; #pragma unroll
;             for (int m = 0; m < 4; ++m) { const unsigned o = ob0 + (unsigned)((ai * HALF + m * 16) * LDC * 4); float s = 0.f;
; #pragma unroll
;                 for (int bj = 0; bj < 2; ++bj) {
;                     const f32x4 o0 = acc[ai][bj][m][0], o1 = acc[ai][bj][m][1];
;                     s += (o0[0] * o0[0] + o0[1] * o0[1]) + (o0[2] * o0[2] + o0[3] * o0[3]) + (o1[0] * o1[0] + o1[1] * o1[1]) + (o1[2] * o1[2] + o1[3] * o1[3]);
;                     if (wf32) { *(f32x4*)(ob + o + bj * HALF * 4) = o0; *(f32x4*)(ob + o + bj * HALF * 4 + 16) = o1; }
;                     else { u32x4 w; w.x = cvt_pk_bf16(o0[0], o0[1]); w.y = cvt_pk_bf16(o0[2], o0[3]); w.z = cvt_pk_bf16(o1[0], o1[1]); w.w = cvt_pk_bf16(o1[2], o1[3]);
;                            *(u32x4*)(xbb + (o >> 1) + bj * HALF * 2) = w; } }
;                 s = sum_16_32(s);
;                 sm[m] = s; }
;             ss[(size_t)(4 * u.pn + wc) * 16384 + u.pm * BM + wr * 64 + ai * HALF + 16 * fq + fr] = fq == 0 ? sm[0] : (fq == 1 ? sm[1] : (fq == 2 ? sm[2] : sm[3])); }
.LBB0_384:
	s_or_b64 exec, exec, s[10:11]
	s_lshl_b32 s1, s33, 2
	s_or_b32 s2, s1, s36
	s_ashr_i32 s3, s2, 31
	s_ashr_i32 s1, s0, 31
	s_lshl_b64 s[2:3], s[2:3], 16
	s_add_u32 s2, s42, s2
	s_addc_u32 s3, s43, s3
	s_lshl_b64 s[0:1], s[0:1], 2
	s_add_u32 s0, s2, s0
	s_addc_u32 s1, s3, s1
	s_add_u32 s0, s0, s18
	s_addc_u32 s1, s1, s19
	s_waitcnt lgkmcnt(0)
	v_lshl_add_u64 v[66:67], v[138:139], 2, s[0:1]
	v_mov_b32_e32 v145, v0
	v_lshl_add_u64 v[66:67], v[66:67], 0, v[144:145]
	global_store_dword v[66:67], v68, off
	v_add_u32_e32 v68, 0x100000, v151
	v_mul_f32_e32 v69, v35, v35
	v_lshrrev_b32_e32 v68, 1, v68
	v_fmac_f32_e32 v69, v34, v34
	v_mul_f32_e32 v70, v37, v37
	v_cvt_pk_bf16_f32 v34, v34, v35
	v_cvt_pk_bf16_f32 v35, v36, v37
	v_fmac_f32_e32 v70, v36, v36
	v_cvt_pk_bf16_f32 v36, v46, v47
	v_cvt_pk_bf16_f32 v37, v48, v49
	ds_bpermute_b32 v166, v255, v68
	ds_bpermute_b32 v168, v255, v34
	ds_bpermute_b32 v169, v255, v35
	ds_bpermute_b32 v170, v255, v36
	ds_bpermute_b32 v171, v255, v37
	s_waitcnt lgkmcnt(0)
	global_store_dwordx4 v166, v[168:171], s[12:13]
	v_add_f32_e32 v69, v69, v70
	v_mul_f32_e32 v70, v47, v47
	v_mul_f32_e32 v34, v39, v39
	v_mul_f32_e32 v35, v41, v41
	v_fmac_f32_e32 v34, v38, v38
	v_fmac_f32_e32 v35, v40, v40
	v_add_f32_e32 v34, v34, v35
	v_mul_f32_e32 v35, v55, v55
	v_fmac_f32_e32 v70, v46, v46
	v_fmac_f32_e32 v35, v54, v54
	v_add_f32_e32 v69, v69, v70
	v_mul_f32_e32 v70, v49, v49
	v_add_f32_e32 v34, v34, v35
	v_mul_f32_e32 v35, v57, v57
	v_fmac_f32_e32 v70, v48, v48
	v_fmac_f32_e32 v35, v56, v56
	v_add_f32_e32 v69, v70, v69
	v_add_f32_e32 v34, v35, v34
	v_add_f32_e32 v46, v69, v34
	v_cvt_pk_bf16_f32 v34, v38, v39
	ds_bpermute_b32 v38, v172, v46
	v_cvt_pk_bf16_f32 v35, v40, v41
	v_cvt_pk_bf16_f32 v36, v54, v55
	v_cvt_pk_bf16_f32 v37, v56, v57
	ds_bpermute_b32 v166, v255, v68
	ds_bpermute_b32 v168, v255, v34
	ds_bpermute_b32 v169, v255, v35
	ds_bpermute_b32 v170, v255, v36
	ds_bpermute_b32 v171, v255, v37
	s_waitcnt lgkmcnt(0)
	global_store_dwordx4 v166, v[168:171], s[12:13] offset:256
	v_cmp_lt_i32_e64 s[10:11], 0, v1
	s_mov_b64 s[0:1], 0
	v_add_u32_e32 v36, 0x120000, v151
	v_lshrrev_b32_e32 v40, 1, v36
	v_cvt_pk_bf16_f32 v36, v10, v11
	s_waitcnt lgkmcnt(0)
	v_add_f32_e32 v34, v46, v38
	v_cvt_pk_bf16_f32 v37, v12, v13
	v_cvt_pk_bf16_f32 v38, v6, v7
	v_cvt_pk_bf16_f32 v39, v8, v9
	ds_bpermute_b32 v166, v255, v40
	ds_bpermute_b32 v168, v255, v36
	ds_bpermute_b32 v169, v255, v37
	ds_bpermute_b32 v170, v255, v38
	ds_bpermute_b32 v171, v255, v39
	s_waitcnt lgkmcnt(0)
	global_store_dwordx4 v166, v[168:171], s[12:13]
	ds_bpermute_b32 v35, v173, v34
	s_mov_b64 s[2:3], 0
	v_mov_b32_e32 v36, v10
	v_mov_b32_e32 v10, v11
	v_mov_b32_e32 v11, v15
	v_mov_b32_e32 v37, v14
	v_pk_mul_f32 v[10:11], v[10:11], v[10:11]
	s_nop 0
	v_pk_fma_f32 v[10:11], v[36:37], v[36:37], v[10:11]
	v_mov_b32_e32 v36, v12
	v_mov_b32_e32 v12, v13
	v_mov_b32_e32 v13, v17
	v_mov_b32_e32 v37, v16
	v_pk_mul_f32 v[12:13], v[12:13], v[12:13]
	s_nop 0
	v_pk_fma_f32 v[12:13], v[36:37], v[36:37], v[12:13]
	s_nop 0
	v_pk_add_f32 v[10:11], v[10:11], v[12:13]
	v_mov_b32_e32 v12, v6
	v_mov_b32_e32 v6, v7
	v_mov_b32_e32 v7, v27
	v_mov_b32_e32 v13, v26
	v_pk_mul_f32 v[6:7], v[6:7], v[6:7]
	s_nop 0
	v_pk_fma_f32 v[6:7], v[12:13], v[12:13], v[6:7]
	s_nop 0
	v_pk_add_f32 v[6:7], v[10:11], v[6:7]
	v_mov_b32_e32 v10, v8
	v_mov_b32_e32 v8, v9
	v_mov_b32_e32 v9, v29
	v_mov_b32_e32 v11, v28
	v_pk_mul_f32 v[8:9], v[8:9], v[8:9]
	s_nop 0
	v_pk_fma_f32 v[8:9], v[10:11], v[10:11], v[8:9]
	s_nop 0
	v_pk_add_f32 v[6:7], v[8:9], v[6:7]
	s_nop 0
	v_add_f32_e32 v10, v6, v7
	v_cvt_pk_bf16_f32 v6, v14, v15
	v_cvt_pk_bf16_f32 v7, v16, v17
	v_cvt_pk_bf16_f32 v8, v26, v27
	v_cvt_pk_bf16_f32 v9, v28, v29
	ds_bpermute_b32 v166, v255, v40
	ds_bpermute_b32 v168, v255, v6
	ds_bpermute_b32 v169, v255, v7
	ds_bpermute_b32 v170, v255, v8
	ds_bpermute_b32 v171, v255, v9
	s_waitcnt lgkmcnt(0)
; __device__ __forceinline__ float sum_16_32(float v) { v += __shfl_xor(v, 16); v += __shfl_xor(v, 32); return v; }
; __device__ __forceinline__ unsigned cvt_pk_bf16(float lo, float hi) { unsigned r; asm volatile("v_cvt_pk_bf16_f32 %0, %1, %2" : "=v"(r) : "v"(lo), "v"(hi)); return r; }
;     __device__ __forceinline__ void operator()(const f32x4 (&acc)[2][2][4][2], const Unit& u, int wr, int wc, int fr, int fq) const {
;     ...
;                 for (int bj = 0; bj < 2; ++bj) {
;                     const f32x4 o0 = acc[ai][bj][m][0], o1 = acc[ai][bj][m][1];
;                     s += (o0[0] * o0[0] + o0[1] * o0[1]) + (o0[2] * o0[2] + o0[3] * o0[3]) + (o1[0] * o1[0] + o1[1] * o1[1]) + (o1[2] * o1[2] + o1[3] * o1[3]);
;                     if (wf32) { *(f32x4*)(ob + o + bj * HALF * 4) = o0; *(f32x4*)(ob + o + bj * HALF * 4 + 16) = o1; }
;                     else { u32x4 w; w.x = cvt_pk_bf16(o0[0], o0[1]); w.y = cvt_pk_bf16(o0[2], o0[3]); w.z = cvt_pk_bf16(o1[0], o1[1]); w.w = cvt_pk_bf16(o1[2], o1[3]);
;                            *(u32x4*)(xbb + (o >> 1) + bj * HALF * 2) = w; } }
;                 s = sum_16_32(s);
;                 sm[m] = s; }
;             ss[(size_t)(4 * u.pn + wc) * 16384 + u.pm * BM + wr * 64 + ai * HALF + 16 * fq + fr] = fq == 0 ? sm[0] : (fq == 1 ? sm[1] : (fq == 2 ? sm[2] : sm[3])); }
	global_store_dwordx4 v166, v[168:171], s[12:13] offset:256
	ds_bpermute_b32 v11, v172, v10
	v_mul_f32_e32 v15, v21, v21
	v_add_u32_e32 v8, 0x140000, v151
	v_lshrrev_b32_e32 v12, 1, v8
	v_mul_f32_e32 v8, v43, v43
	v_mul_f32_e32 v9, v45, v45
	v_fmac_f32_e32 v8, v42, v42
	v_fmac_f32_e32 v9, v44, v44
	v_add_f32_e32 v8, v8, v9
	v_mul_f32_e32 v9, v59, v59
	v_fmac_f32_e32 v9, v58, v58
	v_add_f32_e32 v8, v8, v9
	v_mul_f32_e32 v9, v61, v61
	v_fmac_f32_e32 v9, v60, v60
	v_add_f32_e32 v13, v9, v8
	v_cvt_pk_bf16_f32 v8, v42, v43
	v_cvt_pk_bf16_f32 v9, v44, v45
	s_waitcnt lgkmcnt(0)
	v_add_f32_e32 v6, v10, v11
	v_cvt_pk_bf16_f32 v10, v58, v59
	v_cvt_pk_bf16_f32 v11, v60, v61
	ds_bpermute_b32 v166, v255, v12
	ds_bpermute_b32 v168, v255, v8
	ds_bpermute_b32 v169, v255, v9
	ds_bpermute_b32 v170, v255, v10
	ds_bpermute_b32 v171, v255, v11
	s_waitcnt lgkmcnt(0)
	global_store_dwordx4 v166, v[168:171], s[12:13]
	v_fmac_f32_e32 v15, v20, v20
	ds_bpermute_b32 v7, v173, v6
	v_mul_f32_e32 v8, v51, v51
	v_mul_f32_e32 v9, v53, v53
	v_fmac_f32_e32 v8, v50, v50
	v_fmac_f32_e32 v9, v52, v52
	v_add_f32_e32 v8, v8, v9
	v_mul_f32_e32 v9, v63, v63
	v_fmac_f32_e32 v9, v62, v62
	v_add_f32_e32 v8, v8, v9
	v_mul_f32_e32 v9, v65, v65
	v_fmac_f32_e32 v9, v64, v64
	v_add_f32_e32 v8, v9, v8
	v_add_f32_e32 v13, v13, v8
	ds_bpermute_b32 v14, v172, v13
	v_cvt_pk_bf16_f32 v8, v50, v51
	v_cvt_pk_bf16_f32 v9, v52, v53
	v_cvt_pk_bf16_f32 v10, v62, v63
	v_cvt_pk_bf16_f32 v11, v64, v65
	ds_bpermute_b32 v166, v255, v12
	ds_bpermute_b32 v168, v255, v8
	ds_bpermute_b32 v169, v255, v9
	ds_bpermute_b32 v170, v255, v10
	ds_bpermute_b32 v171, v255, v11
	s_waitcnt lgkmcnt(0)
	global_store_dwordx4 v166, v[168:171], s[12:13] offset:256
	s_nop 1
	v_add_u32_e32 v10, 0x160000, v151
	s_waitcnt lgkmcnt(0)
	v_add_f32_e32 v8, v13, v14
	v_lshrrev_b32_e32 v14, 1, v10
	v_mul_f32_e32 v10, v23, v23
	v_mul_f32_e32 v11, v25, v25
	v_mul_f32_e32 v13, v19, v19
	v_fmac_f32_e32 v10, v22, v22
	v_fmac_f32_e32 v11, v24, v24
	v_fmac_f32_e32 v13, v18, v18
	v_add_f32_e32 v10, v10, v11
	v_mul_f32_e32 v11, v3, v3
	v_add_f32_e32 v13, v13, v15
	v_mul_f32_e32 v15, v31, v31
	v_fmac_f32_e32 v11, v2, v2
	v_fmac_f32_e32 v15, v30, v30
	v_add_f32_e32 v10, v10, v11
	v_mul_f32_e32 v11, v5, v5
	v_add_f32_e32 v13, v13, v15
	v_mul_f32_e32 v15, v33, v33
	v_fmac_f32_e32 v11, v4, v4
	v_fmac_f32_e32 v15, v32, v32
	v_add_f32_e32 v12, v11, v10
	v_add_f32_e32 v13, v15, v13
	v_add_f32_e32 v15, v12, v13
	ds_bpermute_b32 v16, v172, v15
	v_cvt_pk_bf16_f32 v10, v22, v23
	v_cvt_pk_bf16_f32 v11, v24, v25
	v_cvt_pk_bf16_f32 v12, v2, v3
	ds_bpermute_b32 v9, v173, v8
	s_waitcnt lgkmcnt(0)
	v_add_f32_e32 v3, v15, v16
	v_cvt_pk_bf16_f32 v13, v4, v5
	ds_bpermute_b32 v4, v173, v3
	ds_bpermute_b32 v166, v255, v14
	ds_bpermute_b32 v168, v255, v10
	ds_bpermute_b32 v169, v255, v11
	ds_bpermute_b32 v170, v255, v12
	ds_bpermute_b32 v171, v255, v13
	s_waitcnt lgkmcnt(0)
	global_store_dwordx4 v166, v[168:171], s[12:13]
	s_nop 1
	v_cvt_pk_bf16_f32 v10, v18, v19
	v_cvt_pk_bf16_f32 v11, v20, v21
	v_cvt_pk_bf16_f32 v12, v30, v31
	v_cvt_pk_bf16_f32 v13, v32, v33
	ds_bpermute_b32 v166, v255, v14
	ds_bpermute_b32 v168, v255, v10
	ds_bpermute_b32 v169, v255, v11
	ds_bpermute_b32 v170, v255, v12
	ds_bpermute_b32 v171, v255, v13
	s_waitcnt lgkmcnt(0)
	global_store_dwordx4 v166, v[168:171], s[12:13] offset:256
	s_and_saveexec_b64 s[26:27], s[10:11]
	s_xor_b64 s[26:27], exec, s[26:27]
	s_cbranch_execz .LBB0_390
	v_cmp_ne_u32_e64 s[10:11], 1, v1
	v_add_f32_e32 v2, v6, v7
	s_and_b64 s[2:3], s[10:11], exec
	s_andn2_saveexec_b64 s[10:11], s[26:27]
	s_cbranch_execnz .LBB0_391

; __device__ __forceinline__ unsigned cvt_pk_bf16(float lo, float hi) { unsigned r; asm volatile("v_cvt_pk_bf16_f32 %0, %1, %2" : "=v"(r) : "v"(lo), "v"(hi)); return r; }
; __device__ __forceinline__ void load_rs(float (&rs)[8], const RsTable& T, int pm, int lrow0) {
;     const int k = pm == T.pm[0] ? 0 : (pm == T.pm[1] ? 1 : (pm == T.pm[2] ? 2 : 3));
; #pragma unroll
;     for (int i = 0; i < 8; ++i) rs[i] = T.tab[k * 256 + lrow0 + (i >> 2) * HALF + (i & 3) * 16];
;     __device__ __forceinline__ void operator()(const f32x4 (&acc)[2][2][4][2], const Unit& u, int wr, int wc, int fr, int fq) const {
;     ...
;         for (int i = 0; i < 8; ++i) { const int ai = i >> 2, m = i & 3; bf16_t* rowp = O + (size_t)(row0 + ai * HALF + m * 16) * ldc + col0;
; #pragma unroll
;             for (int bj = 0; bj < 2; ++bj) { f32x4 v0 = acc[ai][bj][m][0] * rs[i], v1 = acc[ai][bj][m][1] * rs[i];
; #pragma unroll
;                 for (int e = 0; e < 4; ++e) { const float a = fmaxf(v0[e], 0.f), b = fmaxf(v1[e], 0.f); v0[e] = a * a; v1[e] = b * b; }
;                 u32x4 w; w.x = cvt_pk_bf16(v0[0], v0[1]); w.y = cvt_pk_bf16(v0[2], v0[3]); w.z = cvt_pk_bf16(v1[0], v1[1]); w.w = cvt_pk_bf16(v1[2], v1[3]);
;                 *(u32x4*)(rowp + bj * HALF) = w; } }
.LBB0_487:
	s_cmp_eq_u32 s43, s28
	s_cselect_b32 s0, 0x200, s56
	s_cmp_lg_u32 s43, s27
	s_cselect_b32 s0, s0, 0x100
	s_cmp_lg_u32 s43, s26
	s_cselect_b32 s0, s0, 0
	v_lshl_add_u32 v143, s0, 2, v166
	ds_read2_b32 v[168:169], v143 offset1:16
	ds_read2_b32 v[170:171], v143 offset0:32 offset1:48
	ds_read2_b32 v[148:149], v143 offset0:128 offset1:144
	ds_read2_b32 v[144:145], v143 offset0:160 offset1:176
	v_lshl_add_u32 v142, s43, 8, v1
	s_waitcnt lgkmcnt(0)
	v_pk_mul_f32 v[122:123], v[122:123], v[168:169] op_sel_hi:[1,0]
	v_lshl_add_u32 v146, s42, 8, v153
	v_ashrrev_i32_e32 v143, 31, v142
	v_pk_mul_f32 v[126:127], v[126:127], v[168:169] op_sel_hi:[1,0]
	v_pk_mul_f32 v[124:125], v[124:125], v[168:169] op_sel_hi:[1,0]
	v_max_f32_e32 v122, 0, v122
	v_ashrrev_i32_e32 v147, 31, v146
	v_lshlrev_b64 v[150:151], 14, v[142:143]
	v_pk_mul_f32 v[128:129], v[128:129], v[168:169] op_sel_hi:[1,0]
	v_mul_f32_e32 v143, v122, v122
	v_max_f32_e32 v122, 0, v127
	v_max_f32_e32 v123, 0, v123
	v_max_f32_e32 v124, 0, v124
	v_lshl_add_u64 v[150:151], s[12:13], 0, v[150:151]
	v_lshlrev_b64 v[146:147], 1, v[146:147]
	v_max_f32_e32 v126, 0, v126
	v_mul_f32_e32 v122, v122, v122
	v_mul_f32_e32 v127, v123, v123
	v_max_f32_e32 v123, 0, v128
	v_mul_f32_e32 v128, v124, v124
	v_max_f32_e32 v124, 0, v129
	v_max_f32_e32 v125, 0, v125
	v_pk_mul_f32 v[116:117], v[116:117], v[168:169] op_sel_hi:[1,0]
	v_pk_mul_f32 v[114:115], v[114:115], v[168:169] op_sel_hi:[1,0]
	v_lshl_add_u64 v[150:151], v[150:151], 0, v[146:147]
	v_mul_f32_e32 v126, v126, v126
	v_mul_f32_e32 v123, v123, v123
	v_mul_f32_e32 v124, v124, v124
	v_mul_f32_e32 v125, v125, v125
	v_cvt_pk_bf16_f32 v122, v126, v122
	v_pk_mul_f32 v[120:121], v[120:121], v[168:169] op_sel_hi:[1,0]
	v_pk_mul_f32 v[118:119], v[118:119], v[168:169] op_sel_hi:[1,0]
	v_max_f32_e32 v114, 0, v114
	v_max_f32_e32 v115, 0, v115
	v_max_f32_e32 v116, 0, v116
	v_cvt_pk_bf16_f32 v123, v123, v124
	v_cvt_pk_bf16_f32 v124, v143, v127
	v_cvt_pk_bf16_f32 v125, v128, v125
	ds_bpermute_b32 v174, v255, v150
	ds_bpermute_b32 v175, v255, v151
	ds_bpermute_b32 v176, v255, v122
	ds_bpermute_b32 v177, v255, v123
	ds_bpermute_b32 v178, v255, v124
	ds_bpermute_b32 v179, v255, v125
	s_waitcnt lgkmcnt(0)
	global_store_dwordx4 v[174:175], v[176:179], off
	v_max_f32_e32 v118, 0, v118
	v_max_f32_e32 v117, 0, v117
	v_mul_f32_e32 v122, v114, v114
	v_max_f32_e32 v114, 0, v119
	v_mul_f32_e32 v119, v115, v115
	v_max_f32_e32 v115, 0, v120
	v_mul_f32_e32 v120, v116, v116
	v_max_f32_e32 v116, 0, v121
	v_mul_f32_e32 v114, v114, v114
	v_mul_f32_e32 v115, v115, v115
	v_mul_f32_e32 v116, v116, v116
	v_mul_f32_e32 v118, v118, v118
	v_mul_f32_e32 v117, v117, v117
	v_cvt_pk_bf16_f32 v114, v118, v114
	v_cvt_pk_bf16_f32 v115, v115, v116
	v_cvt_pk_bf16_f32 v116, v122, v119
	v_cvt_pk_bf16_f32 v117, v120, v117
	ds_bpermute_b32 v118, v255, v150
	ds_bpermute_b32 v119, v255, v151
	ds_bpermute_b32 v120, v255, v114
	ds_bpermute_b32 v121, v255, v115
	ds_bpermute_b32 v122, v255, v116
	ds_bpermute_b32 v123, v255, v117
	s_waitcnt lgkmcnt(0)
	global_store_dwordx4 v[118:119], v[120:123], off offset:256
	v_pk_mul_f32 v[90:91], v[90:91], v[170:171] op_sel_hi:[1,0]
	v_pk_mul_f32 v[94:95], v[94:95], v[170:171] op_sel_hi:[1,0]
	v_mov_b32_e32 v116, v169
	v_or_b32_e32 v114, 16, v142
	v_pk_mul_f32 v[106:107], v[106:107], v[116:117] op_sel_hi:[1,0]
	v_ashrrev_i32_e32 v115, 31, v114
	v_pk_mul_f32 v[110:111], v[110:111], v[116:117] op_sel_hi:[1,0]
	v_pk_mul_f32 v[108:109], v[108:109], v[116:117] op_sel_hi:[1,0]
	v_max_f32_e32 v106, 0, v106
	v_lshlrev_b64 v[114:115], 14, v[114:115]
	v_pk_mul_f32 v[112:113], v[112:113], v[116:117] op_sel_hi:[1,0]
	v_mul_f32_e32 v117, v106, v106
	v_max_f32_e32 v106, 0, v111
	v_max_f32_e32 v107, 0, v107
	v_max_f32_e32 v108, 0, v108
	v_lshl_add_u64 v[114:115], s[12:13], 0, v[114:115]
	v_max_f32_e32 v110, 0, v110
	v_mul_f32_e32 v106, v106, v106
	v_mul_f32_e32 v111, v107, v107
	v_max_f32_e32 v107, 0, v112
	v_mul_f32_e32 v112, v108, v108
	v_max_f32_e32 v108, 0, v113
	v_max_f32_e32 v109, 0, v109
	v_pk_mul_f32 v[98:99], v[98:99], v[116:117] op_sel_hi:[1,0]
	v_lshl_add_u64 v[114:115], v[114:115], 0, v[146:147]
	v_mul_f32_e32 v110, v110, v110
	v_mul_f32_e32 v107, v107, v107
	v_mul_f32_e32 v108, v108, v108
	v_mul_f32_e32 v109, v109, v109
	v_cvt_pk_bf16_f32 v106, v110, v106
	v_pk_mul_f32 v[102:103], v[102:103], v[116:117] op_sel_hi:[1,0]
	v_pk_mul_f32 v[100:101], v[100:101], v[116:117] op_sel_hi:[1,0]
	v_max_f32_e32 v98, 0, v98
	v_cvt_pk_bf16_f32 v107, v107, v108
	v_cvt_pk_bf16_f32 v108, v117, v111
	v_cvt_pk_bf16_f32 v109, v112, v109
	ds_bpermute_b32 v118, v255, v114
	ds_bpermute_b32 v119, v255, v115
	ds_bpermute_b32 v120, v255, v106
	ds_bpermute_b32 v121, v255, v107
	ds_bpermute_b32 v122, v255, v108
	ds_bpermute_b32 v123, v255, v109
	s_waitcnt lgkmcnt(0)
	global_store_dwordx4 v[118:119], v[120:123], off
	v_pk_mul_f32 v[104:105], v[104:105], v[116:117] op_sel_hi:[1,0]
	v_max_f32_e32 v99, 0, v99
	v_mul_f32_e32 v106, v98, v98
	v_max_f32_e32 v98, 0, v103
	v_max_f32_e32 v100, 0, v100
	v_max_f32_e32 v102, 0, v102
	v_mul_f32_e32 v98, v98, v98
	v_mul_f32_e32 v103, v99, v99
	v_max_f32_e32 v99, 0, v104
	v_mul_f32_e32 v104, v100, v100
	v_max_f32_e32 v100, 0, v105
	v_max_f32_e32 v101, 0, v101
	v_mul_f32_e32 v102, v102, v102
	v_mul_f32_e32 v99, v99, v99
	v_mul_f32_e32 v100, v100, v100
	v_mul_f32_e32 v101, v101, v101
	v_cvt_pk_bf16_f32 v98, v102, v98
	v_cvt_pk_bf16_f32 v99, v99, v100
	v_cvt_pk_bf16_f32 v100, v106, v103
	v_cvt_pk_bf16_f32 v101, v104, v101
	ds_bpermute_b32 v102, v255, v114
	ds_bpermute_b32 v103, v255, v115
	ds_bpermute_b32 v104, v255, v98
	ds_bpermute_b32 v105, v255, v99
	ds_bpermute_b32 v106, v255, v100
	ds_bpermute_b32 v107, v255, v101
	s_waitcnt lgkmcnt(0)
; __device__ __forceinline__ unsigned cvt_pk_bf16(float lo, float hi) { unsigned r; asm volatile("v_cvt_pk_bf16_f32 %0, %1, %2" : "=v"(r) : "v"(lo), "v"(hi)); return r; }
;     __device__ __forceinline__ void operator()(const f32x4 (&acc)[2][2][4][2], const Unit& u, int wr, int wc, int fr, int fq) const {
;     ...
;         for (int i = 0; i < 8; ++i) { const int ai = i >> 2, m = i & 3; bf16_t* rowp = O + (size_t)(row0 + ai * HALF + m * 16) * ldc + col0;
; #pragma unroll
;             for (int bj = 0; bj < 2; ++bj) { f32x4 v0 = acc[ai][bj][m][0] * rs[i], v1 = acc[ai][bj][m][1] * rs[i];
; #pragma unroll
;                 for (int e = 0; e < 4; ++e) { const float a = fmaxf(v0[e], 0.f), b = fmaxf(v1[e], 0.f); v0[e] = a * a; v1[e] = b * b; }
;                 u32x4 w; w.x = cvt_pk_bf16(v0[0], v0[1]); w.y = cvt_pk_bf16(v0[2], v0[3]); w.z = cvt_pk_bf16(v1[0], v1[1]); w.w = cvt_pk_bf16(v1[2], v1[3]);
;                 *(u32x4*)(rowp + bj * HALF) = w; } }
	global_store_dwordx4 v[102:103], v[104:107], off offset:256
	v_pk_mul_f32 v[92:93], v[92:93], v[170:171] op_sel_hi:[1,0]
	v_max_f32_e32 v90, 0, v90
	v_or_b32_e32 v98, 32, v142
	v_ashrrev_i32_e32 v99, 31, v98
	v_lshlrev_b64 v[98:99], 14, v[98:99]
	v_pk_mul_f32 v[96:97], v[96:97], v[170:171] op_sel_hi:[1,0]
	v_mul_f32_e32 v100, v90, v90
	v_max_f32_e32 v90, 0, v95
	v_max_f32_e32 v91, 0, v91
	v_max_f32_e32 v92, 0, v92
	v_lshl_add_u64 v[98:99], s[12:13], 0, v[98:99]
	v_max_f32_e32 v94, 0, v94
	v_mul_f32_e32 v90, v90, v90
	v_mul_f32_e32 v95, v91, v91
	v_max_f32_e32 v91, 0, v96
	v_mul_f32_e32 v96, v92, v92
	v_max_f32_e32 v92, 0, v97
	v_max_f32_e32 v93, 0, v93
	v_pk_mul_f32 v[84:85], v[84:85], v[170:171] op_sel_hi:[1,0]
	v_pk_mul_f32 v[82:83], v[82:83], v[170:171] op_sel_hi:[1,0]
	v_lshl_add_u64 v[98:99], v[98:99], 0, v[146:147]
	v_mul_f32_e32 v94, v94, v94
	v_mul_f32_e32 v91, v91, v91
	v_mul_f32_e32 v92, v92, v92
	v_mul_f32_e32 v93, v93, v93
	v_cvt_pk_bf16_f32 v90, v94, v90
	v_pk_mul_f32 v[88:89], v[88:89], v[170:171] op_sel_hi:[1,0]
	v_pk_mul_f32 v[86:87], v[86:87], v[170:171] op_sel_hi:[1,0]
	v_max_f32_e32 v82, 0, v82
	v_max_f32_e32 v83, 0, v83
	v_max_f32_e32 v84, 0, v84
	v_cvt_pk_bf16_f32 v91, v91, v92
	v_cvt_pk_bf16_f32 v92, v100, v95
	v_cvt_pk_bf16_f32 v93, v96, v93
	ds_bpermute_b32 v100, v255, v98
	ds_bpermute_b32 v101, v255, v99
	ds_bpermute_b32 v102, v255, v90
	ds_bpermute_b32 v103, v255, v91
	ds_bpermute_b32 v104, v255, v92
	ds_bpermute_b32 v105, v255, v93
	s_waitcnt lgkmcnt(0)
	global_store_dwordx4 v[100:101], v[102:105], off
	v_max_f32_e32 v86, 0, v86
	v_max_f32_e32 v85, 0, v85
	v_mul_f32_e32 v90, v82, v82
	v_max_f32_e32 v82, 0, v87
	v_mul_f32_e32 v87, v83, v83
	v_max_f32_e32 v83, 0, v88
	v_mul_f32_e32 v88, v84, v84
	v_max_f32_e32 v84, 0, v89
	v_mul_f32_e32 v82, v82, v82
	v_mul_f32_e32 v83, v83, v83
	v_mul_f32_e32 v84, v84, v84
	v_mul_f32_e32 v86, v86, v86
	v_mul_f32_e32 v85, v85, v85
	v_cvt_pk_bf16_f32 v82, v86, v82
	v_cvt_pk_bf16_f32 v83, v83, v84
	v_cvt_pk_bf16_f32 v84, v90, v87
	v_cvt_pk_bf16_f32 v85, v88, v85
	ds_bpermute_b32 v86, v255, v98
	ds_bpermute_b32 v87, v255, v99
	ds_bpermute_b32 v88, v255, v82
	ds_bpermute_b32 v89, v255, v83
	ds_bpermute_b32 v90, v255, v84
	ds_bpermute_b32 v91, v255, v85
	s_waitcnt lgkmcnt(0)
	global_store_dwordx4 v[86:87], v[88:91], off offset:256
	v_pk_mul_f32 v[58:59], v[58:59], v[148:149] op_sel_hi:[1,0]
	v_pk_mul_f32 v[62:63], v[62:63], v[148:149] op_sel_hi:[1,0]
	v_mov_b32_e32 v84, v171
	v_or_b32_e32 v82, 48, v142
	v_pk_mul_f32 v[74:75], v[74:75], v[84:85] op_sel_hi:[1,0]
	v_ashrrev_i32_e32 v83, 31, v82
	v_pk_mul_f32 v[78:79], v[78:79], v[84:85] op_sel_hi:[1,0]
	v_pk_mul_f32 v[76:77], v[76:77], v[84:85] op_sel_hi:[1,0]
	v_max_f32_e32 v74, 0, v74
	v_lshlrev_b64 v[82:83], 14, v[82:83]
	v_pk_mul_f32 v[80:81], v[80:81], v[84:85] op_sel_hi:[1,0]
	v_mul_f32_e32 v85, v74, v74
	v_max_f32_e32 v74, 0, v79
	v_max_f32_e32 v75, 0, v75
	v_max_f32_e32 v76, 0, v76
	v_lshl_add_u64 v[82:83], s[12:13], 0, v[82:83]
	v_max_f32_e32 v78, 0, v78
	v_mul_f32_e32 v74, v74, v74
	v_mul_f32_e32 v79, v75, v75
	v_max_f32_e32 v75, 0, v80
	v_mul_f32_e32 v80, v76, v76
	v_max_f32_e32 v76, 0, v81
	v_max_f32_e32 v77, 0, v77
	v_pk_mul_f32 v[68:69], v[68:69], v[84:85] op_sel_hi:[1,0]
	v_pk_mul_f32 v[66:67], v[66:67], v[84:85] op_sel_hi:[1,0]
	v_lshl_add_u64 v[82:83], v[82:83], 0, v[146:147]
	v_mul_f32_e32 v78, v78, v78
	v_mul_f32_e32 v75, v75, v75
	v_mul_f32_e32 v76, v76, v76
	v_mul_f32_e32 v77, v77, v77
	v_cvt_pk_bf16_f32 v74, v78, v74
	v_pk_mul_f32 v[72:73], v[72:73], v[84:85] op_sel_hi:[1,0]
	v_pk_mul_f32 v[70:71], v[70:71], v[84:85] op_sel_hi:[1,0]
	v_max_f32_e32 v66, 0, v66
	v_max_f32_e32 v67, 0, v67
	v_max_f32_e32 v68, 0, v68
	v_cvt_pk_bf16_f32 v75, v75, v76
	v_cvt_pk_bf16_f32 v76, v85, v79
	v_cvt_pk_bf16_f32 v77, v80, v77
	ds_bpermute_b32 v84, v255, v82
	ds_bpermute_b32 v85, v255, v83
	ds_bpermute_b32 v86, v255, v74
	ds_bpermute_b32 v87, v255, v75
	ds_bpermute_b32 v88, v255, v76
	ds_bpermute_b32 v89, v255, v77
	s_waitcnt lgkmcnt(0)
	global_store_dwordx4 v[84:85], v[86:89], off
	v_max_f32_e32 v70, 0, v70
	v_max_f32_e32 v69, 0, v69
	v_mul_f32_e32 v74, v66, v66
	v_max_f32_e32 v66, 0, v71
	v_mul_f32_e32 v71, v67, v67
	v_max_f32_e32 v67, 0, v72
	v_mul_f32_e32 v72, v68, v68
	v_max_f32_e32 v68, 0, v73
	v_mul_f32_e32 v66, v66, v66
	v_mul_f32_e32 v67, v67, v67
	v_mul_f32_e32 v68, v68, v68
	v_mul_f32_e32 v70, v70, v70
	v_mul_f32_e32 v69, v69, v69
	v_cvt_pk_bf16_f32 v66, v70, v66
	v_cvt_pk_bf16_f32 v67, v67, v68
	v_cvt_pk_bf16_f32 v68, v74, v71
	v_pk_mul_f32 v[60:61], v[60:61], v[148:149] op_sel_hi:[1,0]
	v_max_f32_e32 v58, 0, v58
	v_cvt_pk_bf16_f32 v69, v72, v69
	ds_bpermute_b32 v70, v255, v82
	ds_bpermute_b32 v71, v255, v83
	ds_bpermute_b32 v72, v255, v66
	ds_bpermute_b32 v73, v255, v67
	ds_bpermute_b32 v74, v255, v68
	ds_bpermute_b32 v75, v255, v69
	s_waitcnt lgkmcnt(0)
	global_store_dwordx4 v[70:71], v[72:75], off offset:256
	s_mov_b64 s[0:1], 0x200000
	v_pk_mul_f32 v[64:65], v[64:65], v[148:149] op_sel_hi:[1,0]
	v_max_f32_e32 v62, 0, v62
	v_mul_f32_e32 v68, v58, v58
	v_max_f32_e32 v58, 0, v63
	v_max_f32_e32 v59, 0, v59
	v_max_f32_e32 v60, 0, v60
	v_lshl_add_u64 v[66:67], v[150:151], 0, s[0:1]
	v_mul_f32_e32 v62, v62, v62
	v_mul_f32_e32 v58, v58, v58
	v_mul_f32_e32 v63, v59, v59
	v_max_f32_e32 v59, 0, v64
	v_mul_f32_e32 v64, v60, v60
	v_max_f32_e32 v60, 0, v65
	s_mov_b32 s0, 0x200000
	v_mul_f32_e32 v59, v59, v59
	v_max_f32_e32 v61, 0, v61
	v_mul_f32_e32 v60, v60, v60
	v_cvt_pk_bf16_f32 v58, v62, v58
	v_add_co_u32_e32 v62, vcc, s0, v150
	v_pk_mul_f32 v[52:53], v[52:53], v[148:149] op_sel_hi:[1,0]
	v_pk_mul_f32 v[50:51], v[50:51], v[148:149] op_sel_hi:[1,0]
	v_mul_f32_e32 v61, v61, v61
	v_cvt_pk_bf16_f32 v59, v59, v60
	v_cvt_pk_bf16_f32 v60, v68, v63
	v_addc_co_u32_e32 v63, vcc, 0, v151, vcc
	v_pk_mul_f32 v[56:57], v[56:57], v[148:149] op_sel_hi:[1,0]
	v_pk_mul_f32 v[54:55], v[54:55], v[148:149] op_sel_hi:[1,0]
	v_max_f32_e32 v50, 0, v50
	v_max_f32_e32 v51, 0, v51
	v_max_f32_e32 v52, 0, v52
	v_cvt_pk_bf16_f32 v61, v64, v61
	ds_bpermute_b32 v68, v255, v62
	ds_bpermute_b32 v69, v255, v63
	ds_bpermute_b32 v70, v255, v58
	ds_bpermute_b32 v71, v255, v59
	ds_bpermute_b32 v72, v255, v60
	ds_bpermute_b32 v73, v255, v61
	s_waitcnt lgkmcnt(0)
; __device__ __forceinline__ unsigned cvt_pk_bf16(float lo, float hi) { unsigned r; asm volatile("v_cvt_pk_bf16_f32 %0, %1, %2" : "=v"(r) : "v"(lo), "v"(hi)); return r; }
;     __device__ __forceinline__ void operator()(const f32x4 (&acc)[2][2][4][2], const Unit& u, int wr, int wc, int fr, int fq) const {
;     ...
;         for (int i = 0; i < 8; ++i) { const int ai = i >> 2, m = i & 3; bf16_t* rowp = O + (size_t)(row0 + ai * HALF + m * 16) * ldc + col0;
; #pragma unroll
;             for (int bj = 0; bj < 2; ++bj) { f32x4 v0 = acc[ai][bj][m][0] * rs[i], v1 = acc[ai][bj][m][1] * rs[i];
; #pragma unroll
;                 for (int e = 0; e < 4; ++e) { const float a = fmaxf(v0[e], 0.f), b = fmaxf(v1[e], 0.f); v0[e] = a * a; v1[e] = b * b; }
;                 u32x4 w; w.x = cvt_pk_bf16(v0[0], v0[1]); w.y = cvt_pk_bf16(v0[2], v0[3]); w.z = cvt_pk_bf16(v1[0], v1[1]); w.w = cvt_pk_bf16(v1[2], v1[3]);
;                 *(u32x4*)(rowp + bj * HALF) = w; } }
	global_store_dwordx4 v[68:69], v[70:73], off
	v_max_f32_e32 v54, 0, v54
	v_max_f32_e32 v53, 0, v53
	v_mul_f32_e32 v58, v50, v50
	v_max_f32_e32 v50, 0, v55
	v_mul_f32_e32 v55, v51, v51
	v_max_f32_e32 v51, 0, v56
	v_mul_f32_e32 v56, v52, v52
	v_max_f32_e32 v52, 0, v57
	v_mul_f32_e32 v50, v50, v50
	v_mul_f32_e32 v51, v51, v51
	v_mul_f32_e32 v52, v52, v52
	v_mul_f32_e32 v54, v54, v54
	v_mul_f32_e32 v53, v53, v53
	v_cvt_pk_bf16_f32 v50, v54, v50
	v_cvt_pk_bf16_f32 v51, v51, v52
	v_cvt_pk_bf16_f32 v52, v58, v55
	v_cvt_pk_bf16_f32 v53, v56, v53
	ds_bpermute_b32 v54, v255, v66
	ds_bpermute_b32 v55, v255, v67
	ds_bpermute_b32 v56, v255, v50
	ds_bpermute_b32 v57, v255, v51
	ds_bpermute_b32 v58, v255, v52
	ds_bpermute_b32 v59, v255, v53
	s_waitcnt lgkmcnt(0)
	global_store_dwordx4 v[54:55], v[56:59], off offset:256
	v_pk_mul_f32 v[26:27], v[26:27], v[144:145] op_sel_hi:[1,0]
	v_pk_mul_f32 v[30:31], v[30:31], v[144:145] op_sel_hi:[1,0]
	v_mov_b32_e32 v52, v149
	v_add_u32_e32 v50, 0x90, v142
	v_pk_mul_f32 v[42:43], v[42:43], v[52:53] op_sel_hi:[1,0]
	v_ashrrev_i32_e32 v51, 31, v50
	v_pk_mul_f32 v[46:47], v[46:47], v[52:53] op_sel_hi:[1,0]
	v_pk_mul_f32 v[44:45], v[44:45], v[52:53] op_sel_hi:[1,0]
	v_max_f32_e32 v42, 0, v42
	v_lshlrev_b64 v[50:51], 14, v[50:51]
	v_pk_mul_f32 v[48:49], v[48:49], v[52:53] op_sel_hi:[1,0]
	v_mul_f32_e32 v53, v42, v42
	v_max_f32_e32 v42, 0, v47
	v_max_f32_e32 v43, 0, v43
	v_max_f32_e32 v44, 0, v44
	v_lshl_add_u64 v[50:51], s[12:13], 0, v[50:51]
	v_max_f32_e32 v46, 0, v46
	v_mul_f32_e32 v42, v42, v42
	v_mul_f32_e32 v47, v43, v43
	v_max_f32_e32 v43, 0, v48
	v_mul_f32_e32 v48, v44, v44
	v_max_f32_e32 v44, 0, v49
	v_max_f32_e32 v45, 0, v45
	v_pk_mul_f32 v[34:35], v[34:35], v[52:53] op_sel_hi:[1,0]
	v_lshl_add_u64 v[50:51], v[50:51], 0, v[146:147]
	v_mul_f32_e32 v46, v46, v46
	v_mul_f32_e32 v43, v43, v43
	v_mul_f32_e32 v44, v44, v44
	v_mul_f32_e32 v45, v45, v45
	v_cvt_pk_bf16_f32 v42, v46, v42
	v_pk_mul_f32 v[38:39], v[38:39], v[52:53] op_sel_hi:[1,0]
	v_pk_mul_f32 v[36:37], v[36:37], v[52:53] op_sel_hi:[1,0]
	v_max_f32_e32 v34, 0, v34
	v_cvt_pk_bf16_f32 v43, v43, v44
	v_cvt_pk_bf16_f32 v44, v53, v47
	v_cvt_pk_bf16_f32 v45, v48, v45
	ds_bpermute_b32 v54, v255, v50
	ds_bpermute_b32 v55, v255, v51
	ds_bpermute_b32 v56, v255, v42
	ds_bpermute_b32 v57, v255, v43
	ds_bpermute_b32 v58, v255, v44
	ds_bpermute_b32 v59, v255, v45
	s_waitcnt lgkmcnt(0)
	global_store_dwordx4 v[54:55], v[56:59], off
	v_pk_mul_f32 v[40:41], v[40:41], v[52:53] op_sel_hi:[1,0]
	v_max_f32_e32 v35, 0, v35
	v_mul_f32_e32 v42, v34, v34
	v_max_f32_e32 v34, 0, v39
	v_max_f32_e32 v36, 0, v36
	v_max_f32_e32 v38, 0, v38
	v_mul_f32_e32 v34, v34, v34
	v_mul_f32_e32 v39, v35, v35
	v_max_f32_e32 v35, 0, v40
	v_mul_f32_e32 v40, v36, v36
	v_max_f32_e32 v36, 0, v41
	v_max_f32_e32 v37, 0, v37
	v_mul_f32_e32 v38, v38, v38
	v_mul_f32_e32 v35, v35, v35
	v_mul_f32_e32 v36, v36, v36
	v_mul_f32_e32 v37, v37, v37
	v_cvt_pk_bf16_f32 v34, v38, v34
	v_cvt_pk_bf16_f32 v35, v35, v36
	v_cvt_pk_bf16_f32 v36, v42, v39
	v_cvt_pk_bf16_f32 v37, v40, v37
	ds_bpermute_b32 v38, v255, v50
	ds_bpermute_b32 v39, v255, v51
	ds_bpermute_b32 v40, v255, v34
	ds_bpermute_b32 v41, v255, v35
	ds_bpermute_b32 v42, v255, v36
	ds_bpermute_b32 v43, v255, v37
	s_waitcnt lgkmcnt(0)
	global_store_dwordx4 v[38:39], v[40:43], off offset:256
	v_pk_mul_f32 v[28:29], v[28:29], v[144:145] op_sel_hi:[1,0]
	v_max_f32_e32 v26, 0, v26
	v_add_u32_e32 v34, 0xa0, v142
	v_ashrrev_i32_e32 v35, 31, v34
	v_lshlrev_b64 v[34:35], 14, v[34:35]
	v_pk_mul_f32 v[32:33], v[32:33], v[144:145] op_sel_hi:[1,0]
	v_mul_f32_e32 v36, v26, v26
	v_max_f32_e32 v26, 0, v31
	v_max_f32_e32 v27, 0, v27
	v_max_f32_e32 v28, 0, v28
	v_lshl_add_u64 v[34:35], s[12:13], 0, v[34:35]
	v_max_f32_e32 v30, 0, v30
	v_mul_f32_e32 v26, v26, v26
	v_mul_f32_e32 v31, v27, v27
	v_max_f32_e32 v27, 0, v32
	v_mul_f32_e32 v32, v28, v28
	v_max_f32_e32 v28, 0, v33
	v_max_f32_e32 v29, 0, v29
	v_pk_mul_f32 v[20:21], v[20:21], v[144:145] op_sel_hi:[1,0]
	v_pk_mul_f32 v[18:19], v[18:19], v[144:145] op_sel_hi:[1,0]
	v_lshl_add_u64 v[34:35], v[34:35], 0, v[146:147]
	v_mul_f32_e32 v30, v30, v30
	v_mul_f32_e32 v27, v27, v27
	v_mul_f32_e32 v28, v28, v28
	v_mul_f32_e32 v29, v29, v29
	v_cvt_pk_bf16_f32 v26, v30, v26
	v_pk_mul_f32 v[24:25], v[24:25], v[144:145] op_sel_hi:[1,0]
	v_pk_mul_f32 v[22:23], v[22:23], v[144:145] op_sel_hi:[1,0]
	v_max_f32_e32 v18, 0, v18
	v_max_f32_e32 v19, 0, v19
	v_max_f32_e32 v20, 0, v20
	v_cvt_pk_bf16_f32 v27, v27, v28
	v_cvt_pk_bf16_f32 v28, v36, v31
	v_cvt_pk_bf16_f32 v29, v32, v29
	ds_bpermute_b32 v36, v255, v34
	ds_bpermute_b32 v37, v255, v35
	ds_bpermute_b32 v38, v255, v26
	ds_bpermute_b32 v39, v255, v27
	ds_bpermute_b32 v40, v255, v28
	ds_bpermute_b32 v41, v255, v29
	s_waitcnt lgkmcnt(0)
; __device__ __forceinline__ unsigned cvt_pk_bf16(float lo, float hi) { unsigned r; asm volatile("v_cvt_pk_bf16_f32 %0, %1, %2" : "=v"(r) : "v"(lo), "v"(hi)); return r; }
;     __device__ __forceinline__ void operator()(const f32x4 (&acc)[2][2][4][2], const Unit& u, int wr, int wc, int fr, int fq) const {
;     ...
;         for (int i = 0; i < 8; ++i) { const int ai = i >> 2, m = i & 3; bf16_t* rowp = O + (size_t)(row0 + ai * HALF + m * 16) * ldc + col0;
; #pragma unroll
;             for (int bj = 0; bj < 2; ++bj) { f32x4 v0 = acc[ai][bj][m][0] * rs[i], v1 = acc[ai][bj][m][1] * rs[i];
; #pragma unroll
;                 for (int e = 0; e < 4; ++e) { const float a = fmaxf(v0[e], 0.f), b = fmaxf(v1[e], 0.f); v0[e] = a * a; v1[e] = b * b; }
;                 u32x4 w; w.x = cvt_pk_bf16(v0[0], v0[1]); w.y = cvt_pk_bf16(v0[2], v0[3]); w.z = cvt_pk_bf16(v1[0], v1[1]); w.w = cvt_pk_bf16(v1[2], v1[3]);
;                 *(u32x4*)(rowp + bj * HALF) = w; } }
	global_store_dwordx4 v[36:37], v[38:41], off
	v_max_f32_e32 v22, 0, v22
	v_max_f32_e32 v21, 0, v21
	v_mul_f32_e32 v26, v18, v18
	v_max_f32_e32 v18, 0, v23
	v_mul_f32_e32 v23, v19, v19
	v_max_f32_e32 v19, 0, v24
	v_mul_f32_e32 v24, v20, v20
	v_max_f32_e32 v20, 0, v25
	v_mul_f32_e32 v18, v18, v18
	v_mul_f32_e32 v19, v19, v19
	v_mul_f32_e32 v20, v20, v20
	v_mul_f32_e32 v22, v22, v22
	v_mul_f32_e32 v21, v21, v21
	v_cvt_pk_bf16_f32 v18, v22, v18
	v_cvt_pk_bf16_f32 v19, v19, v20
	v_cvt_pk_bf16_f32 v20, v26, v23
	v_cvt_pk_bf16_f32 v21, v24, v21
	ds_bpermute_b32 v22, v255, v34
	ds_bpermute_b32 v23, v255, v35
	ds_bpermute_b32 v24, v255, v18
	ds_bpermute_b32 v25, v255, v19
	ds_bpermute_b32 v26, v255, v20
	ds_bpermute_b32 v27, v255, v21
	s_waitcnt lgkmcnt(0)
	global_store_dwordx4 v[22:23], v[24:27], off offset:256
	s_andn2_b64 vcc, exec, s[6:7]
	s_mov_b64 s[0:1], -1
	v_mov_b32_e32 v20, v145
	v_add_u32_e32 v18, 0xb0, v142
	v_pk_mul_f32 v[10:11], v[10:11], v[20:21] op_sel_hi:[1,0]
	v_ashrrev_i32_e32 v19, 31, v18
	v_pk_mul_f32 v[14:15], v[14:15], v[20:21] op_sel_hi:[1,0]
	v_pk_mul_f32 v[12:13], v[12:13], v[20:21] op_sel_hi:[1,0]
	v_max_f32_e32 v10, 0, v10
	v_lshlrev_b64 v[18:19], 14, v[18:19]
	v_pk_mul_f32 v[16:17], v[16:17], v[20:21] op_sel_hi:[1,0]
	v_mul_f32_e32 v21, v10, v10
	v_max_f32_e32 v10, 0, v15
	v_max_f32_e32 v11, 0, v11
	v_max_f32_e32 v12, 0, v12
	v_lshl_add_u64 v[18:19], s[12:13], 0, v[18:19]
	v_max_f32_e32 v14, 0, v14
	v_mul_f32_e32 v10, v10, v10
	v_mul_f32_e32 v15, v11, v11
	v_max_f32_e32 v11, 0, v16
	v_mul_f32_e32 v16, v12, v12
	v_max_f32_e32 v12, 0, v17
	v_max_f32_e32 v13, 0, v13
	v_pk_mul_f32 v[4:5], v[4:5], v[20:21] op_sel_hi:[1,0]
	v_pk_mul_f32 v[2:3], v[2:3], v[20:21] op_sel_hi:[1,0]
	v_lshl_add_u64 v[18:19], v[18:19], 0, v[146:147]
	v_mul_f32_e32 v14, v14, v14
	v_mul_f32_e32 v11, v11, v11
	v_mul_f32_e32 v12, v12, v12
	v_mul_f32_e32 v13, v13, v13
	v_cvt_pk_bf16_f32 v10, v14, v10
	v_pk_mul_f32 v[8:9], v[8:9], v[20:21] op_sel_hi:[1,0]
	v_pk_mul_f32 v[6:7], v[6:7], v[20:21] op_sel_hi:[1,0]
	v_max_f32_e32 v2, 0, v2
	v_max_f32_e32 v3, 0, v3
	v_max_f32_e32 v4, 0, v4
	v_cvt_pk_bf16_f32 v11, v11, v12
	v_cvt_pk_bf16_f32 v12, v21, v15
	v_cvt_pk_bf16_f32 v13, v16, v13
	ds_bpermute_b32 v20, v255, v18
	ds_bpermute_b32 v21, v255, v19
	ds_bpermute_b32 v22, v255, v10
	ds_bpermute_b32 v23, v255, v11
	ds_bpermute_b32 v24, v255, v12
	ds_bpermute_b32 v25, v255, v13
	s_waitcnt lgkmcnt(0)
	global_store_dwordx4 v[20:21], v[22:25], off
	v_max_f32_e32 v5, 0, v5
	v_max_f32_e32 v6, 0, v6
	v_mul_f32_e32 v10, v2, v2
	v_max_f32_e32 v2, 0, v7
	v_mul_f32_e32 v7, v3, v3
	v_max_f32_e32 v3, 0, v8
	v_mul_f32_e32 v8, v4, v4
	v_max_f32_e32 v4, 0, v9
	v_mul_f32_e32 v2, v2, v2
	v_mul_f32_e32 v3, v3, v3
	v_mul_f32_e32 v4, v4, v4
	v_mul_f32_e32 v5, v5, v5
	v_readlane_b32 s50, v252, 33
	v_mul_f32_e32 v6, v6, v6
	v_cvt_pk_bf16_f32 v2, v6, v2
	v_cvt_pk_bf16_f32 v3, v3, v4
	v_cvt_pk_bf16_f32 v4, v10, v7
	v_cvt_pk_bf16_f32 v5, v8, v5
	ds_bpermute_b32 v10, v255, v18
	ds_bpermute_b32 v11, v255, v19
	ds_bpermute_b32 v12, v255, v2
	ds_bpermute_b32 v13, v255, v3
	ds_bpermute_b32 v14, v255, v4
	ds_bpermute_b32 v15, v255, v5
	s_waitcnt lgkmcnt(0)
	global_store_dwordx4 v[10:11], v[12:15], off offset:256
	v_readlane_b32 s51, v252, 34
	s_cbranch_vccnz .LBB0_476
	s_andn2_b64 vcc, exec, s[10:11]
	s_cbranch_vccnz .LBB0_475
	s_barrier
	s_branch .LBB0_475

; __device__ __forceinline__ unsigned cvt_pk_bf16(float lo, float hi) { unsigned r; asm volatile("v_cvt_pk_bf16_f32 %0, %1, %2" : "=v"(r) : "v"(lo), "v"(hi)); return r; }
;     __device__ __forceinline__ void operator()(const f32x4 (&acc)[2][2][4][2], const Unit& u, int wr, int wc, int fr, int fq) const {
;     ...
;         for (int ai = 0; ai < 2; ++ai) { float sm[4];
; #pragma unroll
;             for (int m = 0; m < 4; ++m) { const unsigned o = ob0 + (unsigned)((ai * HALF + m * 16) * LDC * 4); float s = 0.f;
; #pragma unroll
;                 for (int bj = 0; bj < 2; ++bj) {
;                     const f32x4 o0 = acc[ai][bj][m][0], o1 = acc[ai][bj][m][1];
;                     s += (o0[0] * o0[0] + o0[1] * o0[1]) + (o0[2] * o0[2] + o0[3] * o0[3]) + (o1[0] * o1[0] + o1[1] * o1[1]) + (o1[2] * o1[2] + o1[3] * o1[3]);
;                     if (wf32) { *(f32x4*)(ob + o + bj * HALF * 4) = o0; *(f32x4*)(ob + o + bj * HALF * 4 + 16) = o1; }
;                     else { u32x4 w; w.x = cvt_pk_bf16(o0[0], o0[1]); w.y = cvt_pk_bf16(o0[2], o0[3]); w.z = cvt_pk_bf16(o1[0], o1[1]); w.w = cvt_pk_bf16(o1[2], o1[3]);
;                            *(u32x4*)(xbb + (o >> 1) + bj * HALF * 2) = w; } }
.LBB0_548:
	v_cvt_pk_bf16_f32 v166, v118, v119
	v_mov_b32_e32 v152, v118
	v_mov_b32_e32 v118, v119
	v_mov_b32_e32 v119, v123
	v_mov_b32_e32 v153, v122
	v_pk_mul_f32 v[118:119], v[118:119], v[118:119]
	v_cvt_pk_bf16_f32 v167, v120, v121
	v_cvt_pk_bf16_f32 v168, v114, v115
	v_cvt_pk_bf16_f32 v169, v116, v117
	s_lshl_b32 s0, s45, 8
	v_pk_fma_f32 v[118:119], v[152:153], v[152:153], v[118:119]
	v_mov_b32_e32 v152, v120
	v_mov_b32_e32 v120, v121
	v_mov_b32_e32 v121, v125
	v_mov_b32_e32 v153, v124
	v_pk_mul_f32 v[120:121], v[120:121], v[120:121]
	s_lshl_b32 s1, s33, 10
	v_pk_fma_f32 v[120:121], v[152:153], v[152:153], v[120:121]
	v_add_lshl_u32 v145, s0, v146, 13
	v_pk_add_f32 v[118:119], v[118:119], v[120:121]
	v_mov_b32_e32 v120, v114
	v_mov_b32_e32 v114, v115
	v_mov_b32_e32 v115, v127
	v_mov_b32_e32 v121, v126
	v_pk_mul_f32 v[114:115], v[114:115], v[114:115]
	v_add3_u32 v151, v148, s1, v145
	v_pk_fma_f32 v[114:115], v[120:121], v[120:121], v[114:115]
	v_lshrrev_b32_e32 v145, 1, v151
	v_pk_add_f32 v[114:115], v[118:119], v[114:115]
	v_mov_b32_e32 v118, v116
	v_mov_b32_e32 v116, v117
	v_mov_b32_e32 v117, v129
	v_mov_b32_e32 v119, v128
	v_pk_mul_f32 v[116:117], v[116:117], v[116:117]
	ds_bpermute_b32 v174, v255, v145
	ds_bpermute_b32 v176, v255, v166
	ds_bpermute_b32 v177, v255, v167
	ds_bpermute_b32 v178, v255, v168
	ds_bpermute_b32 v179, v255, v169
	s_waitcnt lgkmcnt(0)
	global_store_dwordx4 v174, v[176:179], s[10:11]
	v_pk_fma_f32 v[116:117], v[118:119], v[118:119], v[116:117]
	v_cmp_lt_i32_e32 vcc, 0, v1
	v_pk_add_f32 v[114:115], v[116:117], v[114:115]
	s_mov_b64 s[2:3], 0
	v_add_f32_e32 v118, v114, v115
	ds_bpermute_b32 v119, v172, v118
	v_cvt_pk_bf16_f32 v114, v122, v123
	v_cvt_pk_bf16_f32 v115, v124, v125
	v_cvt_pk_bf16_f32 v116, v126, v127
	v_cvt_pk_bf16_f32 v117, v128, v129
	ds_bpermute_b32 v166, v255, v145
	ds_bpermute_b32 v168, v255, v114
	ds_bpermute_b32 v169, v255, v115
	ds_bpermute_b32 v170, v255, v116
	ds_bpermute_b32 v171, v255, v117
	s_waitcnt lgkmcnt(0)
	global_store_dwordx4 v166, v[168:171], s[10:11] offset:256
	s_nop 1
	v_add_u32_e32 v116, 0x20000, v151
	v_mul_f32_e32 v117, v99, v99
	s_waitcnt lgkmcnt(0)
	v_add_f32_e32 v114, v118, v119
	v_lshrrev_b32_e32 v116, 1, v116
	v_fmac_f32_e32 v117, v98, v98
	v_mul_f32_e32 v118, v101, v101
	v_cvt_pk_bf16_f32 v98, v98, v99
	v_cvt_pk_bf16_f32 v99, v100, v101
	v_fmac_f32_e32 v118, v100, v100
	v_cvt_pk_bf16_f32 v100, v106, v107
	v_cvt_pk_bf16_f32 v101, v108, v109
	ds_bpermute_b32 v166, v255, v116
	ds_bpermute_b32 v168, v255, v98
	ds_bpermute_b32 v169, v255, v99
	ds_bpermute_b32 v170, v255, v100
	ds_bpermute_b32 v171, v255, v101
	s_waitcnt lgkmcnt(0)
	global_store_dwordx4 v166, v[168:171], s[10:11]
	v_add_f32_e32 v117, v117, v118
	v_mul_f32_e32 v118, v107, v107
	v_mul_f32_e32 v98, v103, v103
	v_mul_f32_e32 v99, v105, v105
	v_fmac_f32_e32 v98, v102, v102
	v_fmac_f32_e32 v99, v104, v104
	v_add_f32_e32 v98, v98, v99
	v_mul_f32_e32 v99, v111, v111
	v_fmac_f32_e32 v118, v106, v106
	v_fmac_f32_e32 v99, v110, v110
	v_add_f32_e32 v117, v117, v118
	v_mul_f32_e32 v118, v109, v109
	v_add_f32_e32 v98, v98, v99
	v_mul_f32_e32 v99, v113, v113
	v_fmac_f32_e32 v118, v108, v108
	v_fmac_f32_e32 v99, v112, v112
	v_add_f32_e32 v117, v118, v117
	v_add_f32_e32 v98, v99, v98
	v_add_f32_e32 v106, v117, v98
	v_cvt_pk_bf16_f32 v98, v102, v103
	ds_bpermute_b32 v102, v172, v106
	v_cvt_pk_bf16_f32 v99, v104, v105
	v_cvt_pk_bf16_f32 v100, v110, v111
	v_cvt_pk_bf16_f32 v101, v112, v113
	ds_bpermute_b32 v166, v255, v116
	ds_bpermute_b32 v168, v255, v98
	ds_bpermute_b32 v169, v255, v99
	ds_bpermute_b32 v170, v255, v100
	ds_bpermute_b32 v171, v255, v101
	s_waitcnt lgkmcnt(0)
	global_store_dwordx4 v166, v[168:171], s[10:11] offset:256
	ds_bpermute_b32 v115, v173, v114
	s_nop 0
	v_add_u32_e32 v100, 0x40000, v151
	v_mul_f32_e32 v101, v83, v83
	s_waitcnt lgkmcnt(0)
; __device__ __forceinline__ float sum_16_32(float v) { v += __shfl_xor(v, 16); v += __shfl_xor(v, 32); return v; }
; __device__ __forceinline__ unsigned cvt_pk_bf16(float lo, float hi) { unsigned r; asm volatile("v_cvt_pk_bf16_f32 %0, %1, %2" : "=v"(r) : "v"(lo), "v"(hi)); return r; }
;     __device__ __forceinline__ void operator()(const f32x4 (&acc)[2][2][4][2], const Unit& u, int wr, int wc, int fr, int fq) const {
;     ...
;         for (int ai = 0; ai < 2; ++ai) { float sm[4];
; #pragma unroll
;             for (int m = 0; m < 4; ++m) { const unsigned o = ob0 + (unsigned)((ai * HALF + m * 16) * LDC * 4); float s = 0.f;
; #pragma unroll
;                 for (int bj = 0; bj < 2; ++bj) {
;                     const f32x4 o0 = acc[ai][bj][m][0], o1 = acc[ai][bj][m][1];
;                     s += (o0[0] * o0[0] + o0[1] * o0[1]) + (o0[2] * o0[2] + o0[3] * o0[3]) + (o1[0] * o1[0] + o1[1] * o1[1]) + (o1[2] * o1[2] + o1[3] * o1[3]);
;                     if (wf32) { *(f32x4*)(ob + o + bj * HALF * 4) = o0; *(f32x4*)(ob + o + bj * HALF * 4 + 16) = o1; }
;                     else { u32x4 w; w.x = cvt_pk_bf16(o0[0], o0[1]); w.y = cvt_pk_bf16(o0[2], o0[3]); w.z = cvt_pk_bf16(o1[0], o1[1]); w.w = cvt_pk_bf16(o1[2], o1[3]);
;                            *(u32x4*)(xbb + (o >> 1) + bj * HALF * 2) = w; } }
;                 s = sum_16_32(s);
;                 sm[m] = s; }
;             ss[(size_t)(4 * u.pn + wc) * 16384 + u.pm * BM + wr * 64 + ai * HALF + 16 * fq + fr] = fq == 0 ? sm[0] : (fq == 1 ? sm[1] : (fq == 2 ? sm[2] : sm[3])); }
	v_add_f32_e32 v98, v106, v102
	v_lshrrev_b32_e32 v100, 1, v100
	v_fmac_f32_e32 v101, v82, v82
	v_mul_f32_e32 v102, v85, v85
	v_cvt_pk_bf16_f32 v82, v82, v83
	v_cvt_pk_bf16_f32 v83, v84, v85
	v_fmac_f32_e32 v102, v84, v84
	v_cvt_pk_bf16_f32 v84, v90, v91
	v_cvt_pk_bf16_f32 v85, v92, v93
	ds_bpermute_b32 v166, v255, v100
	ds_bpermute_b32 v168, v255, v82
	ds_bpermute_b32 v169, v255, v83
	ds_bpermute_b32 v170, v255, v84
	ds_bpermute_b32 v171, v255, v85
	s_waitcnt lgkmcnt(0)
	global_store_dwordx4 v166, v[168:171], s[10:11]
	v_add_f32_e32 v101, v101, v102
	v_mul_f32_e32 v102, v91, v91
	v_mul_f32_e32 v82, v87, v87
	v_mul_f32_e32 v83, v89, v89
	v_fmac_f32_e32 v82, v86, v86
	v_fmac_f32_e32 v83, v88, v88
	v_add_f32_e32 v82, v82, v83
	v_mul_f32_e32 v83, v95, v95
	v_fmac_f32_e32 v102, v90, v90
	v_fmac_f32_e32 v83, v94, v94
	v_add_f32_e32 v101, v101, v102
	v_mul_f32_e32 v102, v93, v93
	v_add_f32_e32 v82, v82, v83
	v_mul_f32_e32 v83, v97, v97
	v_fmac_f32_e32 v102, v92, v92
	v_fmac_f32_e32 v83, v96, v96
	v_add_f32_e32 v101, v102, v101
	v_add_f32_e32 v82, v83, v82
	v_add_f32_e32 v90, v101, v82
	v_cvt_pk_bf16_f32 v82, v86, v87
	ds_bpermute_b32 v86, v172, v90
	v_cvt_pk_bf16_f32 v83, v88, v89
	v_cvt_pk_bf16_f32 v84, v94, v95
	v_cvt_pk_bf16_f32 v85, v96, v97
	ds_bpermute_b32 v166, v255, v100
	ds_bpermute_b32 v168, v255, v82
	ds_bpermute_b32 v169, v255, v83
	ds_bpermute_b32 v170, v255, v84
	ds_bpermute_b32 v171, v255, v85
	s_waitcnt lgkmcnt(0)
	global_store_dwordx4 v166, v[168:171], s[10:11] offset:256
	ds_bpermute_b32 v99, v173, v98
	s_waitcnt lgkmcnt(0)
	v_add_f32_e32 v82, v90, v86
	v_mul_f32_e32 v85, v75, v75
	v_mul_f32_e32 v86, v77, v77
	v_fmac_f32_e32 v85, v74, v74
	v_fmac_f32_e32 v86, v76, v76
	v_cvt_pk_bf16_f32 v74, v74, v75
	v_cvt_pk_bf16_f32 v75, v76, v77
	v_mul_f32_e32 v76, v71, v71
	v_mul_f32_e32 v77, v73, v73
	v_fmac_f32_e32 v76, v70, v70
	v_fmac_f32_e32 v77, v72, v72
	v_add_f32_e32 v85, v85, v86
	v_mul_f32_e32 v86, v67, v67
	v_add_f32_e32 v76, v76, v77
	v_mul_f32_e32 v77, v79, v79
	v_fmac_f32_e32 v86, v66, v66
	v_fmac_f32_e32 v77, v78, v78
	v_add_f32_e32 v85, v85, v86
	v_mul_f32_e32 v86, v69, v69
	v_add_f32_e32 v76, v76, v77
	v_mul_f32_e32 v77, v81, v81
	v_fmac_f32_e32 v86, v68, v68
	v_fmac_f32_e32 v77, v80, v80
	v_add_f32_e32 v85, v86, v85
	v_add_f32_e32 v76, v77, v76
	v_add_f32_e32 v85, v85, v76
	ds_bpermute_b32 v86, v172, v85
	v_cvt_pk_bf16_f32 v76, v66, v67
	ds_bpermute_b32 v83, v173, v82
	v_add_u32_e32 v84, 0x60000, v151
	v_lshrrev_b32_e32 v84, 1, v84
	s_waitcnt lgkmcnt(0)
	v_add_f32_e32 v66, v85, v86
	ds_bpermute_b32 v67, v173, v66
	v_cvt_pk_bf16_f32 v77, v68, v69
	ds_bpermute_b32 v166, v255, v84
	ds_bpermute_b32 v168, v255, v74
	ds_bpermute_b32 v169, v255, v75
	ds_bpermute_b32 v170, v255, v76
	ds_bpermute_b32 v171, v255, v77
	s_waitcnt lgkmcnt(0)
	global_store_dwordx4 v166, v[168:171], s[10:11]
	v_cvt_pk_bf16_f32 v68, v70, v71
	v_cvt_pk_bf16_f32 v69, v72, v73
	v_cvt_pk_bf16_f32 v70, v78, v79
	v_cvt_pk_bf16_f32 v71, v80, v81
	ds_bpermute_b32 v166, v255, v84
	ds_bpermute_b32 v168, v255, v68
	ds_bpermute_b32 v169, v255, v69
	ds_bpermute_b32 v170, v255, v70
	ds_bpermute_b32 v171, v255, v71
	s_waitcnt lgkmcnt(0)
	global_store_dwordx4 v166, v[168:171], s[10:11] offset:256
	s_and_saveexec_b64 s[8:9], vcc
	s_xor_b64 s[8:9], exec, s[8:9]
	v_readlane_b32 s50, v252, 33
	v_readlane_b32 s51, v252, 34
	s_cbranch_execz .LBB0_558
	v_cmp_eq_u32_e32 vcc, 1, v1
	s_mov_b64 s[2:3], -1
	s_and_saveexec_b64 s[26:27], vcc
	v_add_f32_e32 v68, v98, v99
	s_xor_b64 s[2:3], exec, -1
	s_or_b64 exec, exec, s[26:27]
	s_and_b64 s[2:3], s[2:3], exec
	s_or_saveexec_b64 s[8:9], s[8:9]
	v_cmp_ne_u32_e32 vcc, 0, v1
	s_xor_b64 exec, exec, s[8:9]
	s_cbranch_execnz .LBB0_559

; __device__ __forceinline__ float sum_16_32(float v) { v += __shfl_xor(v, 16); v += __shfl_xor(v, 32); return v; }
; __device__ __forceinline__ unsigned cvt_pk_bf16(float lo, float hi) { unsigned r; asm volatile("v_cvt_pk_bf16_f32 %0, %1, %2" : "=v"(r) : "v"(lo), "v"(hi)); return r; }
;     __device__ __forceinline__ void operator()(const f32x4 (&acc)[2][2][4][2], const Unit& u, int wr, int wc, int fr, int fq) const {
;     ...
;         for (int ai = 0; ai < 2; ++ai) { float sm[4];
; #pragma unroll
;             for (int m = 0; m < 4; ++m) { const unsigned o = ob0 + (unsigned)((ai * HALF + m * 16) * LDC * 4); float s = 0.f;
; #pragma unroll
;                 for (int bj = 0; bj < 2; ++bj) {
;                     const f32x4 o0 = acc[ai][bj][m][0], o1 = acc[ai][bj][m][1];
;                     s += (o0[0] * o0[0] + o0[1] * o0[1]) + (o0[2] * o0[2] + o0[3] * o0[3]) + (o1[0] * o1[0] + o1[1] * o1[1]) + (o1[2] * o1[2] + o1[3] * o1[3]);
;                     if (wf32) { *(f32x4*)(ob + o + bj * HALF * 4) = o0; *(f32x4*)(ob + o + bj * HALF * 4 + 16) = o1; }
;                     else { u32x4 w; w.x = cvt_pk_bf16(o0[0], o0[1]); w.y = cvt_pk_bf16(o0[2], o0[3]); w.z = cvt_pk_bf16(o1[0], o1[1]); w.w = cvt_pk_bf16(o1[2], o1[3]);
;                            *(u32x4*)(xbb + (o >> 1) + bj * HALF * 2) = w; } }
;                 s = sum_16_32(s);
;                 sm[m] = s; }
;             ss[(size_t)(4 * u.pn + wc) * 16384 + u.pm * BM + wr * 64 + ai * HALF + 16 * fq + fr] = fq == 0 ? sm[0] : (fq == 1 ? sm[1] : (fq == 2 ? sm[2] : sm[3])); }
.LBB0_554:
	s_or_b64 exec, exec, s[8:9]
	s_lshl_b32 s1, s33, 2
	s_or_b32 s2, s1, s34
	s_ashr_i32 s3, s2, 31
	s_ashr_i32 s1, s0, 31
	s_lshl_b64 s[2:3], s[2:3], 16
	s_add_u32 s2, s40, s2
	s_addc_u32 s3, s41, s3
	s_lshl_b64 s[0:1], s[0:1], 2
	s_add_u32 s0, s2, s0
	s_addc_u32 s1, s3, s1
	s_add_u32 s0, s0, s16
	s_addc_u32 s1, s1, s17
	s_waitcnt lgkmcnt(0)
	v_lshl_add_u64 v[66:67], v[138:139], 2, s[0:1]
	v_mov_b32_e32 v145, v0
	v_lshl_add_u64 v[66:67], v[66:67], 0, v[144:145]
	global_store_dword v[66:67], v68, off
	v_add_u32_e32 v68, 0x100000, v151
	v_mul_f32_e32 v69, v35, v35
	v_lshrrev_b32_e32 v68, 1, v68
	v_fmac_f32_e32 v69, v34, v34
	v_mul_f32_e32 v70, v37, v37
	v_cvt_pk_bf16_f32 v34, v34, v35
	v_cvt_pk_bf16_f32 v35, v36, v37
	v_fmac_f32_e32 v70, v36, v36
	v_cvt_pk_bf16_f32 v36, v46, v47
	v_cvt_pk_bf16_f32 v37, v48, v49
	ds_bpermute_b32 v166, v255, v68
	ds_bpermute_b32 v168, v255, v34
	ds_bpermute_b32 v169, v255, v35
	ds_bpermute_b32 v170, v255, v36
	ds_bpermute_b32 v171, v255, v37
	s_waitcnt lgkmcnt(0)
	global_store_dwordx4 v166, v[168:171], s[10:11]
	v_add_f32_e32 v69, v69, v70
	v_mul_f32_e32 v70, v47, v47
	v_mul_f32_e32 v34, v39, v39
	v_mul_f32_e32 v35, v41, v41
	v_fmac_f32_e32 v34, v38, v38
	v_fmac_f32_e32 v35, v40, v40
	v_add_f32_e32 v34, v34, v35
	v_mul_f32_e32 v35, v55, v55
	v_fmac_f32_e32 v70, v46, v46
	v_fmac_f32_e32 v35, v54, v54
	v_add_f32_e32 v69, v69, v70
	v_mul_f32_e32 v70, v49, v49
	v_add_f32_e32 v34, v34, v35
	v_mul_f32_e32 v35, v57, v57
	v_fmac_f32_e32 v70, v48, v48
	v_fmac_f32_e32 v35, v56, v56
	v_add_f32_e32 v69, v70, v69
	v_add_f32_e32 v34, v35, v34
	v_add_f32_e32 v46, v69, v34
	v_cvt_pk_bf16_f32 v34, v38, v39
	ds_bpermute_b32 v38, v172, v46
	v_cvt_pk_bf16_f32 v35, v40, v41
	v_cvt_pk_bf16_f32 v36, v54, v55
	v_cvt_pk_bf16_f32 v37, v56, v57
	ds_bpermute_b32 v166, v255, v68
	ds_bpermute_b32 v168, v255, v34
	ds_bpermute_b32 v169, v255, v35
	ds_bpermute_b32 v170, v255, v36
	ds_bpermute_b32 v171, v255, v37
	s_waitcnt lgkmcnt(0)
	global_store_dwordx4 v166, v[168:171], s[10:11] offset:256
	v_cmp_lt_i32_e64 s[8:9], 0, v1
	s_mov_b64 s[0:1], 0
	v_add_u32_e32 v36, 0x120000, v151
	v_lshrrev_b32_e32 v40, 1, v36
	v_cvt_pk_bf16_f32 v36, v10, v11
	s_waitcnt lgkmcnt(0)
	v_add_f32_e32 v34, v46, v38
	v_cvt_pk_bf16_f32 v37, v12, v13
	v_cvt_pk_bf16_f32 v38, v6, v7
	v_cvt_pk_bf16_f32 v39, v8, v9
	ds_bpermute_b32 v166, v255, v40
	ds_bpermute_b32 v168, v255, v36
	ds_bpermute_b32 v169, v255, v37
	ds_bpermute_b32 v170, v255, v38
	ds_bpermute_b32 v171, v255, v39
	s_waitcnt lgkmcnt(0)
	global_store_dwordx4 v166, v[168:171], s[10:11]
	ds_bpermute_b32 v35, v173, v34
	s_mov_b64 s[2:3], 0
	v_mov_b32_e32 v36, v10
	v_mov_b32_e32 v10, v11
	v_mov_b32_e32 v11, v15
	v_mov_b32_e32 v37, v14
	v_pk_mul_f32 v[10:11], v[10:11], v[10:11]
	s_nop 0
	v_pk_fma_f32 v[10:11], v[36:37], v[36:37], v[10:11]
	v_mov_b32_e32 v36, v12
	v_mov_b32_e32 v12, v13
	v_mov_b32_e32 v13, v17
	v_mov_b32_e32 v37, v16
	v_pk_mul_f32 v[12:13], v[12:13], v[12:13]
	s_nop 0
	v_pk_fma_f32 v[12:13], v[36:37], v[36:37], v[12:13]
	s_nop 0
	v_pk_add_f32 v[10:11], v[10:11], v[12:13]
	v_mov_b32_e32 v12, v6
	v_mov_b32_e32 v6, v7
	v_mov_b32_e32 v7, v27
	v_mov_b32_e32 v13, v26
	v_pk_mul_f32 v[6:7], v[6:7], v[6:7]
	s_nop 0
	v_pk_fma_f32 v[6:7], v[12:13], v[12:13], v[6:7]
	s_nop 0
	v_pk_add_f32 v[6:7], v[10:11], v[6:7]
	v_mov_b32_e32 v10, v8
	v_mov_b32_e32 v8, v9
	v_mov_b32_e32 v9, v29
	v_mov_b32_e32 v11, v28
	v_pk_mul_f32 v[8:9], v[8:9], v[8:9]
	s_nop 0
	v_pk_fma_f32 v[8:9], v[10:11], v[10:11], v[8:9]
	s_nop 0
	v_pk_add_f32 v[6:7], v[8:9], v[6:7]
	s_nop 0
	v_add_f32_e32 v10, v6, v7
	v_cvt_pk_bf16_f32 v6, v14, v15
	v_cvt_pk_bf16_f32 v7, v16, v17
	v_cvt_pk_bf16_f32 v8, v26, v27
	v_cvt_pk_bf16_f32 v9, v28, v29
	ds_bpermute_b32 v166, v255, v40
	ds_bpermute_b32 v168, v255, v6
	ds_bpermute_b32 v169, v255, v7
	ds_bpermute_b32 v170, v255, v8
	ds_bpermute_b32 v171, v255, v9
	s_waitcnt lgkmcnt(0)
; __device__ __forceinline__ float sum_16_32(float v) { v += __shfl_xor(v, 16); v += __shfl_xor(v, 32); return v; }
; __device__ __forceinline__ unsigned cvt_pk_bf16(float lo, float hi) { unsigned r; asm volatile("v_cvt_pk_bf16_f32 %0, %1, %2" : "=v"(r) : "v"(lo), "v"(hi)); return r; }
;     __device__ __forceinline__ void operator()(const f32x4 (&acc)[2][2][4][2], const Unit& u, int wr, int wc, int fr, int fq) const {
;     ...
;                 for (int bj = 0; bj < 2; ++bj) {
;                     const f32x4 o0 = acc[ai][bj][m][0], o1 = acc[ai][bj][m][1];
;                     s += (o0[0] * o0[0] + o0[1] * o0[1]) + (o0[2] * o0[2] + o0[3] * o0[3]) + (o1[0] * o1[0] + o1[1] * o1[1]) + (o1[2] * o1[2] + o1[3] * o1[3]);
;                     if (wf32) { *(f32x4*)(ob + o + bj * HALF * 4) = o0; *(f32x4*)(ob + o + bj * HALF * 4 + 16) = o1; }
;                     else { u32x4 w; w.x = cvt_pk_bf16(o0[0], o0[1]); w.y = cvt_pk_bf16(o0[2], o0[3]); w.z = cvt_pk_bf16(o1[0], o1[1]); w.w = cvt_pk_bf16(o1[2], o1[3]);
;                            *(u32x4*)(xbb + (o >> 1) + bj * HALF * 2) = w; } }
;                 s = sum_16_32(s);
;                 sm[m] = s; }
;             ss[(size_t)(4 * u.pn + wc) * 16384 + u.pm * BM + wr * 64 + ai * HALF + 16 * fq + fr] = fq == 0 ? sm[0] : (fq == 1 ? sm[1] : (fq == 2 ? sm[2] : sm[3])); }
	global_store_dwordx4 v166, v[168:171], s[10:11] offset:256
	ds_bpermute_b32 v11, v172, v10
	v_mul_f32_e32 v15, v21, v21
	v_add_u32_e32 v8, 0x140000, v151
	v_lshrrev_b32_e32 v12, 1, v8
	v_mul_f32_e32 v8, v43, v43
	v_mul_f32_e32 v9, v45, v45
	v_fmac_f32_e32 v8, v42, v42
	v_fmac_f32_e32 v9, v44, v44
	v_add_f32_e32 v8, v8, v9
	v_mul_f32_e32 v9, v59, v59
	v_fmac_f32_e32 v9, v58, v58
	v_add_f32_e32 v8, v8, v9
	v_mul_f32_e32 v9, v61, v61
	v_fmac_f32_e32 v9, v60, v60
	v_add_f32_e32 v13, v9, v8
	v_cvt_pk_bf16_f32 v8, v42, v43
	v_cvt_pk_bf16_f32 v9, v44, v45
	s_waitcnt lgkmcnt(0)
	v_add_f32_e32 v6, v10, v11
	v_cvt_pk_bf16_f32 v10, v58, v59
	v_cvt_pk_bf16_f32 v11, v60, v61
	ds_bpermute_b32 v166, v255, v12
	ds_bpermute_b32 v168, v255, v8
	ds_bpermute_b32 v169, v255, v9
	ds_bpermute_b32 v170, v255, v10
	ds_bpermute_b32 v171, v255, v11
	s_waitcnt lgkmcnt(0)
	global_store_dwordx4 v166, v[168:171], s[10:11]
	v_fmac_f32_e32 v15, v20, v20
	ds_bpermute_b32 v7, v173, v6
	v_mul_f32_e32 v8, v51, v51
	v_mul_f32_e32 v9, v53, v53
	v_fmac_f32_e32 v8, v50, v50
	v_fmac_f32_e32 v9, v52, v52
	v_add_f32_e32 v8, v8, v9
	v_mul_f32_e32 v9, v63, v63
	v_fmac_f32_e32 v9, v62, v62
	v_add_f32_e32 v8, v8, v9
	v_mul_f32_e32 v9, v65, v65
	v_fmac_f32_e32 v9, v64, v64
	v_add_f32_e32 v8, v9, v8
	v_add_f32_e32 v13, v13, v8
	ds_bpermute_b32 v14, v172, v13
	v_cvt_pk_bf16_f32 v8, v50, v51
	v_cvt_pk_bf16_f32 v9, v52, v53
	v_cvt_pk_bf16_f32 v10, v62, v63
	v_cvt_pk_bf16_f32 v11, v64, v65
	ds_bpermute_b32 v166, v255, v12
	ds_bpermute_b32 v168, v255, v8
	ds_bpermute_b32 v169, v255, v9
	ds_bpermute_b32 v170, v255, v10
	ds_bpermute_b32 v171, v255, v11
	s_waitcnt lgkmcnt(0)
	global_store_dwordx4 v166, v[168:171], s[10:11] offset:256
	s_nop 1
	v_add_u32_e32 v10, 0x160000, v151
	s_waitcnt lgkmcnt(0)
	v_add_f32_e32 v8, v13, v14
	v_lshrrev_b32_e32 v14, 1, v10
	v_mul_f32_e32 v10, v23, v23
	v_mul_f32_e32 v11, v25, v25
	v_mul_f32_e32 v13, v19, v19
	v_fmac_f32_e32 v10, v22, v22
	v_fmac_f32_e32 v11, v24, v24
	v_fmac_f32_e32 v13, v18, v18
	v_add_f32_e32 v10, v10, v11
	v_mul_f32_e32 v11, v3, v3
	v_add_f32_e32 v13, v13, v15
	v_mul_f32_e32 v15, v31, v31
	v_fmac_f32_e32 v11, v2, v2
	v_fmac_f32_e32 v15, v30, v30
	v_add_f32_e32 v10, v10, v11
	v_mul_f32_e32 v11, v5, v5
	v_add_f32_e32 v13, v13, v15
	v_mul_f32_e32 v15, v33, v33
	v_fmac_f32_e32 v11, v4, v4
	v_fmac_f32_e32 v15, v32, v32
	v_add_f32_e32 v12, v11, v10
	v_add_f32_e32 v13, v15, v13
	v_add_f32_e32 v15, v12, v13
	ds_bpermute_b32 v16, v172, v15
	v_cvt_pk_bf16_f32 v10, v22, v23
	v_cvt_pk_bf16_f32 v11, v24, v25
	v_cvt_pk_bf16_f32 v12, v2, v3
	ds_bpermute_b32 v9, v173, v8
	s_waitcnt lgkmcnt(0)
	v_add_f32_e32 v3, v15, v16
	v_cvt_pk_bf16_f32 v13, v4, v5
	ds_bpermute_b32 v4, v173, v3
	ds_bpermute_b32 v166, v255, v14
	ds_bpermute_b32 v168, v255, v10
	ds_bpermute_b32 v169, v255, v11
	ds_bpermute_b32 v170, v255, v12
	ds_bpermute_b32 v171, v255, v13
	s_waitcnt lgkmcnt(0)
	global_store_dwordx4 v166, v[168:171], s[10:11]
	s_nop 1
	v_cvt_pk_bf16_f32 v10, v18, v19
	v_cvt_pk_bf16_f32 v11, v20, v21
	v_cvt_pk_bf16_f32 v12, v30, v31
	v_cvt_pk_bf16_f32 v13, v32, v33
	ds_bpermute_b32 v166, v255, v14
	ds_bpermute_b32 v168, v255, v10
	ds_bpermute_b32 v169, v255, v11
	ds_bpermute_b32 v170, v255, v12
	ds_bpermute_b32 v171, v255, v13
	s_waitcnt lgkmcnt(0)
	global_store_dwordx4 v166, v[168:171], s[10:11] offset:256
	s_and_saveexec_b64 s[26:27], s[8:9]
	s_xor_b64 s[26:27], exec, s[26:27]
	s_cbranch_execz .LBB0_560
	v_cmp_ne_u32_e64 s[8:9], 1, v1
	v_add_f32_e32 v2, v6, v7
	s_and_b64 s[2:3], s[8:9], exec
	s_andn2_saveexec_b64 s[8:9], s[26:27]
	s_cbranch_execnz .LBB0_561

; __global__ void __launch_bounds__(NWAVES * 64, 2) hybrid_fwd(Args a) {
	.amdhsa_kernel _Z10hybrid_fwd4Args
		.amdhsa_group_segment_fixed_size 0
		.amdhsa_private_segment_fixed_size 0
		.amdhsa_kernarg_size 368
		.amdhsa_user_sgpr_count 2
		.amdhsa_user_sgpr_dispatch_ptr 0
		.amdhsa_user_sgpr_queue_ptr 0
		.amdhsa_user_sgpr_kernarg_segment_ptr 1
		.amdhsa_user_sgpr_dispatch_id 0
		.amdhsa_user_sgpr_kernarg_preload_length 0
		.amdhsa_user_sgpr_kernarg_preload_offset 0
		.amdhsa_user_sgpr_private_segment_size 0
		.amdhsa_uses_dynamic_stack 0
		.amdhsa_enable_private_segment 0
		.amdhsa_system_sgpr_workgroup_id_x 1
		.amdhsa_system_sgpr_workgroup_id_y 0
		.amdhsa_system_sgpr_workgroup_id_z 0
		.amdhsa_system_sgpr_workgroup_info 0
		.amdhsa_system_vgpr_workitem_id 2
		.amdhsa_next_free_vgpr 256
		.amdhsa_next_free_sgpr 100
		.amdhsa_accum_offset 256
		.amdhsa_reserve_vcc 1
		.amdhsa_float_round_mode_32 0
		.amdhsa_float_round_mode_16_64 0
		.amdhsa_float_denorm_mode_32 3
		.amdhsa_float_denorm_mode_16_64 3
		.amdhsa_dx10_clamp 1
		.amdhsa_ieee_mode 1
		.amdhsa_fp16_overflow 0
		.amdhsa_tg_split 0
		.amdhsa_exception_fp_ieee_invalid_op 0
		.amdhsa_exception_fp_denorm_src 0
		.amdhsa_exception_fp_ieee_div_zero 0
		.amdhsa_exception_fp_ieee_overflow 0
		.amdhsa_exception_fp_ieee_underflow 0
		.amdhsa_exception_fp_ieee_inexact 0
		.amdhsa_exception_int_div_zero 0
	.end_amdhsa_kernel

; __global__ void __launch_bounds__(NWAVES * 64, 2) hybrid_fwd(Args a) {
amdhsa.kernels:
  - .agpr_count:     0
    .args:
      - .offset:         0
        .size:           112
        .value_kind:     by_value
      - .offset:         112
        .size:           4
        .value_kind:     hidden_block_count_x
      - .offset:         116
        .size:           4
        .value_kind:     hidden_block_count_y
      - .offset:         120
        .size:           4
        .value_kind:     hidden_block_count_z
      - .offset:         124
        .size:           2
        .value_kind:     hidden_group_size_x
      - .offset:         126
        .size:           2
        .value_kind:     hidden_group_size_y
      - .offset:         128
        .size:           2
        .value_kind:     hidden_group_size_z
      - .offset:         130
        .size:           2
        .value_kind:     hidden_remainder_x
      - .offset:         132
        .size:           2
        .value_kind:     hidden_remainder_y
      - .offset:         134
        .size:           2
        .value_kind:     hidden_remainder_z
      - .offset:         152
        .size:           8
        .value_kind:     hidden_global_offset_x
      - .offset:         160
        .size:           8
        .value_kind:     hidden_global_offset_y
      - .offset:         168
        .size:           8
        .value_kind:     hidden_global_offset_z
      - .offset:         176
        .size:           2
        .value_kind:     hidden_grid_dims
      - .offset:         200
        .size:           8
        .value_kind:     hidden_multigrid_sync_arg
      - .offset:         232
        .size:           4
        .value_kind:     hidden_dynamic_lds_size
    .group_segment_fixed_size: 0
    .kernarg_segment_align: 8
    .kernarg_segment_size: 368
    .language:       OpenCL C
    .language_version:
      - 2
      - 0
    .max_flat_workgroup_size: 512
    .name:           _Z10hybrid_fwd4Args
    .private_segment_fixed_size: 0
    .sgpr_count:     106
    .sgpr_spill_count: 164
    .symbol:         _Z10hybrid_fwd4Args.kd
    .uniform_work_group_size: 1
    .uses_dynamic_stack: false
    .vgpr_count:     256
    .vgpr_spill_count: 0
    .wavefront_size: 64
